# out/down GEMMs: context K-quarter units as 256 half units (two workgroups per unit); ctx-row fold on the hand-written norm path
# speedup vs baseline: 1.0072x; 1.0031x over previous
.LBB0_689:
	v_lshrrev_b32_e32 v16, 1, v14
	v_and_b32_e32 v16, 24, v16
	v_and_b32_e32 v15, 15, v14
	v_lshlrev_b32_e32 v17, 1, v16
	v_lshlrev_b32_e32 v14, 2, v14
	s_lshl_b32 s7, s7, 5
	v_lshl_or_b32 v174, s8, 6, v15
	v_lshl_or_b32 v15, v15, 6, v17
	s_lshl_b32 s8, s8, 13
	v_and_b32_e32 v14, 32, v14
	s_and_b32 s7, s7, 0x60
	v_bitop3_b32 v17, v15, s8, v14 bitop3:0xde
	s_lshl_b32 s8, s7, 7
	s_add_u32 s46, s20, 0x19624000
	s_addc_u32 s47, s21, 0
	s_mul_i32 s9, s80, 0x3c000
	v_bitop3_b32 v175, v15, s8, v14 bitop3:0xde
	s_mul_hi_u32 s8, s80, 0x3c000
	s_add_u32 s74, s20, s9
	s_addc_u32 s75, s21, s8
	s_add_u32 s76, s20, 0x3bce8000
	s_addc_u32 s77, s21, 0
	s_add_u32 s8, s36, 0x8000
	v_mov_b32_e32 v161, v99
	s_addc_u32 s9, s37, 0
	v_mov_b32_e32 v157, v99
	s_add_i32 m0, s70, 0x18000
	v_lshl_add_u64 v[14:15], s[8:9], 0, v[160:161]
	s_waitcnt vmcnt(2)
	s_barrier
	global_load_lds_dwordx4 v[14:15], off
	v_lshl_add_u64 v[14:15], s[8:9], 0, v[156:157]
	s_add_i32 m0, s70, 0x1a000
	s_add_i32 s82, s70, 0x8000
	s_add_i32 s83, s70, 0xa000
	global_load_lds_dwordx4 v[14:15], off
	v_lshl_add_u64 v[2:3], v[2:3], 0, s[24:25]
	s_mov_b32 m0, s82
	s_add_u32 s8, s36, 0xc000
	global_load_lds_dwordx4 v[2:3], off
	v_lshl_add_u64 v[2:3], v[4:5], 0, s[24:25]
	s_mov_b32 m0, s83
	s_addc_u32 s9, s37, 0
	global_load_lds_dwordx4 v[2:3], off
	s_add_i32 m0, s70, 0x1c000
	v_lshl_add_u64 v[2:3], s[8:9], 0, v[160:161]
	global_load_lds_dwordx4 v[2:3], off
	v_lshl_add_u64 v[2:3], s[8:9], 0, v[156:157]
	s_add_i32 m0, s70, 0x1e000
	s_movk_i32 s9, 0xa00
	global_load_lds_dwordx4 v[2:3], off
	v_lshrrev_b32_e32 v3, 1, v6
	v_mul_lo_u32 v2, v7, s9
	s_mov_b32 s8, 0xa000
	s_cmpk_lt_u32 s6, 0x100
	v_or_b32_e32 v176, s7, v16
	v_mad_u64_u32 v[2:3], s[6:7], v3, s8, v[2:3]
	v_or_b32_e32 v2, v2, v8
	v_add_lshl_u32 v2, v2, v9, 1
	v_mov_b32_e32 v3, v99
	s_mov_b64 s[10:11], 0xa0080
	v_lshl_add_u64 v[162:163], v[2:3], 0, s[10:11]
	v_lshrrev_b32_e32 v3, 1, v11
	v_mul_lo_u32 v2, v10, s9
	v_mad_u64_u32 v[2:3], s[6:7], v3, s8, v[2:3]
	s_waitcnt vmcnt(6)
	v_or_b32_e32 v2, v2, v12
	s_cselect_b64 s[48:49], -1, 0
	s_cmp_lg_u64 s[38:39], 0
	v_add_lshl_u32 v2, v2, v13, 1
	v_mov_b32_e32 v3, v99
	v_readlane_b32 s56, v254, 21
	s_cselect_b64 s[54:55], -1, 0
	s_mov_b32 s16, 0xa000
	v_lshl_add_u64 v[164:165], v[2:3], 0, s[10:11]
	s_mov_b32 s84, 0
	v_add_u32_e32 v177, 0, v17
	v_readlane_b32 s8, v254, 20
	v_readlane_b32 s9, v254, 50
	v_readlane_b32 s6, v254, 40
	v_readlane_b32 s7, v254, 19
	v_readlane_b32 s57, v254, 22
	s_barrier
	s_mov_b32 s100, 0
	s_branch .LBB0_692

.LBB0_691:
	s_mov_b32 s100, s101
	s_andn2_b64 vcc, exec, s[4:5]
	s_mov_b32 s8, s86
	s_mov_b32 s9, s85
	s_mov_b32 s6, s88
	s_mov_b32 s7, s87
	s_mov_b64 s[36:37], s[60:61]
	s_mov_b64 s[4:5], s[58:59]
	s_cbranch_vccz .LBB0_841
.LBB0_692:
	s_add_i32 s84, s84, 1
	s_mul_i32 s10, s84, s52
	s_add_i32 s10, s10, s2
	s_mov_b32 s101, 0
	s_cmp_lg_u32 s52, 0x100
	s_cbranch_scc1 .Lgo_sched_done
	s_cmpk_lt_i32 s10, 0x200
	s_cbranch_scc1 .Lgo_sched_done
	s_and_b32 s101, s10, 1
	s_add_i32 s101, s101, 1
	s_sub_i32 s10, s10, 0x200
	s_lshr_b32 s10, s10, 1
	s_add_i32 s10, s10, 0x200
.Lgo_sched_done:
	s_cmpk_lt_i32 s10, 0x200
	s_cselect_b64 s[40:41], -1, 0
	s_ashr_i32 s11, s10, 31
	s_lshr_b32 s11, s11, 29
	s_add_i32 s11, s10, s11
	s_and_b32 s12, s11, -8
	s_sub_i32 s12, s10, s12
	s_cmpk_gt_i32 s10, 0x1ff
	s_cselect_b64 s[20:21], -1, 0
	s_and_b64 s[42:43], s[20:21], exec
	s_cselect_b32 s59, 0, s12
	s_cmp_gt_i32 s59, -1
	s_mov_b64 s[42:43], -1
	s_cbranch_scc0 .LBB0_694
	s_lshl_b32 s58, s59, 6
	s_cbranch_execnz .LBB0_696
	s_branch .LBB0_695

.LBB0_704:
	s_xor_b64 s[62:63], s[56:57], -1
	s_add_i32 s89, s7, -2
	s_add_u32 s90, s36, 0x10000
	v_mov_b32_e32 v2, 0
	s_mov_b64 s[56:57], s[20:21]
	s_addc_u32 s91, s37, 0
	s_mov_b32 s10, 0
	v_mov_b32_e32 v3, v2
	v_mov_b32_e32 v4, v2
	v_mov_b32_e32 v5, v2
	v_mov_b32_e32 v6, v2
	v_mov_b32_e32 v7, v2
	v_mov_b32_e32 v8, v2
	v_mov_b32_e32 v9, v2
	v_mov_b32_e32 v18, v2
	v_mov_b32_e32 v19, v2
	v_mov_b32_e32 v20, v2
	v_mov_b32_e32 v21, v2
	v_mov_b32_e32 v22, v2
	v_mov_b32_e32 v23, v2
	v_mov_b32_e32 v24, v2
	v_mov_b32_e32 v25, v2
	v_mov_b32_e32 v34, v2
	v_mov_b32_e32 v35, v2
	v_mov_b32_e32 v36, v2
	v_mov_b32_e32 v37, v2
	v_mov_b32_e32 v38, v2
	v_mov_b32_e32 v39, v2
	v_mov_b32_e32 v40, v2
	v_mov_b32_e32 v41, v2
	v_mov_b32_e32 v58, v2
	v_mov_b32_e32 v59, v2
	v_mov_b32_e32 v60, v2
	v_mov_b32_e32 v61, v2
	v_mov_b32_e32 v62, v2
	v_mov_b32_e32 v63, v2
	v_mov_b32_e32 v64, v2
	v_mov_b32_e32 v65, v2
	v_mov_b32_e32 v10, v2
	v_mov_b32_e32 v11, v2
	v_mov_b32_e32 v12, v2
	v_mov_b32_e32 v13, v2
	v_mov_b32_e32 v14, v2
	v_mov_b32_e32 v15, v2
	v_mov_b32_e32 v16, v2
	v_mov_b32_e32 v17, v2
	v_mov_b32_e32 v26, v2
	v_mov_b32_e32 v27, v2
	v_mov_b32_e32 v28, v2
	v_mov_b32_e32 v29, v2
	v_mov_b32_e32 v30, v2
	v_mov_b32_e32 v31, v2
	v_mov_b32_e32 v32, v2
	v_mov_b32_e32 v33, v2
	v_mov_b32_e32 v42, v2
	v_mov_b32_e32 v43, v2
	v_mov_b32_e32 v44, v2
	v_mov_b32_e32 v45, v2
	v_mov_b32_e32 v46, v2
	v_mov_b32_e32 v47, v2
	v_mov_b32_e32 v48, v2
	v_mov_b32_e32 v49, v2
	v_mov_b32_e32 v74, v2
	v_mov_b32_e32 v75, v2
	v_mov_b32_e32 v76, v2
	v_mov_b32_e32 v77, v2
	v_mov_b32_e32 v78, v2
	v_mov_b32_e32 v79, v2
	v_mov_b32_e32 v80, v2
	v_mov_b32_e32 v81, v2
	v_mov_b32_e32 v82, v2
	v_mov_b32_e32 v83, v2
	v_mov_b32_e32 v84, v2
	v_mov_b32_e32 v85, v2
	v_mov_b32_e32 v86, v2
	v_mov_b32_e32 v87, v2
	v_mov_b32_e32 v88, v2
	v_mov_b32_e32 v89, v2
	v_mov_b32_e32 v100, v2
	v_mov_b32_e32 v101, v2
	v_mov_b32_e32 v102, v2
	v_mov_b32_e32 v103, v2
	v_mov_b32_e32 v104, v2
	v_mov_b32_e32 v105, v2
	v_mov_b32_e32 v106, v2
	v_mov_b32_e32 v107, v2
	v_mov_b32_e32 v116, v2
	v_mov_b32_e32 v117, v2
	v_mov_b32_e32 v118, v2
	v_mov_b32_e32 v119, v2
	v_mov_b32_e32 v120, v2
	v_mov_b32_e32 v121, v2
	v_mov_b32_e32 v122, v2
	v_mov_b32_e32 v123, v2
	v_mov_b32_e32 v132, v2
	v_mov_b32_e32 v133, v2
	v_mov_b32_e32 v134, v2
	v_mov_b32_e32 v135, v2
	v_mov_b32_e32 v136, v2
	v_mov_b32_e32 v137, v2
	v_mov_b32_e32 v138, v2
	v_mov_b32_e32 v139, v2
	v_mov_b32_e32 v90, v2
	v_mov_b32_e32 v91, v2
	v_mov_b32_e32 v92, v2
	v_mov_b32_e32 v93, v2
	v_mov_b32_e32 v94, v2
	v_mov_b32_e32 v95, v2
	v_mov_b32_e32 v96, v2
	v_mov_b32_e32 v97, v2
	v_mov_b32_e32 v108, v2
	v_mov_b32_e32 v109, v2
	v_mov_b32_e32 v110, v2
	v_mov_b32_e32 v111, v2
	v_mov_b32_e32 v112, v2
	v_mov_b32_e32 v113, v2
	v_mov_b32_e32 v114, v2
	v_mov_b32_e32 v115, v2
	v_mov_b32_e32 v124, v2
	v_mov_b32_e32 v125, v2
	v_mov_b32_e32 v126, v2
	v_mov_b32_e32 v127, v2
	v_mov_b32_e32 v128, v2
	v_mov_b32_e32 v129, v2
	v_mov_b32_e32 v130, v2
	v_mov_b32_e32 v131, v2
	v_mov_b32_e32 v140, v2
	v_mov_b32_e32 v141, v2
	v_mov_b32_e32 v142, v2
	v_mov_b32_e32 v143, v2
	v_mov_b32_e32 v144, v2
	v_mov_b32_e32 v145, v2
	v_mov_b32_e32 v146, v2
	v_mov_b32_e32 v147, v2
	s_cmp_eq_u32 s100, 1
	s_cbranch_scc1 .Lgo_h0_loop
	s_cmp_eq_u32 s100, 2
	s_cbranch_scc1 .Lgo_h1_loop

.Lgo_after_loop:
	s_and_b64 vcc, exec, s[48:49]
	s_cbranch_vccz .LBB0_708
	s_barrier

.LBB0_710:
	s_lshl_b64 s[4:5], s[4:5], 2
	v_lshl_or_b32 v166, s9, 8, v176
	s_add_u32 s4, s74, s4
	s_addc_u32 s5, s75, s5
	v_ashrrev_i32_e32 v167, 31, v166
	v_lshl_add_u64 v[50:51], v[166:167], 2, s[4:5]
	s_mov_b64 s[4:5], 0x194e4000
	v_lshl_add_u64 v[54:55], v[50:51], 0, s[4:5]
	s_mov_b32 s4, 0x194e4000
	v_add_co_u32_e32 v50, vcc, s4, v50
	v_lshl_add_u32 v168, s8, 8, v174
	s_nop 0
	v_addc_co_u32_e32 v51, vcc, 0, v51, vcc
	global_load_dwordx4 v[66:69], v[50:51], off
	global_load_dwordx4 v[70:73], v[54:55], off offset:16
	s_nop 0
	global_load_dwordx4 v[50:53], v[54:55], off offset:528
	s_nop 0
	global_load_dwordx4 v[54:57], v[54:55], off offset:512
	v_ashrrev_i32_e32 v169, 31, v168
	v_lshlrev_b64 v[148:149], 11, v[168:169]
	v_lshl_add_u64 v[170:171], v[148:149], 0, v[166:167]
	v_cndmask_b32_e64 v148, 0, 1, s[54:55]
	s_mov_b64 s[4:5], -1
	s_and_b64 vcc, exec, s[62:63]
	v_cmp_ne_u32_e64 s[42:43], 1, v148
	s_cbranch_vccz .Lepi_out_orig
	s_cmp_lg_u64 s[54:55], 0
	s_cbranch_scc1 .Lepi_out_orig
	v_lshl_add_u32 v152, v168, 11, v166
	v_lshlrev_b32_e32 v152, 1, v152
	s_mov_b64 s[8:9], s[46:47]
	global_load_dwordx4 v[178:181], v152, s[8:9]
	global_load_dwordx4 v[182:185], v152, s[8:9] offset:256
	s_add_u32 s8, s8, 0x10000
	s_addc_u32 s9, s9, 0
	global_load_dwordx4 v[186:189], v152, s[8:9]
	global_load_dwordx4 v[190:193], v152, s[8:9] offset:256
	s_add_u32 s8, s8, 0x10000
	s_addc_u32 s9, s9, 0
	global_load_dwordx4 v[194:197], v152, s[8:9]
	global_load_dwordx4 v[208:211], v152, s[8:9] offset:256
	s_add_u32 s8, s8, 0x10000
	s_addc_u32 s9, s9, 0
	global_load_dwordx4 v[212:215], v152, s[8:9]
	global_load_dwordx4 v[216:219], v152, s[8:9] offset:256
	s_mov_b64 s[8:9], s[46:47]
	s_add_u32 s4, s46, 0x80000
	s_addc_u32 s5, s47, 0
	s_waitcnt vmcnt(7)
	v_pk_mul_f32 v[144:145], v[144:145], v[66:67]
	v_pk_mul_f32 v[146:147], v[146:147], v[68:69]
	v_pk_mul_f32 v[140:141], v[140:141], v[70:71]
	v_pk_mul_f32 v[142:143], v[142:143], v[72:73]
	v_lshlrev_b32_e32 v148, 16, v178
	v_and_b32_e32 v149, 0xffff0000, v178
	v_lshlrev_b32_e32 v150, 16, v179
	v_and_b32_e32 v151, 0xffff0000, v179
	v_pk_add_f32 v[144:145], v[144:145], v[148:149]
	v_pk_add_f32 v[146:147], v[146:147], v[150:151]
	v_lshlrev_b32_e32 v148, 16, v180
	v_and_b32_e32 v149, 0xffff0000, v180
	v_lshlrev_b32_e32 v150, 16, v181
	v_and_b32_e32 v151, 0xffff0000, v181
	v_pk_add_f32 v[140:141], v[140:141], v[148:149]
	v_pk_add_f32 v[142:143], v[142:143], v[150:151]
	v_cvt_pk_bf16_f32 v178, v144, v145
	v_cvt_pk_bf16_f32 v179, v146, v147
	v_cvt_pk_bf16_f32 v180, v140, v141
	v_cvt_pk_bf16_f32 v181, v142, v143
	global_store_dwordx4 v152, v[178:181], s[8:9]
	s_nop 0
	global_load_dwordx4 v[178:181], v152, s[4:5]
	s_waitcnt vmcnt(8)
	v_pk_mul_f32 v[136:137], v[136:137], v[54:55]
	v_pk_mul_f32 v[138:139], v[138:139], v[56:57]
	v_pk_mul_f32 v[132:133], v[132:133], v[50:51]
	v_pk_mul_f32 v[134:135], v[134:135], v[52:53]
	v_lshlrev_b32_e32 v148, 16, v182
	v_and_b32_e32 v149, 0xffff0000, v182
	v_lshlrev_b32_e32 v150, 16, v183
	v_and_b32_e32 v151, 0xffff0000, v183
	v_pk_add_f32 v[136:137], v[136:137], v[148:149]
	v_pk_add_f32 v[138:139], v[138:139], v[150:151]
	v_lshlrev_b32_e32 v148, 16, v184
	v_and_b32_e32 v149, 0xffff0000, v184
	v_lshlrev_b32_e32 v150, 16, v185
	v_and_b32_e32 v151, 0xffff0000, v185
	v_pk_add_f32 v[132:133], v[132:133], v[148:149]
	v_pk_add_f32 v[134:135], v[134:135], v[150:151]
	v_cvt_pk_bf16_f32 v182, v136, v137
	v_cvt_pk_bf16_f32 v183, v138, v139
	v_cvt_pk_bf16_f32 v184, v132, v133
	v_cvt_pk_bf16_f32 v185, v134, v135
	global_store_dwordx4 v152, v[182:185], s[8:9] offset:256
	s_add_u32 s8, s8, 0x10000
	s_addc_u32 s9, s9, 0
	global_load_dwordx4 v[182:185], v152, s[4:5] offset:256
	s_add_u32 s4, s4, 0x10000
	s_addc_u32 s5, s5, 0
	s_waitcnt vmcnt(9)
	v_pk_mul_f32 v[128:129], v[128:129], v[66:67]
	v_pk_mul_f32 v[130:131], v[130:131], v[68:69]
	v_pk_mul_f32 v[124:125], v[124:125], v[70:71]
	v_pk_mul_f32 v[126:127], v[126:127], v[72:73]
	v_lshlrev_b32_e32 v148, 16, v186
	v_and_b32_e32 v149, 0xffff0000, v186
	v_lshlrev_b32_e32 v150, 16, v187
	v_and_b32_e32 v151, 0xffff0000, v187
	v_pk_add_f32 v[128:129], v[128:129], v[148:149]
	v_pk_add_f32 v[130:131], v[130:131], v[150:151]
	v_lshlrev_b32_e32 v148, 16, v188
	v_and_b32_e32 v149, 0xffff0000, v188
	v_lshlrev_b32_e32 v150, 16, v189
	v_and_b32_e32 v151, 0xffff0000, v189
	v_pk_add_f32 v[124:125], v[124:125], v[148:149]
	v_pk_add_f32 v[126:127], v[126:127], v[150:151]
	v_cvt_pk_bf16_f32 v186, v128, v129
	v_cvt_pk_bf16_f32 v187, v130, v131
	v_cvt_pk_bf16_f32 v188, v124, v125
	v_cvt_pk_bf16_f32 v189, v126, v127
	global_store_dwordx4 v152, v[186:189], s[8:9]
	s_nop 0
	global_load_dwordx4 v[186:189], v152, s[4:5]
	s_waitcnt vmcnt(10)
	v_pk_mul_f32 v[120:121], v[120:121], v[54:55]
	v_pk_mul_f32 v[122:123], v[122:123], v[56:57]
	v_pk_mul_f32 v[116:117], v[116:117], v[50:51]
	v_pk_mul_f32 v[118:119], v[118:119], v[52:53]
	v_lshlrev_b32_e32 v148, 16, v190
	v_and_b32_e32 v149, 0xffff0000, v190
	v_lshlrev_b32_e32 v150, 16, v191
	v_and_b32_e32 v151, 0xffff0000, v191
	v_pk_add_f32 v[120:121], v[120:121], v[148:149]
	v_pk_add_f32 v[122:123], v[122:123], v[150:151]
	v_lshlrev_b32_e32 v148, 16, v192
	v_and_b32_e32 v149, 0xffff0000, v192
	v_lshlrev_b32_e32 v150, 16, v193
	v_and_b32_e32 v151, 0xffff0000, v193
	v_pk_add_f32 v[116:117], v[116:117], v[148:149]
	v_pk_add_f32 v[118:119], v[118:119], v[150:151]
	v_cvt_pk_bf16_f32 v190, v120, v121
	v_cvt_pk_bf16_f32 v191, v122, v123
	v_cvt_pk_bf16_f32 v192, v116, v117
	v_cvt_pk_bf16_f32 v193, v118, v119
	global_store_dwordx4 v152, v[190:193], s[8:9] offset:256
	s_add_u32 s8, s8, 0x10000
	s_addc_u32 s9, s9, 0
	global_load_dwordx4 v[190:193], v152, s[4:5] offset:256
	s_add_u32 s4, s4, 0x10000
	s_addc_u32 s5, s5, 0
	s_waitcnt vmcnt(11)
	v_pk_mul_f32 v[112:113], v[112:113], v[66:67]
	v_pk_mul_f32 v[114:115], v[114:115], v[68:69]
	v_pk_mul_f32 v[108:109], v[108:109], v[70:71]
	v_pk_mul_f32 v[110:111], v[110:111], v[72:73]
	v_lshlrev_b32_e32 v148, 16, v194
	v_and_b32_e32 v149, 0xffff0000, v194
	v_lshlrev_b32_e32 v150, 16, v195
	v_and_b32_e32 v151, 0xffff0000, v195
	v_pk_add_f32 v[112:113], v[112:113], v[148:149]
	v_pk_add_f32 v[114:115], v[114:115], v[150:151]
	v_lshlrev_b32_e32 v148, 16, v196
	v_and_b32_e32 v149, 0xffff0000, v196
	v_lshlrev_b32_e32 v150, 16, v197
	v_and_b32_e32 v151, 0xffff0000, v197
	v_pk_add_f32 v[108:109], v[108:109], v[148:149]
	v_pk_add_f32 v[110:111], v[110:111], v[150:151]
	v_cvt_pk_bf16_f32 v194, v112, v113
	v_cvt_pk_bf16_f32 v195, v114, v115
	v_cvt_pk_bf16_f32 v196, v108, v109
	v_cvt_pk_bf16_f32 v197, v110, v111
	global_store_dwordx4 v152, v[194:197], s[8:9]
	s_nop 0
	global_load_dwordx4 v[194:197], v152, s[4:5]
	s_waitcnt vmcnt(12)
	v_pk_mul_f32 v[104:105], v[104:105], v[54:55]
	v_pk_mul_f32 v[106:107], v[106:107], v[56:57]
	v_pk_mul_f32 v[100:101], v[100:101], v[50:51]
	v_pk_mul_f32 v[102:103], v[102:103], v[52:53]
	v_lshlrev_b32_e32 v148, 16, v208
	v_and_b32_e32 v149, 0xffff0000, v208
	v_lshlrev_b32_e32 v150, 16, v209
	v_and_b32_e32 v151, 0xffff0000, v209
	v_pk_add_f32 v[104:105], v[104:105], v[148:149]
	v_pk_add_f32 v[106:107], v[106:107], v[150:151]
	v_lshlrev_b32_e32 v148, 16, v210
	v_and_b32_e32 v149, 0xffff0000, v210
	v_lshlrev_b32_e32 v150, 16, v211
	v_and_b32_e32 v151, 0xffff0000, v211
	v_pk_add_f32 v[100:101], v[100:101], v[148:149]
	v_pk_add_f32 v[102:103], v[102:103], v[150:151]
	v_cvt_pk_bf16_f32 v208, v104, v105
	v_cvt_pk_bf16_f32 v209, v106, v107
	v_cvt_pk_bf16_f32 v210, v100, v101
	v_cvt_pk_bf16_f32 v211, v102, v103
	global_store_dwordx4 v152, v[208:211], s[8:9] offset:256
	s_add_u32 s8, s8, 0x10000
	s_addc_u32 s9, s9, 0
	global_load_dwordx4 v[208:211], v152, s[4:5] offset:256
	s_add_u32 s4, s4, 0x10000
	s_addc_u32 s5, s5, 0
	s_waitcnt vmcnt(13)
	v_pk_mul_f32 v[94:95], v[94:95], v[66:67]
	v_pk_mul_f32 v[96:97], v[96:97], v[68:69]
	v_pk_mul_f32 v[90:91], v[90:91], v[70:71]
	v_pk_mul_f32 v[92:93], v[92:93], v[72:73]
	v_lshlrev_b32_e32 v148, 16, v212
	v_and_b32_e32 v149, 0xffff0000, v212
	v_lshlrev_b32_e32 v150, 16, v213
	v_and_b32_e32 v151, 0xffff0000, v213
	v_pk_add_f32 v[94:95], v[94:95], v[148:149]
	v_pk_add_f32 v[96:97], v[96:97], v[150:151]
	v_lshlrev_b32_e32 v148, 16, v214
	v_and_b32_e32 v149, 0xffff0000, v214
	v_lshlrev_b32_e32 v150, 16, v215
	v_and_b32_e32 v151, 0xffff0000, v215
	v_pk_add_f32 v[90:91], v[90:91], v[148:149]
	v_pk_add_f32 v[92:93], v[92:93], v[150:151]
	v_cvt_pk_bf16_f32 v212, v94, v95
	v_cvt_pk_bf16_f32 v213, v96, v97
	v_cvt_pk_bf16_f32 v214, v90, v91
	v_cvt_pk_bf16_f32 v215, v92, v93
	global_store_dwordx4 v152, v[212:215], s[8:9]
	s_nop 0
	global_load_dwordx4 v[212:215], v152, s[4:5]
	s_waitcnt vmcnt(14)
	v_pk_mul_f32 v[86:87], v[86:87], v[54:55]
	v_pk_mul_f32 v[88:89], v[88:89], v[56:57]
	v_pk_mul_f32 v[82:83], v[82:83], v[50:51]
	v_pk_mul_f32 v[84:85], v[84:85], v[52:53]
	v_lshlrev_b32_e32 v148, 16, v216
	v_and_b32_e32 v149, 0xffff0000, v216
	v_lshlrev_b32_e32 v150, 16, v217
	v_and_b32_e32 v151, 0xffff0000, v217
	v_pk_add_f32 v[86:87], v[86:87], v[148:149]
	v_pk_add_f32 v[88:89], v[88:89], v[150:151]
	v_lshlrev_b32_e32 v148, 16, v218
	v_and_b32_e32 v149, 0xffff0000, v218
	v_lshlrev_b32_e32 v150, 16, v219
	v_and_b32_e32 v151, 0xffff0000, v219
	v_pk_add_f32 v[82:83], v[82:83], v[148:149]
	v_pk_add_f32 v[84:85], v[84:85], v[150:151]
	v_cvt_pk_bf16_f32 v216, v86, v87
	v_cvt_pk_bf16_f32 v217, v88, v89
	v_cvt_pk_bf16_f32 v218, v82, v83
	v_cvt_pk_bf16_f32 v219, v84, v85
	global_store_dwordx4 v152, v[216:219], s[8:9] offset:256
	s_add_u32 s8, s8, 0x10000
	s_addc_u32 s9, s9, 0
	global_load_dwordx4 v[216:219], v152, s[4:5] offset:256
	s_add_u32 s4, s46, 0x80000
	s_addc_u32 s5, s47, 0
	s_waitcnt vmcnt(14)
	v_pk_mul_f32 v[78:79], v[78:79], v[66:67]
	v_pk_mul_f32 v[80:81], v[80:81], v[68:69]
	v_pk_mul_f32 v[74:75], v[74:75], v[70:71]
	v_pk_mul_f32 v[76:77], v[76:77], v[72:73]
	v_lshlrev_b32_e32 v148, 16, v178
	v_and_b32_e32 v149, 0xffff0000, v178
	v_lshlrev_b32_e32 v150, 16, v179
	v_and_b32_e32 v151, 0xffff0000, v179
	v_pk_add_f32 v[78:79], v[78:79], v[148:149]
	v_pk_add_f32 v[80:81], v[80:81], v[150:151]
	v_lshlrev_b32_e32 v148, 16, v180
	v_and_b32_e32 v149, 0xffff0000, v180
	v_lshlrev_b32_e32 v150, 16, v181
	v_and_b32_e32 v151, 0xffff0000, v181
	v_pk_add_f32 v[74:75], v[74:75], v[148:149]
	v_pk_add_f32 v[76:77], v[76:77], v[150:151]
	v_cvt_pk_bf16_f32 v178, v78, v79
	v_cvt_pk_bf16_f32 v179, v80, v81
	v_cvt_pk_bf16_f32 v180, v74, v75
	v_cvt_pk_bf16_f32 v181, v76, v77
	global_store_dwordx4 v152, v[178:181], s[4:5]
	s_waitcnt vmcnt(13)
	v_pk_mul_f32 v[62:63], v[62:63], v[54:55]
	v_pk_mul_f32 v[64:65], v[64:65], v[56:57]
	v_pk_mul_f32 v[58:59], v[58:59], v[50:51]
	v_pk_mul_f32 v[60:61], v[60:61], v[52:53]
	v_lshlrev_b32_e32 v148, 16, v182
	v_and_b32_e32 v149, 0xffff0000, v182
	v_lshlrev_b32_e32 v150, 16, v183
	v_and_b32_e32 v151, 0xffff0000, v183
	v_pk_add_f32 v[62:63], v[62:63], v[148:149]
	v_pk_add_f32 v[64:65], v[64:65], v[150:151]
	v_lshlrev_b32_e32 v148, 16, v184
	v_and_b32_e32 v149, 0xffff0000, v184
	v_lshlrev_b32_e32 v150, 16, v185
	v_and_b32_e32 v151, 0xffff0000, v185
	v_pk_add_f32 v[58:59], v[58:59], v[148:149]
	v_pk_add_f32 v[60:61], v[60:61], v[150:151]
	v_cvt_pk_bf16_f32 v182, v62, v63
	v_cvt_pk_bf16_f32 v183, v64, v65
	v_cvt_pk_bf16_f32 v184, v58, v59
	v_cvt_pk_bf16_f32 v185, v60, v61
	global_store_dwordx4 v152, v[182:185], s[4:5] offset:256
	s_add_u32 s4, s4, 0x10000
	s_addc_u32 s5, s5, 0
	s_waitcnt vmcnt(12)
	v_pk_mul_f32 v[46:47], v[46:47], v[66:67]
	v_pk_mul_f32 v[48:49], v[48:49], v[68:69]
	v_pk_mul_f32 v[42:43], v[42:43], v[70:71]
	v_pk_mul_f32 v[44:45], v[44:45], v[72:73]
	v_lshlrev_b32_e32 v148, 16, v186
	v_and_b32_e32 v149, 0xffff0000, v186
	v_lshlrev_b32_e32 v150, 16, v187
	v_and_b32_e32 v151, 0xffff0000, v187
	v_pk_add_f32 v[46:47], v[46:47], v[148:149]
	v_pk_add_f32 v[48:49], v[48:49], v[150:151]
	v_lshlrev_b32_e32 v148, 16, v188
	v_and_b32_e32 v149, 0xffff0000, v188
	v_lshlrev_b32_e32 v150, 16, v189
	v_and_b32_e32 v151, 0xffff0000, v189
	v_pk_add_f32 v[42:43], v[42:43], v[148:149]
	v_pk_add_f32 v[44:45], v[44:45], v[150:151]
	v_cvt_pk_bf16_f32 v186, v46, v47
	v_cvt_pk_bf16_f32 v187, v48, v49
	v_cvt_pk_bf16_f32 v188, v42, v43
	v_cvt_pk_bf16_f32 v189, v44, v45
	global_store_dwordx4 v152, v[186:189], s[4:5]
	s_waitcnt vmcnt(11)
	v_pk_mul_f32 v[38:39], v[38:39], v[54:55]
	v_pk_mul_f32 v[40:41], v[40:41], v[56:57]
	v_pk_mul_f32 v[34:35], v[34:35], v[50:51]
	v_pk_mul_f32 v[36:37], v[36:37], v[52:53]
	v_lshlrev_b32_e32 v148, 16, v190
	v_and_b32_e32 v149, 0xffff0000, v190
	v_lshlrev_b32_e32 v150, 16, v191
	v_and_b32_e32 v151, 0xffff0000, v191
	v_pk_add_f32 v[38:39], v[38:39], v[148:149]
	v_pk_add_f32 v[40:41], v[40:41], v[150:151]
	v_lshlrev_b32_e32 v148, 16, v192
	v_and_b32_e32 v149, 0xffff0000, v192
	v_lshlrev_b32_e32 v150, 16, v193
	v_and_b32_e32 v151, 0xffff0000, v193
	v_pk_add_f32 v[34:35], v[34:35], v[148:149]
	v_pk_add_f32 v[36:37], v[36:37], v[150:151]
	v_cvt_pk_bf16_f32 v190, v38, v39
	v_cvt_pk_bf16_f32 v191, v40, v41
	v_cvt_pk_bf16_f32 v192, v34, v35
	v_cvt_pk_bf16_f32 v193, v36, v37
	global_store_dwordx4 v152, v[190:193], s[4:5] offset:256
	s_add_u32 s4, s4, 0x10000
	s_addc_u32 s5, s5, 0
	s_waitcnt vmcnt(10)
	v_pk_mul_f32 v[30:31], v[30:31], v[66:67]
	v_pk_mul_f32 v[32:33], v[32:33], v[68:69]
	v_pk_mul_f32 v[26:27], v[26:27], v[70:71]
	v_pk_mul_f32 v[28:29], v[28:29], v[72:73]
	v_lshlrev_b32_e32 v148, 16, v194
	v_and_b32_e32 v149, 0xffff0000, v194
	v_lshlrev_b32_e32 v150, 16, v195
	v_and_b32_e32 v151, 0xffff0000, v195
	v_pk_add_f32 v[30:31], v[30:31], v[148:149]
	v_pk_add_f32 v[32:33], v[32:33], v[150:151]
	v_lshlrev_b32_e32 v148, 16, v196
	v_and_b32_e32 v149, 0xffff0000, v196
	v_lshlrev_b32_e32 v150, 16, v197
	v_and_b32_e32 v151, 0xffff0000, v197
	v_pk_add_f32 v[26:27], v[26:27], v[148:149]
	v_pk_add_f32 v[28:29], v[28:29], v[150:151]
	v_cvt_pk_bf16_f32 v194, v30, v31
	v_cvt_pk_bf16_f32 v195, v32, v33
	v_cvt_pk_bf16_f32 v196, v26, v27
	v_cvt_pk_bf16_f32 v197, v28, v29
	global_store_dwordx4 v152, v[194:197], s[4:5]
	s_waitcnt vmcnt(9)
	v_pk_mul_f32 v[22:23], v[22:23], v[54:55]
	v_pk_mul_f32 v[24:25], v[24:25], v[56:57]
	v_pk_mul_f32 v[18:19], v[18:19], v[50:51]
	v_pk_mul_f32 v[20:21], v[20:21], v[52:53]
	v_lshlrev_b32_e32 v148, 16, v208
	v_and_b32_e32 v149, 0xffff0000, v208
	v_lshlrev_b32_e32 v150, 16, v209
	v_and_b32_e32 v151, 0xffff0000, v209
	v_pk_add_f32 v[22:23], v[22:23], v[148:149]
	v_pk_add_f32 v[24:25], v[24:25], v[150:151]
	v_lshlrev_b32_e32 v148, 16, v210
	v_and_b32_e32 v149, 0xffff0000, v210
	v_lshlrev_b32_e32 v150, 16, v211
	v_and_b32_e32 v151, 0xffff0000, v211
	v_pk_add_f32 v[18:19], v[18:19], v[148:149]
	v_pk_add_f32 v[20:21], v[20:21], v[150:151]
	v_cvt_pk_bf16_f32 v208, v22, v23
	v_cvt_pk_bf16_f32 v209, v24, v25
	v_cvt_pk_bf16_f32 v210, v18, v19
	v_cvt_pk_bf16_f32 v211, v20, v21
	global_store_dwordx4 v152, v[208:211], s[4:5] offset:256
	s_add_u32 s4, s4, 0x10000
	s_addc_u32 s5, s5, 0
	s_waitcnt vmcnt(8)
	v_pk_mul_f32 v[14:15], v[14:15], v[66:67]
	v_pk_mul_f32 v[16:17], v[16:17], v[68:69]
	v_pk_mul_f32 v[10:11], v[10:11], v[70:71]
	v_pk_mul_f32 v[12:13], v[12:13], v[72:73]
	v_lshlrev_b32_e32 v148, 16, v212
	v_and_b32_e32 v149, 0xffff0000, v212
	v_lshlrev_b32_e32 v150, 16, v213
	v_and_b32_e32 v151, 0xffff0000, v213
	v_pk_add_f32 v[14:15], v[14:15], v[148:149]
	v_pk_add_f32 v[16:17], v[16:17], v[150:151]
	v_lshlrev_b32_e32 v148, 16, v214
	v_and_b32_e32 v149, 0xffff0000, v214
	v_lshlrev_b32_e32 v150, 16, v215
	v_and_b32_e32 v151, 0xffff0000, v215
	v_pk_add_f32 v[10:11], v[10:11], v[148:149]
	v_pk_add_f32 v[12:13], v[12:13], v[150:151]
	v_cvt_pk_bf16_f32 v212, v14, v15
	v_cvt_pk_bf16_f32 v213, v16, v17
	v_cvt_pk_bf16_f32 v214, v10, v11
	v_cvt_pk_bf16_f32 v215, v12, v13
	global_store_dwordx4 v152, v[212:215], s[4:5]
	s_waitcnt vmcnt(7)
	v_pk_mul_f32 v[6:7], v[6:7], v[54:55]
	v_pk_mul_f32 v[8:9], v[8:9], v[56:57]
	v_pk_mul_f32 v[2:3], v[2:3], v[50:51]
	v_pk_mul_f32 v[4:5], v[4:5], v[52:53]
	v_lshlrev_b32_e32 v148, 16, v216
	v_and_b32_e32 v149, 0xffff0000, v216
	v_lshlrev_b32_e32 v150, 16, v217
	v_and_b32_e32 v151, 0xffff0000, v217
	v_pk_add_f32 v[6:7], v[6:7], v[148:149]
	v_pk_add_f32 v[8:9], v[8:9], v[150:151]
	v_lshlrev_b32_e32 v148, 16, v218
	v_and_b32_e32 v149, 0xffff0000, v218
	v_lshlrev_b32_e32 v150, 16, v219
	v_and_b32_e32 v151, 0xffff0000, v219
	v_pk_add_f32 v[2:3], v[2:3], v[148:149]
	v_pk_add_f32 v[4:5], v[4:5], v[150:151]
	v_cvt_pk_bf16_f32 v216, v6, v7
	v_cvt_pk_bf16_f32 v217, v8, v9
	v_cvt_pk_bf16_f32 v218, v2, v3
	v_cvt_pk_bf16_f32 v219, v4, v5
	global_store_dwordx4 v152, v[216:219], s[4:5] offset:256
	s_branch .LBB0_820

.LBB0_715:
	v_cvt_f32_u32_e32 v152, s7
	v_cvt_f32_u32_e32 v153, s6
	s_brev_b32 s8, 31
	v_lshlrev_b64 v[148:149], 13, v[168:169]
	v_rcp_iflag_f32_e32 v154, v152
	s_mov_b32 s9, -1
	v_lshl_add_u64 v[148:149], v[148:149], 0, s[8:9]
	s_and_b64 vcc, exec, s[4:5]
	s_cbranch_vccz .LBB0_717
	v_mul_f32_e32 v150, v153, v154
	v_trunc_f32_e32 v150, v150
	v_cvt_u32_f32_e32 v151, v150
	v_fma_f32 v150, -v150, v152, v153
	v_cmp_ge_f32_e64 s[4:5], |v150|, v152
	s_cmp_lg_u64 s[4:5], 0
	v_readfirstlane_b32 s4, v151
	s_addc_u32 s4, s4, 0
	s_and_b32 s4, s4, 0xff
	s_lshl_b32 s4, s4, 23
	s_add_u32 s4, s76, s4
	s_addc_u32 s5, s77, 0
	v_lshl_add_u64 v[150:151], s[4:5], 0, v[148:149]
	v_lshl_add_u64 v[150:151], v[166:167], 2, v[150:151]
	s_cmp_eq_u32 s100, 2
	s_cbranch_scc1 .Lgo_sp0
	global_store_dwordx4 v[150:151], v[144:147], off
	global_store_dwordx4 v[150:151], v[140:143], off offset:16
.Lgo_sp0:
.LBB0_717:
	v_pk_mul_f32 v[138:139], v[138:139], v[56:57]
	v_pk_mul_f32 v[136:137], v[136:137], v[54:55]
	v_pk_mul_f32 v[134:135], v[134:135], v[52:53]
	v_pk_mul_f32 v[132:133], v[132:133], v[50:51]
	s_mov_b64 s[4:5], -1
	s_and_b64 vcc, exec, s[62:63]
	s_cbranch_vccz .LBB0_722
	s_and_b64 vcc, exec, s[42:43]
	s_cbranch_vccnz .LBB0_826
	v_lshl_add_u64 v[140:141], v[170:171], 2, s[38:39]
	global_load_dwordx4 v[144:147], v[140:141], off offset:528
	s_nop 0
	global_load_dwordx4 v[140:143], v[140:141], off offset:512
	v_or_b32_e32 v170, 0x80, v170
	v_lshl_add_u64 v[150:151], v[170:171], 1, s[46:47]
	s_cbranch_execnz .LBB0_721

.LBB0_722:
	s_and_b64 vcc, exec, s[4:5]
	s_cbranch_vccz .LBB0_724
	v_mul_f32_e32 v140, v153, v154
	v_trunc_f32_e32 v140, v140
	v_cvt_u32_f32_e32 v141, v140
	v_fma_f32 v140, -v140, v152, v153
	v_cmp_ge_f32_e64 s[4:5], |v140|, v152
	s_cmp_lg_u64 s[4:5], 0
	v_readfirstlane_b32 s4, v141
	s_addc_u32 s4, s4, 0
	s_and_b32 s4, s4, 0xff
	s_lshl_b32 s4, s4, 23
	s_add_u32 s4, s76, s4
	s_addc_u32 s5, s77, 0
	v_lshl_add_u64 v[140:141], s[4:5], 0, v[148:149]
	v_lshl_add_u64 v[140:141], v[166:167], 2, v[140:141]
	s_cmp_eq_u32 s100, 1
	s_cbranch_scc1 .Lgo_sp1
	global_store_dwordx4 v[140:141], v[136:139], off offset:512
	global_store_dwordx4 v[140:141], v[132:135], off offset:528
.Lgo_sp1:
.LBB0_724:
	s_nop 1
	v_or_b32_e32 v132, 16, v168
	v_ashrrev_i32_e32 v133, 31, v132
	v_lshlrev_b64 v[132:133], 11, v[132:133]
	v_lshl_add_u64 v[140:141], v[132:133], 0, v[166:167]
	v_pk_mul_f32 v[130:131], v[130:131], v[68:69]
	v_pk_mul_f32 v[128:129], v[128:129], v[66:67]
	v_pk_mul_f32 v[126:127], v[126:127], v[72:73]
	v_pk_mul_f32 v[124:125], v[124:125], v[70:71]
	s_mov_b64 s[4:5], -1
	s_and_b64 vcc, exec, s[62:63]
	s_cbranch_vccz .LBB0_729
	s_and_b64 vcc, exec, s[42:43]
	s_cbranch_vccnz .LBB0_827
	v_lshl_add_u64 v[132:133], v[140:141], 2, s[38:39]
	global_load_dwordx4 v[136:139], v[132:133], off offset:16
	s_nop 0
	global_load_dwordx4 v[132:135], v[132:133], off
	v_lshl_add_u64 v[142:143], v[140:141], 1, s[46:47]
	s_cbranch_execnz .LBB0_728

.LBB0_729:
	s_mov_b32 s6, 0xf8020000
	s_nop 0
	v_lshlrev_b64 v[132:133], 13, v[168:169]
	s_mov_b32 s7, -1
	v_lshl_add_u64 v[132:133], v[132:133], 0, s[6:7]
	s_and_b64 vcc, exec, s[4:5]
	s_cbranch_vccz .LBB0_731
	v_mul_f32_e32 v134, v153, v154
	v_trunc_f32_e32 v134, v134
	v_cvt_u32_f32_e32 v135, v134
	v_fma_f32 v134, -v134, v152, v153
	v_cmp_ge_f32_e64 s[4:5], |v134|, v152
	s_cmp_lg_u64 s[4:5], 0
	v_readfirstlane_b32 s4, v135
	s_addc_u32 s4, s4, 0
	s_and_b32 s4, s4, 0xff
	s_lshl_b32 s4, s4, 23
	s_add_u32 s4, s76, s4
	s_addc_u32 s5, s77, 0
	v_lshl_add_u64 v[134:135], s[4:5], 0, v[132:133]
	v_lshl_add_u64 v[134:135], v[166:167], 2, v[134:135]
	s_cmp_eq_u32 s100, 2
	s_cbranch_scc1 .Lgo_sp2
	global_store_dwordx4 v[134:135], v[128:131], off
	global_store_dwordx4 v[134:135], v[124:127], off offset:16
.Lgo_sp2:
.LBB0_731:
	v_pk_mul_f32 v[122:123], v[122:123], v[56:57]
	v_pk_mul_f32 v[120:121], v[120:121], v[54:55]
	v_pk_mul_f32 v[118:119], v[118:119], v[52:53]
	v_pk_mul_f32 v[116:117], v[116:117], v[50:51]
	s_mov_b64 s[4:5], -1
	s_and_b64 vcc, exec, s[62:63]
	s_cbranch_vccz .LBB0_736
	s_and_b64 vcc, exec, s[42:43]
	s_cbranch_vccnz .LBB0_828
	v_lshl_add_u64 v[124:125], v[140:141], 2, s[38:39]
	global_load_dwordx4 v[128:131], v[124:125], off offset:528
	s_nop 0
	global_load_dwordx4 v[124:127], v[124:125], off offset:512
	v_or_b32_e32 v140, 0x80, v140
	v_lshl_add_u64 v[134:135], v[140:141], 1, s[46:47]
	s_cbranch_execnz .LBB0_735

.LBB0_736:
	s_and_b64 vcc, exec, s[4:5]
	s_cbranch_vccz .LBB0_738
	v_mul_f32_e32 v124, v153, v154
	v_trunc_f32_e32 v124, v124
	v_cvt_u32_f32_e32 v125, v124
	v_fma_f32 v124, -v124, v152, v153
	v_cmp_ge_f32_e64 s[4:5], |v124|, v152
	s_cmp_lg_u64 s[4:5], 0
	v_readfirstlane_b32 s4, v125
	s_addc_u32 s4, s4, 0
	s_and_b32 s4, s4, 0xff
	s_lshl_b32 s4, s4, 23
	s_add_u32 s4, s76, s4
	s_addc_u32 s5, s77, 0
	v_lshl_add_u64 v[124:125], s[4:5], 0, v[132:133]
	v_lshl_add_u64 v[124:125], v[166:167], 2, v[124:125]
	s_cmp_eq_u32 s100, 1
	s_cbranch_scc1 .Lgo_sp3
	global_store_dwordx4 v[124:125], v[120:123], off offset:512
	global_store_dwordx4 v[124:125], v[116:119], off offset:528
.Lgo_sp3:
.LBB0_738:
	s_nop 1
	v_or_b32_e32 v116, 32, v168
	v_ashrrev_i32_e32 v117, 31, v116
	v_lshlrev_b64 v[116:117], 11, v[116:117]
	v_lshl_add_u64 v[124:125], v[116:117], 0, v[166:167]
	v_pk_mul_f32 v[114:115], v[114:115], v[68:69]
	v_pk_mul_f32 v[112:113], v[112:113], v[66:67]
	v_pk_mul_f32 v[110:111], v[110:111], v[72:73]
	v_pk_mul_f32 v[108:109], v[108:109], v[70:71]
	s_mov_b64 s[4:5], -1
	s_and_b64 vcc, exec, s[62:63]
	s_cbranch_vccz .LBB0_743
	s_and_b64 vcc, exec, s[42:43]
	s_cbranch_vccnz .LBB0_829
	v_lshl_add_u64 v[116:117], v[124:125], 2, s[38:39]
	global_load_dwordx4 v[120:123], v[116:117], off offset:16
	s_nop 0
	global_load_dwordx4 v[116:119], v[116:117], off
	v_lshl_add_u64 v[126:127], v[124:125], 1, s[46:47]
	s_cbranch_execnz .LBB0_742

.LBB0_743:
	s_mov_b32 s6, 0xf8040000
	s_nop 0
	v_lshlrev_b64 v[116:117], 13, v[168:169]
	s_mov_b32 s7, -1
	v_lshl_add_u64 v[116:117], v[116:117], 0, s[6:7]
	s_and_b64 vcc, exec, s[4:5]
	s_cbranch_vccz .LBB0_745
	v_mul_f32_e32 v118, v153, v154
	v_trunc_f32_e32 v118, v118
	v_cvt_u32_f32_e32 v119, v118
	v_fma_f32 v118, -v118, v152, v153
	v_cmp_ge_f32_e64 s[4:5], |v118|, v152
	s_cmp_lg_u64 s[4:5], 0
	v_readfirstlane_b32 s4, v119
	s_addc_u32 s4, s4, 0
	s_and_b32 s4, s4, 0xff
	s_lshl_b32 s4, s4, 23
	s_add_u32 s4, s76, s4
	s_addc_u32 s5, s77, 0
	v_lshl_add_u64 v[118:119], s[4:5], 0, v[116:117]
	v_lshl_add_u64 v[118:119], v[166:167], 2, v[118:119]
	s_cmp_eq_u32 s100, 2
	s_cbranch_scc1 .Lgo_sp4
	global_store_dwordx4 v[118:119], v[112:115], off
	global_store_dwordx4 v[118:119], v[108:111], off offset:16
.Lgo_sp4:
.LBB0_745:
	v_pk_mul_f32 v[106:107], v[106:107], v[56:57]
	v_pk_mul_f32 v[104:105], v[104:105], v[54:55]
	v_pk_mul_f32 v[102:103], v[102:103], v[52:53]
	v_pk_mul_f32 v[100:101], v[100:101], v[50:51]
	s_mov_b64 s[4:5], -1
	s_and_b64 vcc, exec, s[62:63]
	s_cbranch_vccz .LBB0_750
	s_and_b64 vcc, exec, s[42:43]
	s_cbranch_vccnz .LBB0_830
	v_lshl_add_u64 v[108:109], v[124:125], 2, s[38:39]
	global_load_dwordx4 v[112:115], v[108:109], off offset:528
	s_nop 0
	global_load_dwordx4 v[108:111], v[108:109], off offset:512
	v_or_b32_e32 v124, 0x80, v124
	v_lshl_add_u64 v[118:119], v[124:125], 1, s[46:47]
	s_cbranch_execnz .LBB0_749

.LBB0_750:
	s_and_b64 vcc, exec, s[4:5]
	s_cbranch_vccz .LBB0_752
	v_mul_f32_e32 v108, v153, v154
	v_trunc_f32_e32 v108, v108
	v_cvt_u32_f32_e32 v109, v108
	v_fma_f32 v108, -v108, v152, v153
	v_cmp_ge_f32_e64 s[4:5], |v108|, v152
	s_cmp_lg_u64 s[4:5], 0
	v_readfirstlane_b32 s4, v109
	s_addc_u32 s4, s4, 0
	s_and_b32 s4, s4, 0xff
	s_lshl_b32 s4, s4, 23
	s_add_u32 s4, s76, s4
	s_addc_u32 s5, s77, 0
	v_lshl_add_u64 v[108:109], s[4:5], 0, v[116:117]
	v_lshl_add_u64 v[108:109], v[166:167], 2, v[108:109]
	s_cmp_eq_u32 s100, 1
	s_cbranch_scc1 .Lgo_sp5
	global_store_dwordx4 v[108:109], v[104:107], off offset:512
	global_store_dwordx4 v[108:109], v[100:103], off offset:528
.Lgo_sp5:
.LBB0_752:
	s_nop 1
	v_or_b32_e32 v100, 48, v168
	v_ashrrev_i32_e32 v101, 31, v100
	v_lshlrev_b64 v[100:101], 11, v[100:101]
	v_lshl_add_u64 v[108:109], v[100:101], 0, v[166:167]
	v_pk_mul_f32 v[96:97], v[96:97], v[68:69]
	v_pk_mul_f32 v[94:95], v[94:95], v[66:67]
	v_pk_mul_f32 v[92:93], v[92:93], v[72:73]
	v_pk_mul_f32 v[90:91], v[90:91], v[70:71]
	s_mov_b64 s[4:5], -1
	s_and_b64 vcc, exec, s[62:63]
	s_cbranch_vccz .LBB0_757
	s_and_b64 vcc, exec, s[42:43]
	s_cbranch_vccnz .LBB0_831
	v_lshl_add_u64 v[100:101], v[108:109], 2, s[38:39]
	global_load_dwordx4 v[104:107], v[100:101], off offset:16
	s_nop 0
	global_load_dwordx4 v[100:103], v[100:101], off
	v_lshl_add_u64 v[110:111], v[108:109], 1, s[46:47]
	s_cbranch_execnz .LBB0_756

.LBB0_757:
	s_mov_b32 s6, 0xf8060000
	s_nop 0
	v_lshlrev_b64 v[100:101], 13, v[168:169]
	s_mov_b32 s7, -1
	v_lshl_add_u64 v[100:101], v[100:101], 0, s[6:7]
	s_and_b64 vcc, exec, s[4:5]
	s_cbranch_vccz .LBB0_759
	v_mul_f32_e32 v102, v153, v154
	v_trunc_f32_e32 v102, v102
	v_cvt_u32_f32_e32 v103, v102
	v_fma_f32 v102, -v102, v152, v153
	v_cmp_ge_f32_e64 s[4:5], |v102|, v152
	s_cmp_lg_u64 s[4:5], 0
	v_readfirstlane_b32 s4, v103
	s_addc_u32 s4, s4, 0
	s_and_b32 s4, s4, 0xff
	s_lshl_b32 s4, s4, 23
	s_add_u32 s4, s76, s4
	s_addc_u32 s5, s77, 0
	v_lshl_add_u64 v[102:103], s[4:5], 0, v[100:101]
	v_lshl_add_u64 v[102:103], v[166:167], 2, v[102:103]
	s_cmp_eq_u32 s100, 2
	s_cbranch_scc1 .Lgo_sp6
	global_store_dwordx4 v[102:103], v[94:97], off
	global_store_dwordx4 v[102:103], v[90:93], off offset:16
.Lgo_sp6:
.LBB0_759:
	v_pk_mul_f32 v[88:89], v[88:89], v[56:57]
	v_pk_mul_f32 v[86:87], v[86:87], v[54:55]
	v_pk_mul_f32 v[84:85], v[84:85], v[52:53]
	v_pk_mul_f32 v[82:83], v[82:83], v[50:51]
	s_mov_b64 s[4:5], -1
	s_and_b64 vcc, exec, s[62:63]
	s_cbranch_vccz .LBB0_764
	s_and_b64 vcc, exec, s[42:43]
	s_cbranch_vccnz .LBB0_832
	v_lshl_add_u64 v[90:91], v[108:109], 2, s[38:39]
	global_load_dwordx4 v[94:97], v[90:91], off offset:528
	s_nop 0
	global_load_dwordx4 v[90:93], v[90:91], off offset:512
	v_or_b32_e32 v108, 0x80, v108
	v_lshl_add_u64 v[102:103], v[108:109], 1, s[46:47]
	s_cbranch_execnz .LBB0_763

.LBB0_764:
	s_and_b64 vcc, exec, s[4:5]
	s_cbranch_vccz .LBB0_766
	v_mul_f32_e32 v90, v153, v154
	v_trunc_f32_e32 v90, v90
	v_cvt_u32_f32_e32 v91, v90
	v_fma_f32 v90, -v90, v152, v153
	v_cmp_ge_f32_e64 s[4:5], |v90|, v152
	s_cmp_lg_u64 s[4:5], 0
	v_readfirstlane_b32 s4, v91
	s_addc_u32 s4, s4, 0
	s_and_b32 s4, s4, 0xff
	s_lshl_b32 s4, s4, 23
	s_add_u32 s4, s76, s4
	s_addc_u32 s5, s77, 0
	v_lshl_add_u64 v[90:91], s[4:5], 0, v[100:101]
	v_lshl_add_u64 v[90:91], v[166:167], 2, v[90:91]
	s_cmp_eq_u32 s100, 1
	s_cbranch_scc1 .Lgo_sp7
	global_store_dwordx4 v[90:91], v[86:89], off offset:512
	global_store_dwordx4 v[90:91], v[82:85], off offset:528
.Lgo_sp7:
.LBB0_766:
	s_nop 1
	v_lshlrev_b64 v[82:83], 11, v[168:169]
	v_lshl_add_u64 v[82:83], v[82:83], 0, v[166:167]
	s_mov_b64 s[4:5], 0x40000
	v_lshl_add_u64 v[90:91], v[82:83], 0, s[4:5]
	v_pk_mul_f32 v[80:81], v[80:81], v[68:69]
	v_pk_mul_f32 v[78:79], v[78:79], v[66:67]
	v_pk_mul_f32 v[76:77], v[76:77], v[72:73]
	v_pk_mul_f32 v[74:75], v[74:75], v[70:71]
	s_mov_b64 s[4:5], -1
	s_and_b64 vcc, exec, s[62:63]
	s_cbranch_vccz .LBB0_771
	s_and_b64 vcc, exec, s[42:43]
	s_cbranch_vccnz .LBB0_833
	v_lshl_add_u64 v[82:83], v[90:91], 2, s[38:39]
	global_load_dwordx4 v[86:89], v[82:83], off offset:16
	s_nop 0
	global_load_dwordx4 v[82:85], v[82:83], off
	v_lshl_add_u64 v[92:93], v[90:91], 1, s[46:47]
	s_cbranch_execnz .LBB0_770

.LBB0_771:
	s_mov_b32 s6, 0xf8100000
	s_nop 0
	v_lshlrev_b64 v[82:83], 13, v[168:169]
	s_mov_b32 s7, -1
	v_lshl_add_u64 v[82:83], v[82:83], 0, s[6:7]
	s_and_b64 vcc, exec, s[4:5]
	s_cbranch_vccz .LBB0_773
	v_mul_f32_e32 v84, v153, v154
	v_trunc_f32_e32 v84, v84
	v_cvt_u32_f32_e32 v85, v84
	v_fma_f32 v84, -v84, v152, v153
	v_cmp_ge_f32_e64 s[4:5], |v84|, v152
	s_cmp_lg_u64 s[4:5], 0
	v_readfirstlane_b32 s4, v85
	s_addc_u32 s4, s4, 0
	s_and_b32 s4, s4, 0xff
	s_lshl_b32 s4, s4, 23
	s_add_u32 s4, s76, s4
	s_addc_u32 s5, s77, 0
	v_lshl_add_u64 v[84:85], s[4:5], 0, v[82:83]
	v_lshl_add_u64 v[84:85], v[166:167], 2, v[84:85]
	s_cmp_eq_u32 s100, 2
	s_cbranch_scc1 .Lgo_sp8
	global_store_dwordx4 v[84:85], v[78:81], off
	global_store_dwordx4 v[84:85], v[74:77], off offset:16
.Lgo_sp8:
.LBB0_773:
	v_pk_mul_f32 v[64:65], v[64:65], v[56:57]
	v_pk_mul_f32 v[62:63], v[62:63], v[54:55]
	v_pk_mul_f32 v[60:61], v[60:61], v[52:53]
	v_pk_mul_f32 v[58:59], v[58:59], v[50:51]
	s_mov_b64 s[4:5], -1
	s_and_b64 vcc, exec, s[62:63]
	s_cbranch_vccz .LBB0_778
	s_and_b64 vcc, exec, s[42:43]
	s_cbranch_vccnz .LBB0_834
	v_lshl_add_u64 v[74:75], v[90:91], 2, s[38:39]
	global_load_dwordx4 v[78:81], v[74:75], off offset:528
	s_nop 0
	global_load_dwordx4 v[74:77], v[74:75], off offset:512
	v_or_b32_e32 v90, 0x80, v90
	v_lshl_add_u64 v[84:85], v[90:91], 1, s[46:47]
	s_cbranch_execnz .LBB0_777

.LBB0_778:
	s_and_b64 vcc, exec, s[4:5]
	s_cbranch_vccz .LBB0_780
	v_mul_f32_e32 v74, v153, v154
	v_trunc_f32_e32 v74, v74
	v_cvt_u32_f32_e32 v75, v74
	v_fma_f32 v74, -v74, v152, v153
	v_cmp_ge_f32_e64 s[4:5], |v74|, v152
	s_cmp_lg_u64 s[4:5], 0
	v_readfirstlane_b32 s4, v75
	s_addc_u32 s4, s4, 0
	s_and_b32 s4, s4, 0xff
	s_lshl_b32 s4, s4, 23
	s_add_u32 s4, s76, s4
	s_addc_u32 s5, s77, 0
	v_lshl_add_u64 v[74:75], s[4:5], 0, v[82:83]
	v_lshl_add_u64 v[74:75], v[166:167], 2, v[74:75]
	s_cmp_eq_u32 s100, 1
	s_cbranch_scc1 .Lgo_sp9
	global_store_dwordx4 v[74:75], v[62:65], off offset:512
	global_store_dwordx4 v[74:75], v[58:61], off offset:528
.Lgo_sp9:
.LBB0_780:
	s_nop 1
	v_lshlrev_b64 v[58:59], 11, v[168:169]
	v_lshl_add_u64 v[58:59], v[58:59], 0, v[166:167]
	s_mov_b64 s[4:5], 0x48000
	v_lshl_add_u64 v[74:75], v[58:59], 0, s[4:5]
	v_pk_mul_f32 v[48:49], v[48:49], v[68:69]
	v_pk_mul_f32 v[46:47], v[46:47], v[66:67]
	v_pk_mul_f32 v[44:45], v[44:45], v[72:73]
	v_pk_mul_f32 v[42:43], v[42:43], v[70:71]
	s_mov_b64 s[4:5], -1
	s_and_b64 vcc, exec, s[62:63]
	s_cbranch_vccz .LBB0_785
	s_and_b64 vcc, exec, s[42:43]
	s_cbranch_vccnz .LBB0_835
	v_lshl_add_u64 v[58:59], v[74:75], 2, s[38:39]
	global_load_dwordx4 v[62:65], v[58:59], off offset:16
	s_nop 0
	global_load_dwordx4 v[58:61], v[58:59], off
	v_lshl_add_u64 v[76:77], v[74:75], 1, s[46:47]
	s_cbranch_execnz .LBB0_784

.LBB0_785:
	s_mov_b32 s6, 0xf8120000
	s_nop 0
	v_lshlrev_b64 v[58:59], 13, v[168:169]
	s_mov_b32 s7, -1
	v_lshl_add_u64 v[58:59], v[58:59], 0, s[6:7]
	s_and_b64 vcc, exec, s[4:5]
	s_cbranch_vccz .LBB0_787
	v_mul_f32_e32 v60, v153, v154
	v_trunc_f32_e32 v60, v60
	v_cvt_u32_f32_e32 v61, v60
	v_fma_f32 v60, -v60, v152, v153
	v_cmp_ge_f32_e64 s[4:5], |v60|, v152
	s_cmp_lg_u64 s[4:5], 0
	v_readfirstlane_b32 s4, v61
	s_addc_u32 s4, s4, 0
	s_and_b32 s4, s4, 0xff
	s_lshl_b32 s4, s4, 23
	s_add_u32 s4, s76, s4
	s_addc_u32 s5, s77, 0
	v_lshl_add_u64 v[60:61], s[4:5], 0, v[58:59]
	v_lshl_add_u64 v[60:61], v[166:167], 2, v[60:61]
	s_cmp_eq_u32 s100, 2
	s_cbranch_scc1 .Lgo_sp10
	global_store_dwordx4 v[60:61], v[46:49], off
	global_store_dwordx4 v[60:61], v[42:45], off offset:16
.Lgo_sp10:
.LBB0_787:
	v_pk_mul_f32 v[40:41], v[40:41], v[56:57]
	v_pk_mul_f32 v[38:39], v[38:39], v[54:55]
	v_pk_mul_f32 v[36:37], v[36:37], v[52:53]
	v_pk_mul_f32 v[34:35], v[34:35], v[50:51]
	s_mov_b64 s[4:5], -1
	s_and_b64 vcc, exec, s[62:63]
	s_cbranch_vccz .LBB0_792
	s_and_b64 vcc, exec, s[42:43]
	s_cbranch_vccnz .LBB0_836
	v_lshl_add_u64 v[42:43], v[74:75], 2, s[38:39]
	global_load_dwordx4 v[46:49], v[42:43], off offset:528
	s_nop 0
	global_load_dwordx4 v[42:45], v[42:43], off offset:512
	v_or_b32_e32 v74, 0x80, v74
	v_lshl_add_u64 v[60:61], v[74:75], 1, s[46:47]
	s_cbranch_execnz .LBB0_791

.LBB0_792:
	s_and_b64 vcc, exec, s[4:5]
	s_cbranch_vccz .LBB0_794
	v_mul_f32_e32 v42, v153, v154
	v_trunc_f32_e32 v42, v42
	v_cvt_u32_f32_e32 v43, v42
	v_fma_f32 v42, -v42, v152, v153
	v_cmp_ge_f32_e64 s[4:5], |v42|, v152
	s_cmp_lg_u64 s[4:5], 0
	v_readfirstlane_b32 s4, v43
	s_addc_u32 s4, s4, 0
	s_and_b32 s4, s4, 0xff
	s_lshl_b32 s4, s4, 23
	s_add_u32 s4, s76, s4
	s_addc_u32 s5, s77, 0
	v_lshl_add_u64 v[42:43], s[4:5], 0, v[58:59]
	v_lshl_add_u64 v[42:43], v[166:167], 2, v[42:43]
	s_cmp_eq_u32 s100, 1
	s_cbranch_scc1 .Lgo_sp11
	global_store_dwordx4 v[42:43], v[38:41], off offset:512
	global_store_dwordx4 v[42:43], v[34:37], off offset:528
.Lgo_sp11:
.LBB0_794:
	s_nop 1
	v_lshlrev_b64 v[34:35], 11, v[168:169]
	v_lshl_add_u64 v[34:35], v[34:35], 0, v[166:167]
	s_mov_b64 s[4:5], 0x50000
	v_lshl_add_u64 v[42:43], v[34:35], 0, s[4:5]
	v_pk_mul_f32 v[32:33], v[32:33], v[68:69]
	v_pk_mul_f32 v[30:31], v[30:31], v[66:67]
	v_pk_mul_f32 v[28:29], v[28:29], v[72:73]
	v_pk_mul_f32 v[26:27], v[26:27], v[70:71]
	s_mov_b64 s[4:5], -1
	s_and_b64 vcc, exec, s[62:63]
	s_cbranch_vccz .LBB0_799
	s_and_b64 vcc, exec, s[42:43]
	s_cbranch_vccnz .LBB0_837
	v_lshl_add_u64 v[34:35], v[42:43], 2, s[38:39]
	global_load_dwordx4 v[38:41], v[34:35], off offset:16
	s_nop 0
	global_load_dwordx4 v[34:37], v[34:35], off
	v_lshl_add_u64 v[44:45], v[42:43], 1, s[46:47]
	s_cbranch_execnz .LBB0_798

.LBB0_799:
	s_mov_b32 s6, 0xf8140000
	s_nop 0
	v_lshlrev_b64 v[34:35], 13, v[168:169]
	s_mov_b32 s7, -1
	v_lshl_add_u64 v[34:35], v[34:35], 0, s[6:7]
	s_and_b64 vcc, exec, s[4:5]
	s_cbranch_vccz .LBB0_801
	v_mul_f32_e32 v36, v153, v154
	v_trunc_f32_e32 v36, v36
	v_cvt_u32_f32_e32 v37, v36
	v_fma_f32 v36, -v36, v152, v153
	v_cmp_ge_f32_e64 s[4:5], |v36|, v152
	s_cmp_lg_u64 s[4:5], 0
	v_readfirstlane_b32 s4, v37
	s_addc_u32 s4, s4, 0
	s_and_b32 s4, s4, 0xff
	s_lshl_b32 s4, s4, 23
	s_add_u32 s4, s76, s4
	s_addc_u32 s5, s77, 0
	v_lshl_add_u64 v[36:37], s[4:5], 0, v[34:35]
	v_lshl_add_u64 v[36:37], v[166:167], 2, v[36:37]
	s_cmp_eq_u32 s100, 2
	s_cbranch_scc1 .Lgo_sp12
	global_store_dwordx4 v[36:37], v[30:33], off
	global_store_dwordx4 v[36:37], v[26:29], off offset:16
.Lgo_sp12:
.LBB0_801:
	v_pk_mul_f32 v[24:25], v[24:25], v[56:57]
	v_pk_mul_f32 v[22:23], v[22:23], v[54:55]
	v_pk_mul_f32 v[20:21], v[20:21], v[52:53]
	v_pk_mul_f32 v[18:19], v[18:19], v[50:51]
	s_mov_b64 s[4:5], -1
	s_and_b64 vcc, exec, s[62:63]
	s_cbranch_vccz .LBB0_806
	s_and_b64 vcc, exec, s[42:43]
	s_cbranch_vccnz .LBB0_838
	v_lshl_add_u64 v[26:27], v[42:43], 2, s[38:39]
	global_load_dwordx4 v[30:33], v[26:27], off offset:528
	s_nop 0
	global_load_dwordx4 v[26:29], v[26:27], off offset:512
	v_or_b32_e32 v42, 0x80, v42
	v_lshl_add_u64 v[36:37], v[42:43], 1, s[46:47]
	s_cbranch_execnz .LBB0_805

.LBB0_806:
	s_and_b64 vcc, exec, s[4:5]
	s_cbranch_vccz .LBB0_808
	v_mul_f32_e32 v26, v153, v154
	v_trunc_f32_e32 v26, v26
	v_cvt_u32_f32_e32 v27, v26
	v_fma_f32 v26, -v26, v152, v153
	v_cmp_ge_f32_e64 s[4:5], |v26|, v152
	s_cmp_lg_u64 s[4:5], 0
	v_readfirstlane_b32 s4, v27
	s_addc_u32 s4, s4, 0
	s_and_b32 s4, s4, 0xff
	s_lshl_b32 s4, s4, 23
	s_add_u32 s4, s76, s4
	s_addc_u32 s5, s77, 0
	v_lshl_add_u64 v[26:27], s[4:5], 0, v[34:35]
	v_lshl_add_u64 v[26:27], v[166:167], 2, v[26:27]
	s_cmp_eq_u32 s100, 1
	s_cbranch_scc1 .Lgo_sp13
	global_store_dwordx4 v[26:27], v[22:25], off offset:512
	global_store_dwordx4 v[26:27], v[18:21], off offset:528
.Lgo_sp13:
.LBB0_808:
	s_nop 1
	v_lshlrev_b64 v[18:19], 11, v[168:169]
	v_lshl_add_u64 v[18:19], v[18:19], 0, v[166:167]
	s_mov_b64 s[4:5], 0x58000
	v_lshl_add_u64 v[26:27], v[18:19], 0, s[4:5]
	v_pk_mul_f32 v[16:17], v[16:17], v[68:69]
	v_pk_mul_f32 v[14:15], v[14:15], v[66:67]
	v_pk_mul_f32 v[12:13], v[12:13], v[72:73]
	v_pk_mul_f32 v[10:11], v[10:11], v[70:71]
	s_mov_b64 s[4:5], -1
	s_and_b64 vcc, exec, s[62:63]
	s_cbranch_vccz .LBB0_813
	s_and_b64 vcc, exec, s[42:43]
	s_cbranch_vccnz .LBB0_839
	v_lshl_add_u64 v[18:19], v[26:27], 2, s[38:39]
	global_load_dwordx4 v[22:25], v[18:19], off offset:16
	s_nop 0
	global_load_dwordx4 v[18:21], v[18:19], off
	v_lshl_add_u64 v[28:29], v[26:27], 1, s[46:47]
	s_cbranch_execnz .LBB0_812

.LBB0_813:
	s_mov_b32 s6, 0xf8160000
	s_nop 0
	v_lshlrev_b64 v[18:19], 13, v[168:169]
	s_mov_b32 s7, -1
	v_lshl_add_u64 v[18:19], v[18:19], 0, s[6:7]
	s_and_b64 vcc, exec, s[4:5]
	s_cbranch_vccz .LBB0_815
	v_mul_f32_e32 v20, v153, v154
	v_trunc_f32_e32 v20, v20
	v_cvt_u32_f32_e32 v21, v20
	v_fma_f32 v20, -v20, v152, v153
	v_cmp_ge_f32_e64 s[4:5], |v20|, v152
	s_cmp_lg_u64 s[4:5], 0
	v_readfirstlane_b32 s4, v21
	s_addc_u32 s4, s4, 0
	s_and_b32 s4, s4, 0xff
	s_lshl_b32 s4, s4, 23
	s_add_u32 s4, s76, s4
	s_addc_u32 s5, s77, 0
	v_lshl_add_u64 v[20:21], s[4:5], 0, v[18:19]
	v_lshl_add_u64 v[20:21], v[166:167], 2, v[20:21]
	s_cmp_eq_u32 s100, 2
	s_cbranch_scc1 .Lgo_sp14
	global_store_dwordx4 v[20:21], v[14:17], off
	global_store_dwordx4 v[20:21], v[10:13], off offset:16
.Lgo_sp14:
.LBB0_815:
	v_pk_mul_f32 v[8:9], v[8:9], v[56:57]
	v_pk_mul_f32 v[6:7], v[6:7], v[54:55]
	v_pk_mul_f32 v[4:5], v[4:5], v[52:53]
	v_pk_mul_f32 v[2:3], v[2:3], v[50:51]
	s_mov_b64 s[4:5], -1
	s_and_b64 vcc, exec, s[62:63]
	s_cbranch_vccz .LBB0_821
	s_and_b64 vcc, exec, s[42:43]
	s_cbranch_vccnz .LBB0_840
	v_lshl_add_u64 v[10:11], v[26:27], 2, s[38:39]
	global_load_dwordx4 v[14:17], v[10:11], off offset:528
	s_nop 0
	global_load_dwordx4 v[10:13], v[10:11], off offset:512
	v_or_b32_e32 v26, 0x80, v26
	v_lshl_add_u64 v[20:21], v[26:27], 1, s[46:47]
	s_cbranch_execnz .LBB0_819

.LBB0_821:
	s_and_b64 vcc, exec, s[4:5]
	s_cbranch_vccz .LBB0_820
	v_mul_f32_e32 v10, v153, v154
	v_trunc_f32_e32 v10, v10
	v_cvt_u32_f32_e32 v11, v10
	v_fma_f32 v10, -v10, v152, v153
	v_cmp_ge_f32_e64 s[4:5], |v10|, v152
	s_cmp_lg_u64 s[4:5], 0
	v_readfirstlane_b32 s4, v11
	s_addc_u32 s4, s4, 0
	s_and_b32 s4, s4, 0xff
	s_lshl_b32 s4, s4, 23
	s_add_u32 s4, s76, s4
	s_addc_u32 s5, s77, 0
	v_lshl_add_u64 v[10:11], s[4:5], 0, v[18:19]
	v_lshl_add_u64 v[10:11], v[166:167], 2, v[10:11]
	s_cmp_eq_u32 s100, 1
	s_cbranch_scc1 .Lgo_sp15
	global_store_dwordx4 v[10:11], v[6:9], off offset:512
	global_store_dwordx4 v[10:11], v[2:5], off offset:528
.Lgo_sp15:
	s_and_b64 vcc, exec, s[40:41]
	s_mov_b64 s[4:5], -1
	s_cbranch_vccnz .LBB0_691
.LBB0_823:
	s_andn2_b64 vcc, exec, s[44:45]
	s_cbranch_vccnz .LBB0_690
	s_barrier
	s_branch .LBB0_690

.Lgo_h0_loop:
	s_add_i32 s11, s10, 2
	s_add_u32 s36, s4, 0x100
	s_addc_u32 s37, s5, 0
	s_add_i32 s12, 0, 0x10000
	s_cmp_eq_u32 s89, s10
	s_cselect_b32 s43, s59, s37
	s_cselect_b32 s42, s58, s36
	s_cselect_b32 s21, s61, s91
	s_cselect_b32 s20, s60, s90
	s_add_i32 s10, 0, 0x14000
	v_add_u32_e32 v70, s12, v175
	v_add_u32_e32 v170, s10, v175
	ds_read_b128 v[50:53], v70
	ds_read_b128 v[54:57], v70 offset:1024
	ds_read_b128 v[66:69], v70 offset:2048
	ds_read_b128 v[70:73], v70 offset:3072
	v_lshl_add_u64 v[198:199], s[4:5], 0, v[164:165]
	s_add_i32 m0, s70, 0xc000
	ds_read_b128 v[178:181], v177
	ds_read_b128 v[182:185], v177 offset:1024
	ds_read_b128 v[186:189], v177 offset:2048
	ds_read_b128 v[190:193], v177 offset:3072
	ds_read_b128 v[194:197], v177 offset:4096
	ds_read_b128 v[208:211], v177 offset:5120
	ds_read_b128 v[212:215], v177 offset:6144
	ds_read_b128 v[216:219], v177 offset:7168
	global_load_lds_dwordx4 v[198:199], off
	v_lshl_add_u64 v[198:199], s[4:5], 0, v[162:163]
	s_add_i32 m0, s70, 0xe000
	s_nop 0
	global_load_lds_dwordx4 v[198:199], off
	s_waitcnt vmcnt(8)
	s_waitcnt lgkmcnt(0)
	s_barrier
	s_setprio 1
	s_waitcnt lgkmcnt(0)
	v_mfma_f32_16x16x32_bf16 v[144:147], v[50:53], v[178:181], v[144:147]
	v_mfma_f32_16x16x32_bf16 v[140:143], v[66:69], v[178:181], v[140:143]
	v_mfma_f32_16x16x32_bf16 v[128:131], v[50:53], v[186:189], v[128:131]
	v_mfma_f32_16x16x32_bf16 v[124:127], v[66:69], v[186:189], v[124:127]
	v_mfma_f32_16x16x32_bf16 v[112:115], v[50:53], v[194:197], v[112:115]
	v_mfma_f32_16x16x32_bf16 v[108:111], v[66:69], v[194:197], v[108:111]
	v_mfma_f32_16x16x32_bf16 v[94:97], v[50:53], v[212:215], v[94:97]
	v_mfma_f32_16x16x32_bf16 v[90:93], v[66:69], v[212:215], v[90:93]
	v_mfma_f32_16x16x32_bf16 v[144:147], v[54:57], v[182:185], v[144:147]
	v_mfma_f32_16x16x32_bf16 v[140:143], v[70:73], v[182:185], v[140:143]
	v_mfma_f32_16x16x32_bf16 v[128:131], v[54:57], v[190:193], v[128:131]
	v_mfma_f32_16x16x32_bf16 v[124:127], v[70:73], v[190:193], v[124:127]
	v_mfma_f32_16x16x32_bf16 v[112:115], v[54:57], v[208:211], v[112:115]
	v_mfma_f32_16x16x32_bf16 v[108:111], v[70:73], v[208:211], v[108:111]
	v_mfma_f32_16x16x32_bf16 v[94:97], v[54:57], v[216:219], v[94:97]
	v_mfma_f32_16x16x32_bf16 v[90:93], v[70:73], v[216:219], v[90:93]
	s_setprio 0
	s_setprio 1
	s_setprio 0
	s_barrier
	s_add_i32 s4, s12, s69
	v_lshl_add_u64 v[198:199], s[20:21], 0, v[160:161]
	s_mov_b32 m0, s4
	ds_read_b128 v[178:181], v177 offset:16384
	ds_read_b128 v[182:185], v177 offset:17408
	ds_read_b128 v[186:189], v177 offset:18432
	ds_read_b128 v[190:193], v177 offset:19456
	ds_read_b128 v[194:197], v177 offset:20480
	ds_read_b128 v[208:211], v177 offset:21504
	ds_read_b128 v[212:215], v177 offset:22528
	ds_read_b128 v[216:219], v177 offset:23552
	global_load_lds_dwordx4 v[198:199], off
	s_add_i32 m0, s4, 0x2000
	s_add_u32 s4, s20, 0x4000
	v_lshl_add_u64 v[198:199], s[20:21], 0, v[156:157]
	s_addc_u32 s5, s21, 0
	s_add_i32 s10, s10, s69
	global_load_lds_dwordx4 v[198:199], off
	v_lshl_add_u64 v[198:199], s[4:5], 0, v[160:161]
	s_mov_b32 m0, s10
	v_lshl_add_u64 v[220:221], s[42:43], 0, v[158:159]
	global_load_lds_dwordx4 v[198:199], off
	v_lshl_add_u64 v[198:199], s[4:5], 0, v[156:157]
	s_add_i32 m0, s10, 0x2000
	s_nop 0
	global_load_lds_dwordx4 v[198:199], off
	v_lshl_add_u64 v[198:199], s[42:43], 0, v[98:99]
	s_mov_b32 m0, s70
	s_nop 0
	global_load_lds_dwordx4 v[198:199], off
	s_mov_b32 m0, s71
	s_nop 0
	global_load_lds_dwordx4 v[220:221], off
	s_waitcnt vmcnt(8)
	s_waitcnt lgkmcnt(0)
	s_barrier
	s_setprio 1
	s_waitcnt lgkmcnt(0)
	v_mfma_f32_16x16x32_bf16 v[78:81], v[50:53], v[178:181], v[78:81]
	v_mfma_f32_16x16x32_bf16 v[74:77], v[66:69], v[178:181], v[74:77]
	v_mfma_f32_16x16x32_bf16 v[46:49], v[50:53], v[186:189], v[46:49]
	v_mfma_f32_16x16x32_bf16 v[42:45], v[66:69], v[186:189], v[42:45]
	v_mfma_f32_16x16x32_bf16 v[30:33], v[50:53], v[194:197], v[30:33]
	v_mfma_f32_16x16x32_bf16 v[26:29], v[66:69], v[194:197], v[26:29]
	v_mfma_f32_16x16x32_bf16 v[14:17], v[50:53], v[212:215], v[14:17]
	v_mfma_f32_16x16x32_bf16 v[10:13], v[66:69], v[212:215], v[10:13]
	v_mfma_f32_16x16x32_bf16 v[78:81], v[54:57], v[182:185], v[78:81]
	v_mfma_f32_16x16x32_bf16 v[74:77], v[70:73], v[182:185], v[74:77]
	v_mfma_f32_16x16x32_bf16 v[46:49], v[54:57], v[190:193], v[46:49]
	v_mfma_f32_16x16x32_bf16 v[42:45], v[70:73], v[190:193], v[42:45]
	v_mfma_f32_16x16x32_bf16 v[30:33], v[54:57], v[208:211], v[30:33]
	v_mfma_f32_16x16x32_bf16 v[26:29], v[70:73], v[208:211], v[26:29]
	v_mfma_f32_16x16x32_bf16 v[14:17], v[54:57], v[216:219], v[14:17]
	v_mfma_f32_16x16x32_bf16 v[10:13], v[70:73], v[216:219], v[10:13]
	s_setprio 0
	s_setprio 1
	s_setprio 0
	s_barrier
	s_add_i32 s10, 0, 0x18000
	s_add_i32 s12, 0, 0x1c000
	v_add_u32_e32 v70, s10, v175
	v_add_u32_e32 v170, s12, v175
	ds_read_b128 v[58:61], v70
	ds_read_b128 v[62:65], v70 offset:1024
	ds_read_b128 v[66:69], v70 offset:2048
	ds_read_b128 v[70:73], v70 offset:3072
	s_add_u32 s4, s42, 0xa0000
	s_addc_u32 s5, s43, 0
	s_mov_b32 m0, s72
	v_lshl_add_u64 v[222:223], s[4:5], 0, v[98:99]
	ds_read_b128 v[178:181], v177 offset:32768
	ds_read_b128 v[182:185], v177 offset:33792
	ds_read_b128 v[186:189], v177 offset:34816
	ds_read_b128 v[190:193], v177 offset:35840
	ds_read_b128 v[194:197], v177 offset:36864
	ds_read_b128 v[208:211], v177 offset:37888
	ds_read_b128 v[212:215], v177 offset:38912
	ds_read_b128 v[216:219], v177 offset:39936
	global_load_lds_dwordx4 v[222:223], off
	v_lshl_add_u64 v[222:223], s[4:5], 0, v[158:159]
	s_mov_b32 m0, s73
	s_nop 0
	global_load_lds_dwordx4 v[222:223], off
	s_waitcnt vmcnt(8)
	s_waitcnt lgkmcnt(0)
	s_barrier
	s_setprio 1
	s_waitcnt lgkmcnt(0)
	v_mfma_f32_16x16x32_bf16 v[144:147], v[58:61], v[178:181], v[144:147]
	v_mfma_f32_16x16x32_bf16 v[140:143], v[66:69], v[178:181], v[140:143]
	v_mfma_f32_16x16x32_bf16 v[128:131], v[58:61], v[186:189], v[128:131]
	v_mfma_f32_16x16x32_bf16 v[124:127], v[66:69], v[186:189], v[124:127]
	v_mfma_f32_16x16x32_bf16 v[112:115], v[58:61], v[194:197], v[112:115]
	v_mfma_f32_16x16x32_bf16 v[108:111], v[66:69], v[194:197], v[108:111]
	v_mfma_f32_16x16x32_bf16 v[94:97], v[58:61], v[212:215], v[94:97]
	v_mfma_f32_16x16x32_bf16 v[90:93], v[66:69], v[212:215], v[90:93]
	v_mfma_f32_16x16x32_bf16 v[144:147], v[62:65], v[182:185], v[144:147]
	v_mfma_f32_16x16x32_bf16 v[140:143], v[70:73], v[182:185], v[140:143]
	v_mfma_f32_16x16x32_bf16 v[128:131], v[62:65], v[190:193], v[128:131]
	v_mfma_f32_16x16x32_bf16 v[124:127], v[70:73], v[190:193], v[124:127]
	v_mfma_f32_16x16x32_bf16 v[112:115], v[62:65], v[208:211], v[112:115]
	v_mfma_f32_16x16x32_bf16 v[108:111], v[70:73], v[208:211], v[108:111]
	v_mfma_f32_16x16x32_bf16 v[94:97], v[62:65], v[216:219], v[94:97]
	v_mfma_f32_16x16x32_bf16 v[90:93], v[70:73], v[216:219], v[90:93]
	s_setprio 0
	s_setprio 1
	s_setprio 0
	s_barrier
	s_add_u32 s4, s20, 0x8000
	s_addc_u32 s5, s21, 0
	s_add_i32 s10, s10, s69
	v_lshl_add_u64 v[222:223], s[4:5], 0, v[160:161]
	s_mov_b32 m0, s10
	ds_read_b128 v[178:181], v177 offset:49152
	ds_read_b128 v[182:185], v177 offset:50176
	ds_read_b128 v[186:189], v177 offset:51200
	ds_read_b128 v[190:193], v177 offset:52224
	ds_read_b128 v[194:197], v177 offset:53248
	ds_read_b128 v[208:211], v177 offset:54272
	ds_read_b128 v[212:215], v177 offset:55296
	ds_read_b128 v[216:219], v177 offset:56320
	global_load_lds_dwordx4 v[222:223], off
	s_add_i32 m0, s10, 0x2000
	v_lshl_add_u64 v[222:223], s[4:5], 0, v[156:157]
	s_add_u32 s4, s20, 0xc000
	s_addc_u32 s5, s21, 0
	s_add_i32 s10, s12, s69
	global_load_lds_dwordx4 v[222:223], off
	v_lshl_add_u64 v[222:223], s[4:5], 0, v[160:161]
	s_mov_b32 m0, s10
	v_lshl_add_u64 v[198:199], v[198:199], 0, s[24:25]
	global_load_lds_dwordx4 v[222:223], off
	v_lshl_add_u64 v[222:223], s[4:5], 0, v[156:157]
	s_add_i32 m0, s10, 0x2000
	s_nop 0
	global_load_lds_dwordx4 v[222:223], off
	s_mov_b32 m0, s82
	s_nop 0
	global_load_lds_dwordx4 v[198:199], off
	v_lshl_add_u64 v[198:199], v[220:221], 0, s[24:25]
	s_mov_b32 m0, s83
	s_nop 0
	global_load_lds_dwordx4 v[198:199], off
	s_waitcnt vmcnt(8)
	s_waitcnt lgkmcnt(0)
	s_barrier
	s_setprio 1
	s_waitcnt lgkmcnt(0)
	v_mfma_f32_16x16x32_bf16 v[78:81], v[58:61], v[178:181], v[78:81]
	v_mfma_f32_16x16x32_bf16 v[74:77], v[66:69], v[178:181], v[74:77]
	v_mfma_f32_16x16x32_bf16 v[46:49], v[58:61], v[186:189], v[46:49]
	v_mfma_f32_16x16x32_bf16 v[42:45], v[66:69], v[186:189], v[42:45]
	v_mfma_f32_16x16x32_bf16 v[30:33], v[58:61], v[194:197], v[30:33]
	v_mfma_f32_16x16x32_bf16 v[26:29], v[66:69], v[194:197], v[26:29]
	v_mfma_f32_16x16x32_bf16 v[14:17], v[58:61], v[212:215], v[14:17]
	v_mfma_f32_16x16x32_bf16 v[10:13], v[66:69], v[212:215], v[10:13]
	v_mfma_f32_16x16x32_bf16 v[78:81], v[62:65], v[182:185], v[78:81]
	v_mfma_f32_16x16x32_bf16 v[74:77], v[70:73], v[182:185], v[74:77]
	v_mfma_f32_16x16x32_bf16 v[46:49], v[62:65], v[190:193], v[46:49]
	v_mfma_f32_16x16x32_bf16 v[42:45], v[70:73], v[190:193], v[42:45]
	v_mfma_f32_16x16x32_bf16 v[30:33], v[62:65], v[208:211], v[30:33]
	v_mfma_f32_16x16x32_bf16 v[26:29], v[70:73], v[208:211], v[26:29]
	v_mfma_f32_16x16x32_bf16 v[14:17], v[62:65], v[216:219], v[14:17]
	v_mfma_f32_16x16x32_bf16 v[10:13], v[70:73], v[216:219], v[10:13]
	s_setprio 0
	s_setprio 1
	s_setprio 0
	s_barrier
	s_add_u32 s90, s90, 0x10000
	s_addc_u32 s91, s91, 0
	s_cmp_ge_u32 s11, s7
	s_mov_b64 s[4:5], s[36:37]
	s_mov_b32 s10, s11
	s_cbranch_scc0 .Lgo_h0_loop
	s_branch .Lgo_after_loop
.Lgo_h1_loop:
	s_add_i32 s11, s10, 2
	s_add_u32 s36, s4, 0x100
	s_addc_u32 s37, s5, 0
	s_add_i32 s12, 0, 0x10000
	s_cmp_eq_u32 s89, s10
	s_cselect_b32 s43, s59, s37
	s_cselect_b32 s42, s58, s36
	s_cselect_b32 s21, s61, s91
	s_cselect_b32 s20, s60, s90
	s_add_i32 s10, 0, 0x14000
	v_add_u32_e32 v70, s12, v175
	v_add_u32_e32 v170, s10, v175
	ds_read_b128 v[148:151], v170
	ds_read_b128 v[152:155], v170 offset:1024
	ds_read_b128 v[166:169], v170 offset:2048
	ds_read_b128 v[170:173], v170 offset:3072
	v_lshl_add_u64 v[198:199], s[4:5], 0, v[164:165]
	s_add_i32 m0, s70, 0xc000
	ds_read_b128 v[178:181], v177
	ds_read_b128 v[182:185], v177 offset:1024
	ds_read_b128 v[186:189], v177 offset:2048
	ds_read_b128 v[190:193], v177 offset:3072
	ds_read_b128 v[194:197], v177 offset:4096
	ds_read_b128 v[208:211], v177 offset:5120
	ds_read_b128 v[212:215], v177 offset:6144
	ds_read_b128 v[216:219], v177 offset:7168
	global_load_lds_dwordx4 v[198:199], off
	v_lshl_add_u64 v[198:199], s[4:5], 0, v[162:163]
	s_add_i32 m0, s70, 0xe000
	s_nop 0
	global_load_lds_dwordx4 v[198:199], off
	s_waitcnt vmcnt(8)
	s_waitcnt lgkmcnt(0)
	s_barrier
	s_setprio 1
	s_waitcnt lgkmcnt(0)
	s_setprio 0
	s_setprio 1
	v_mfma_f32_16x16x32_bf16 v[136:139], v[148:151], v[178:181], v[136:139]
	v_mfma_f32_16x16x32_bf16 v[132:135], v[166:169], v[178:181], v[132:135]
	v_mfma_f32_16x16x32_bf16 v[120:123], v[148:151], v[186:189], v[120:123]
	v_mfma_f32_16x16x32_bf16 v[116:119], v[166:169], v[186:189], v[116:119]
	v_mfma_f32_16x16x32_bf16 v[104:107], v[148:151], v[194:197], v[104:107]
	v_mfma_f32_16x16x32_bf16 v[100:103], v[166:169], v[194:197], v[100:103]
	v_mfma_f32_16x16x32_bf16 v[86:89], v[148:151], v[212:215], v[86:89]
	v_mfma_f32_16x16x32_bf16 v[82:85], v[166:169], v[212:215], v[82:85]
	v_mfma_f32_16x16x32_bf16 v[136:139], v[152:155], v[182:185], v[136:139]
	v_mfma_f32_16x16x32_bf16 v[132:135], v[170:173], v[182:185], v[132:135]
	v_mfma_f32_16x16x32_bf16 v[120:123], v[152:155], v[190:193], v[120:123]
	v_mfma_f32_16x16x32_bf16 v[116:119], v[170:173], v[190:193], v[116:119]
	v_mfma_f32_16x16x32_bf16 v[104:107], v[152:155], v[208:211], v[104:107]
	v_mfma_f32_16x16x32_bf16 v[100:103], v[170:173], v[208:211], v[100:103]
	v_mfma_f32_16x16x32_bf16 v[86:89], v[152:155], v[216:219], v[86:89]
	v_mfma_f32_16x16x32_bf16 v[82:85], v[170:173], v[216:219], v[82:85]
	s_setprio 0
	s_barrier
	s_add_i32 s4, s12, s69
	v_lshl_add_u64 v[198:199], s[20:21], 0, v[160:161]
	s_mov_b32 m0, s4
	ds_read_b128 v[178:181], v177 offset:16384
	ds_read_b128 v[182:185], v177 offset:17408
	ds_read_b128 v[186:189], v177 offset:18432
	ds_read_b128 v[190:193], v177 offset:19456
	ds_read_b128 v[194:197], v177 offset:20480
	ds_read_b128 v[208:211], v177 offset:21504
	ds_read_b128 v[212:215], v177 offset:22528
	ds_read_b128 v[216:219], v177 offset:23552
	global_load_lds_dwordx4 v[198:199], off
	s_add_i32 m0, s4, 0x2000
	s_add_u32 s4, s20, 0x4000
	v_lshl_add_u64 v[198:199], s[20:21], 0, v[156:157]
	s_addc_u32 s5, s21, 0
	s_add_i32 s10, s10, s69
	global_load_lds_dwordx4 v[198:199], off
	v_lshl_add_u64 v[198:199], s[4:5], 0, v[160:161]
	s_mov_b32 m0, s10
	v_lshl_add_u64 v[220:221], s[42:43], 0, v[158:159]
	global_load_lds_dwordx4 v[198:199], off
	v_lshl_add_u64 v[198:199], s[4:5], 0, v[156:157]
	s_add_i32 m0, s10, 0x2000
	s_nop 0
	global_load_lds_dwordx4 v[198:199], off
	v_lshl_add_u64 v[198:199], s[42:43], 0, v[98:99]
	s_mov_b32 m0, s70
	s_nop 0
	global_load_lds_dwordx4 v[198:199], off
	s_mov_b32 m0, s71
	s_nop 0
	global_load_lds_dwordx4 v[220:221], off
	s_waitcnt vmcnt(8)
	s_waitcnt lgkmcnt(0)
	s_barrier
	s_setprio 1
	s_waitcnt lgkmcnt(0)
	s_setprio 0
	s_setprio 1
	v_mfma_f32_16x16x32_bf16 v[38:41], v[148:151], v[186:189], v[38:41]
	v_mfma_f32_16x16x32_bf16 v[34:37], v[166:169], v[186:189], v[34:37]
	v_mfma_f32_16x16x32_bf16 v[22:25], v[148:151], v[194:197], v[22:25]
	v_mfma_f32_16x16x32_bf16 v[18:21], v[166:169], v[194:197], v[18:21]
	v_mfma_f32_16x16x32_bf16 v[6:9], v[148:151], v[212:215], v[6:9]
	v_mfma_f32_16x16x32_bf16 v[2:5], v[166:169], v[212:215], v[2:5]
	v_mfma_f32_16x16x32_bf16 v[50:53], v[148:151], v[178:181], v[62:65]
	v_mfma_f32_16x16x32_bf16 v[54:57], v[166:169], v[178:181], v[58:61]
	v_mfma_f32_16x16x32_bf16 v[38:41], v[152:155], v[190:193], v[38:41]
	v_mfma_f32_16x16x32_bf16 v[34:37], v[170:173], v[190:193], v[34:37]
	v_mfma_f32_16x16x32_bf16 v[22:25], v[152:155], v[208:211], v[22:25]
	v_mfma_f32_16x16x32_bf16 v[18:21], v[170:173], v[208:211], v[18:21]
	v_mfma_f32_16x16x32_bf16 v[6:9], v[152:155], v[216:219], v[6:9]
	v_mfma_f32_16x16x32_bf16 v[2:5], v[170:173], v[216:219], v[2:5]
	v_mfma_f32_16x16x32_bf16 v[50:53], v[152:155], v[182:185], v[50:53]
	v_mfma_f32_16x16x32_bf16 v[54:57], v[170:173], v[182:185], v[54:57]
	s_setprio 0
	s_barrier
	s_add_i32 s10, 0, 0x18000
	s_add_i32 s12, 0, 0x1c000
	v_add_u32_e32 v70, s10, v175
	v_add_u32_e32 v170, s12, v175
	ds_read_b128 v[148:151], v170
	ds_read_b128 v[152:155], v170 offset:1024
	ds_read_b128 v[166:169], v170 offset:2048
	ds_read_b128 v[170:173], v170 offset:3072
	s_add_u32 s4, s42, 0xa0000
	s_addc_u32 s5, s43, 0
	s_mov_b32 m0, s72
	v_lshl_add_u64 v[222:223], s[4:5], 0, v[98:99]
	ds_read_b128 v[178:181], v177 offset:32768
	ds_read_b128 v[182:185], v177 offset:33792
	ds_read_b128 v[186:189], v177 offset:34816
	ds_read_b128 v[190:193], v177 offset:35840
	ds_read_b128 v[194:197], v177 offset:36864
	ds_read_b128 v[208:211], v177 offset:37888
	ds_read_b128 v[212:215], v177 offset:38912
	ds_read_b128 v[216:219], v177 offset:39936
	global_load_lds_dwordx4 v[222:223], off
	v_lshl_add_u64 v[222:223], s[4:5], 0, v[158:159]
	s_mov_b32 m0, s73
	s_nop 0
	global_load_lds_dwordx4 v[222:223], off
	s_waitcnt vmcnt(8)
	s_waitcnt lgkmcnt(0)
	s_barrier
	s_setprio 1
	s_waitcnt lgkmcnt(0)
	s_setprio 0
	s_setprio 1
	v_mfma_f32_16x16x32_bf16 v[136:139], v[148:151], v[178:181], v[136:139]
	v_mfma_f32_16x16x32_bf16 v[132:135], v[166:169], v[178:181], v[132:135]
	v_mfma_f32_16x16x32_bf16 v[120:123], v[148:151], v[186:189], v[120:123]
	v_mfma_f32_16x16x32_bf16 v[116:119], v[166:169], v[186:189], v[116:119]
	v_mfma_f32_16x16x32_bf16 v[104:107], v[148:151], v[194:197], v[104:107]
	v_mfma_f32_16x16x32_bf16 v[100:103], v[166:169], v[194:197], v[100:103]
	v_mfma_f32_16x16x32_bf16 v[86:89], v[148:151], v[212:215], v[86:89]
	v_mfma_f32_16x16x32_bf16 v[82:85], v[166:169], v[212:215], v[82:85]
	v_mfma_f32_16x16x32_bf16 v[136:139], v[152:155], v[182:185], v[136:139]
	v_mfma_f32_16x16x32_bf16 v[132:135], v[170:173], v[182:185], v[132:135]
	v_mfma_f32_16x16x32_bf16 v[120:123], v[152:155], v[190:193], v[120:123]
	v_mfma_f32_16x16x32_bf16 v[116:119], v[170:173], v[190:193], v[116:119]
	v_mfma_f32_16x16x32_bf16 v[104:107], v[152:155], v[208:211], v[104:107]
	v_mfma_f32_16x16x32_bf16 v[100:103], v[170:173], v[208:211], v[100:103]
	v_mfma_f32_16x16x32_bf16 v[86:89], v[152:155], v[216:219], v[86:89]
	v_mfma_f32_16x16x32_bf16 v[82:85], v[170:173], v[216:219], v[82:85]
	s_setprio 0
	s_barrier
	s_add_u32 s4, s20, 0x8000
	s_addc_u32 s5, s21, 0
	s_add_i32 s10, s10, s69
	v_lshl_add_u64 v[222:223], s[4:5], 0, v[160:161]
	s_mov_b32 m0, s10
	ds_read_b128 v[178:181], v177 offset:49152
	ds_read_b128 v[182:185], v177 offset:50176
	ds_read_b128 v[186:189], v177 offset:51200
	ds_read_b128 v[190:193], v177 offset:52224
	ds_read_b128 v[194:197], v177 offset:53248
	ds_read_b128 v[208:211], v177 offset:54272
	ds_read_b128 v[212:215], v177 offset:55296
	ds_read_b128 v[216:219], v177 offset:56320
	global_load_lds_dwordx4 v[222:223], off
	s_add_i32 m0, s10, 0x2000
	v_lshl_add_u64 v[222:223], s[4:5], 0, v[156:157]
	s_add_u32 s4, s20, 0xc000
	s_addc_u32 s5, s21, 0
	s_add_i32 s10, s12, s69
	global_load_lds_dwordx4 v[222:223], off
	v_lshl_add_u64 v[222:223], s[4:5], 0, v[160:161]
	s_mov_b32 m0, s10
	v_lshl_add_u64 v[198:199], v[198:199], 0, s[24:25]
	global_load_lds_dwordx4 v[222:223], off
	v_lshl_add_u64 v[222:223], s[4:5], 0, v[156:157]
	s_add_i32 m0, s10, 0x2000
	s_nop 0
	global_load_lds_dwordx4 v[222:223], off
	s_mov_b32 m0, s82
	s_nop 0
	global_load_lds_dwordx4 v[198:199], off
	v_lshl_add_u64 v[198:199], v[220:221], 0, s[24:25]
	s_mov_b32 m0, s83
	s_nop 0
	global_load_lds_dwordx4 v[198:199], off
	s_waitcnt vmcnt(8)
	s_waitcnt lgkmcnt(0)
	s_barrier
	s_setprio 1
	s_waitcnt lgkmcnt(0)
	s_setprio 0
	s_setprio 1
	v_mfma_f32_16x16x32_bf16 v[50:53], v[148:151], v[178:181], v[50:53]
	v_mfma_f32_16x16x32_bf16 v[62:65], v[152:155], v[182:185], v[50:53]
	v_mfma_f32_16x16x32_bf16 v[50:53], v[166:169], v[178:181], v[54:57]
	v_mfma_f32_16x16x32_bf16 v[38:41], v[148:151], v[186:189], v[38:41]
	v_mfma_f32_16x16x32_bf16 v[34:37], v[166:169], v[186:189], v[34:37]
	v_mfma_f32_16x16x32_bf16 v[22:25], v[148:151], v[194:197], v[22:25]
	v_mfma_f32_16x16x32_bf16 v[18:21], v[166:169], v[194:197], v[18:21]
	v_mfma_f32_16x16x32_bf16 v[6:9], v[148:151], v[212:215], v[6:9]
	v_mfma_f32_16x16x32_bf16 v[2:5], v[166:169], v[212:215], v[2:5]
	v_mfma_f32_16x16x32_bf16 v[58:61], v[170:173], v[182:185], v[50:53]
	v_mfma_f32_16x16x32_bf16 v[38:41], v[152:155], v[190:193], v[38:41]
	v_mfma_f32_16x16x32_bf16 v[34:37], v[170:173], v[190:193], v[34:37]
	v_mfma_f32_16x16x32_bf16 v[22:25], v[152:155], v[208:211], v[22:25]
	v_mfma_f32_16x16x32_bf16 v[18:21], v[170:173], v[208:211], v[18:21]
	v_mfma_f32_16x16x32_bf16 v[6:9], v[152:155], v[216:219], v[6:9]
	v_mfma_f32_16x16x32_bf16 v[2:5], v[170:173], v[216:219], v[2:5]
	s_setprio 0
	s_barrier
	s_add_u32 s90, s90, 0x10000
	s_addc_u32 s91, s91, 0
	s_cmp_ge_u32 s11, s7
	s_mov_b64 s[4:5], s[36:37]
	s_mov_b32 s10, s11
	s_cbranch_scc0 .Lgo_h1_loop
	s_branch .Lgo_after_loop

.LBB0_1146:
	s_add_u32 s42, s20, 0x19624000
	s_addc_u32 s43, s21, 0
	s_mul_i32 s10, s80, 0x3c000
	s_mul_hi_u32 s9, s80, 0x3c000
	s_add_u32 s70, s20, s10
	s_addc_u32 s71, s21, s9
	v_lshrrev_b32_e32 v16, 1, v14
	s_add_u32 s72, s20, 0x3bce8000
	v_and_b32_e32 v16, 24, v16
	s_addc_u32 s73, s21, 0
	v_and_b32_e32 v15, 15, v14
	v_lshlrev_b32_e32 v17, 1, v16
	v_lshlrev_b32_e32 v14, 2, v14
	s_lshl_b32 s7, s7, 5
	v_lshl_or_b32 v166, s8, 6, v15
	v_lshl_or_b32 v15, v15, 6, v17
	s_lshl_b32 s8, s8, 13
	v_and_b32_e32 v14, 32, v14
	s_and_b32 s7, s7, 0x60
	v_bitop3_b32 v17, v15, s8, v14 bitop3:0xde
	s_lshl_b32 s8, s7, 7
	v_bitop3_b32 v167, v15, s8, v14 bitop3:0xde
	s_add_u32 s8, s36, 0x8000
	v_mov_b32_e32 v153, v99
	s_addc_u32 s9, s37, 0
	v_mov_b32_e32 v149, v99
	s_add_i32 m0, s66, 0x18000
	v_lshl_add_u64 v[14:15], s[8:9], 0, v[152:153]
	s_waitcnt vmcnt(2)
	s_barrier
	global_load_lds_dwordx4 v[14:15], off
	v_lshl_add_u64 v[14:15], s[8:9], 0, v[148:149]
	s_add_i32 m0, s66, 0x1a000
	s_add_i32 s74, s66, 0x8000
	s_add_i32 s75, s66, 0xa000
	global_load_lds_dwordx4 v[14:15], off
	v_lshl_add_u64 v[2:3], v[2:3], 0, s[24:25]
	s_mov_b32 m0, s74
	s_add_u32 s8, s36, 0xc000
	global_load_lds_dwordx4 v[2:3], off
	v_lshl_add_u64 v[2:3], v[4:5], 0, s[24:25]
	s_mov_b32 m0, s75
	s_addc_u32 s9, s37, 0
	global_load_lds_dwordx4 v[2:3], off
	s_add_i32 m0, s66, 0x1c000
	v_lshl_add_u64 v[2:3], s[8:9], 0, v[152:153]
	global_load_lds_dwordx4 v[2:3], off
	v_lshl_add_u64 v[2:3], s[8:9], 0, v[148:149]
	s_add_i32 m0, s66, 0x1e000
	s_movk_i32 s9, 0x1600
	global_load_lds_dwordx4 v[2:3], off
	v_lshrrev_b32_e32 v3, 1, v11
	v_mul_lo_u32 v2, v10, s9
	s_mov_b32 s8, 0x16000
	s_cmpk_lt_u32 s6, 0x100
	v_or_b32_e32 v168, s7, v16
	v_mad_u64_u32 v[2:3], s[6:7], v3, s8, v[2:3]
	v_or_b32_e32 v2, v2, v12
	v_add_lshl_u32 v2, v2, v13, 1
	v_mov_b32_e32 v3, v99
	s_mov_b64 s[10:11], 0x160080
	v_lshl_add_u64 v[154:155], v[2:3], 0, s[10:11]
	v_lshrrev_b32_e32 v3, 1, v6
	v_mul_lo_u32 v2, v7, s9
	v_mad_u64_u32 v[2:3], s[6:7], v3, s8, v[2:3]
	s_waitcnt vmcnt(6)
	v_or_b32_e32 v2, v2, v8
	v_add_lshl_u32 v2, v2, v9, 1
	v_mov_b32_e32 v3, v99
	v_readlane_b32 s46, v254, 21
	s_cselect_b64 s[44:45], -1, 0
	v_lshl_add_u64 v[156:157], v[2:3], 0, s[10:11]
	s_mov_b32 s76, 0
	v_add_u32_e32 v169, 0, v17
	v_readlane_b32 s8, v254, 20
	v_readlane_b32 s9, v254, 50
	v_readlane_b32 s7, v254, 43
	v_readlane_b32 s6, v254, 17
	v_readlane_b32 s47, v254, 22
	s_barrier
	s_mov_b32 s100, 0
	s_branch .LBB0_1149

.LBB0_1148:
	s_mov_b32 s100, s101
	s_andn2_b64 vcc, exec, s[4:5]
	s_mov_b32 s8, s81
	s_mov_b32 s9, s77
	s_mov_b32 s7, s83
	s_mov_b32 s6, s82
	s_mov_b64 s[36:37], s[54:55]
	s_mov_b64 s[4:5], s[48:49]
	s_cbranch_vccz .LBB0_1234
.LBB0_1149:
	s_add_i32 s76, s76, 1
	s_mul_i32 s10, s76, s52
	s_add_i32 s10, s10, s2
	s_mov_b32 s101, 0
	s_cmp_lg_u32 s52, 0x100
	s_cbranch_scc1 .Lgd_sched_done
	s_cmpk_lt_i32 s10, 0x200
	s_cbranch_scc1 .Lgd_sched_done
	s_and_b32 s101, s10, 1
	s_add_i32 s101, s101, 1
	s_sub_i32 s10, s10, 0x200
	s_lshr_b32 s10, s10, 1
	s_add_i32 s10, s10, 0x200
.Lgd_sched_done:
	s_cmpk_lt_i32 s10, 0x200
	s_cselect_b64 s[40:41], -1, 0
	s_ashr_i32 s11, s10, 31
	s_lshr_b32 s11, s11, 29
	s_add_i32 s11, s10, s11
	s_and_b32 s12, s11, -8
	s_sub_i32 s14, s10, s12
	s_cmpk_gt_i32 s10, 0x1ff
	s_cselect_b64 s[20:21], -1, 0
	s_and_b64 s[12:13], s[20:21], exec
	s_cselect_b32 s55, 0, s14
	s_cmp_gt_i32 s55, -1
	s_mov_b64 s[48:49], -1
	s_cbranch_scc0 .LBB0_1151
	s_lshl_b32 s54, s55, 6
	s_cbranch_execnz .LBB0_1153
	s_branch .LBB0_1152

.LBB0_1161:
	s_xor_b64 s[56:57], s[46:47], -1
	s_add_i32 s84, s6, -2
	s_add_u32 s85, s36, 0x10000
	v_mov_b32_e32 v2, 0
	s_mov_b64 s[46:47], s[20:21]
	s_addc_u32 s86, s37, 0
	s_mov_b32 s10, 0
	v_mov_b32_e32 v3, v2
	v_mov_b32_e32 v4, v2
	v_mov_b32_e32 v5, v2
	v_mov_b32_e32 v6, v2
	v_mov_b32_e32 v7, v2
	v_mov_b32_e32 v8, v2
	v_mov_b32_e32 v9, v2
	v_mov_b32_e32 v18, v2
	v_mov_b32_e32 v19, v2
	v_mov_b32_e32 v20, v2
	v_mov_b32_e32 v21, v2
	v_mov_b32_e32 v22, v2
	v_mov_b32_e32 v23, v2
	v_mov_b32_e32 v24, v2
	v_mov_b32_e32 v25, v2
	v_mov_b32_e32 v34, v2
	v_mov_b32_e32 v35, v2
	v_mov_b32_e32 v36, v2
	v_mov_b32_e32 v37, v2
	v_mov_b32_e32 v38, v2
	v_mov_b32_e32 v39, v2
	v_mov_b32_e32 v40, v2
	v_mov_b32_e32 v41, v2
	v_mov_b32_e32 v50, v2
	v_mov_b32_e32 v51, v2
	v_mov_b32_e32 v52, v2
	v_mov_b32_e32 v53, v2
	v_mov_b32_e32 v54, v2
	v_mov_b32_e32 v55, v2
	v_mov_b32_e32 v56, v2
	v_mov_b32_e32 v57, v2
	v_mov_b32_e32 v10, v2
	v_mov_b32_e32 v11, v2
	v_mov_b32_e32 v12, v2
	v_mov_b32_e32 v13, v2
	v_mov_b32_e32 v14, v2
	v_mov_b32_e32 v15, v2
	v_mov_b32_e32 v16, v2
	v_mov_b32_e32 v17, v2
	v_mov_b32_e32 v26, v2
	v_mov_b32_e32 v27, v2
	v_mov_b32_e32 v28, v2
	v_mov_b32_e32 v29, v2
	v_mov_b32_e32 v30, v2
	v_mov_b32_e32 v31, v2
	v_mov_b32_e32 v32, v2
	v_mov_b32_e32 v33, v2
	v_mov_b32_e32 v42, v2
	v_mov_b32_e32 v43, v2
	v_mov_b32_e32 v44, v2
	v_mov_b32_e32 v45, v2
	v_mov_b32_e32 v46, v2
	v_mov_b32_e32 v47, v2
	v_mov_b32_e32 v48, v2
	v_mov_b32_e32 v49, v2
	v_mov_b32_e32 v58, v2
	v_mov_b32_e32 v59, v2
	v_mov_b32_e32 v60, v2
	v_mov_b32_e32 v61, v2
	v_mov_b32_e32 v62, v2
	v_mov_b32_e32 v63, v2
	v_mov_b32_e32 v64, v2
	v_mov_b32_e32 v65, v2
	v_mov_b32_e32 v74, v2
	v_mov_b32_e32 v75, v2
	v_mov_b32_e32 v76, v2
	v_mov_b32_e32 v77, v2
	v_mov_b32_e32 v78, v2
	v_mov_b32_e32 v79, v2
	v_mov_b32_e32 v80, v2
	v_mov_b32_e32 v81, v2
	v_mov_b32_e32 v100, v2
	v_mov_b32_e32 v101, v2
	v_mov_b32_e32 v102, v2
	v_mov_b32_e32 v103, v2
	v_mov_b32_e32 v104, v2
	v_mov_b32_e32 v105, v2
	v_mov_b32_e32 v106, v2
	v_mov_b32_e32 v107, v2
	v_mov_b32_e32 v116, v2
	v_mov_b32_e32 v117, v2
	v_mov_b32_e32 v118, v2
	v_mov_b32_e32 v119, v2
	v_mov_b32_e32 v120, v2
	v_mov_b32_e32 v121, v2
	v_mov_b32_e32 v122, v2
	v_mov_b32_e32 v123, v2
	v_mov_b32_e32 v132, v2
	v_mov_b32_e32 v133, v2
	v_mov_b32_e32 v134, v2
	v_mov_b32_e32 v135, v2
	v_mov_b32_e32 v136, v2
	v_mov_b32_e32 v137, v2
	v_mov_b32_e32 v138, v2
	v_mov_b32_e32 v139, v2
	v_mov_b32_e32 v90, v2
	v_mov_b32_e32 v91, v2
	v_mov_b32_e32 v92, v2
	v_mov_b32_e32 v93, v2
	v_mov_b32_e32 v94, v2
	v_mov_b32_e32 v95, v2
	v_mov_b32_e32 v96, v2
	v_mov_b32_e32 v97, v2
	v_mov_b32_e32 v108, v2
	v_mov_b32_e32 v109, v2
	v_mov_b32_e32 v110, v2
	v_mov_b32_e32 v111, v2
	v_mov_b32_e32 v112, v2
	v_mov_b32_e32 v113, v2
	v_mov_b32_e32 v114, v2
	v_mov_b32_e32 v115, v2
	v_mov_b32_e32 v124, v2
	v_mov_b32_e32 v125, v2
	v_mov_b32_e32 v126, v2
	v_mov_b32_e32 v127, v2
	v_mov_b32_e32 v128, v2
	v_mov_b32_e32 v129, v2
	v_mov_b32_e32 v130, v2
	v_mov_b32_e32 v131, v2
	v_mov_b32_e32 v140, v2
	v_mov_b32_e32 v141, v2
	v_mov_b32_e32 v142, v2
	v_mov_b32_e32 v143, v2
	v_mov_b32_e32 v144, v2
	v_mov_b32_e32 v145, v2
	v_mov_b32_e32 v146, v2
	v_mov_b32_e32 v147, v2
	s_cmp_eq_u32 s100, 1
	s_cbranch_scc1 .Lgd_h0_loop
	s_cmp_eq_u32 s100, 2
	s_cbranch_scc1 .Lgd_h1_loop

.Lgd_after_loop:
	s_and_b64 vcc, exec, s[44:45]
	s_cbranch_vccz .LBB0_1165
	s_barrier

.LBB0_1167:
	s_lshl_b64 s[4:5], s[4:5], 2
	v_lshl_or_b32 v158, s9, 8, v168
	s_add_u32 s4, s70, s4
	s_addc_u32 s5, s71, s5
	v_ashrrev_i32_e32 v159, 31, v158
	v_lshl_add_u64 v[66:67], v[158:159], 2, s[4:5]
	s_mov_b64 s[4:5], 0x194ea000
	v_lshl_add_u64 v[68:69], v[66:67], 0, s[4:5]
	s_mov_b32 s4, 0x194ea000
	v_add_co_u32_e32 v66, vcc, s4, v66
	global_load_dwordx4 v[82:85], v[68:69], off offset:16
	s_nop 0
	v_addc_co_u32_e32 v67, vcc, 0, v67, vcc
	global_load_dwordx4 v[86:89], v[66:67], off
	global_load_dwordx4 v[70:73], v[68:69], off offset:512
	s_nop 0
	global_load_dwordx4 v[66:69], v[68:69], off offset:528
	v_lshl_add_u32 v160, s8, 8, v166
	v_ashrrev_i32_e32 v161, 31, v160
	v_lshlrev_b64 v[162:163], 11, v[160:161]
	v_lshl_add_u64 v[162:163], v[162:163], 0, v[158:159]
	s_mov_b64 s[4:5], -1
	s_and_b64 vcc, exec, s[56:57]
	v_lshl_add_u64 v[162:163], v[162:163], 1, s[42:43]
	s_cbranch_vccz .Lepi_down_orig
	v_lshl_add_u32 v162, v160, 11, v158
	v_lshlrev_b32_e32 v162, 1, v162
	s_mov_b64 s[8:9], s[42:43]
	global_load_dwordx4 v[178:181], v162, s[8:9]
	global_load_dwordx4 v[182:185], v162, s[8:9] offset:256
	s_add_u32 s8, s8, 0x10000
	s_addc_u32 s9, s9, 0
	global_load_dwordx4 v[186:189], v162, s[8:9]
	global_load_dwordx4 v[190:193], v162, s[8:9] offset:256
	s_add_u32 s8, s8, 0x10000
	s_addc_u32 s9, s9, 0
	global_load_dwordx4 v[194:197], v162, s[8:9]
	global_load_dwordx4 v[208:211], v162, s[8:9] offset:256
	s_add_u32 s8, s8, 0x10000
	s_addc_u32 s9, s9, 0
	global_load_dwordx4 v[212:215], v162, s[8:9]
	global_load_dwordx4 v[216:219], v162, s[8:9] offset:256
	s_mov_b64 s[8:9], s[42:43]
	s_add_u32 s4, s42, 0x80000
	s_addc_u32 s5, s43, 0
	s_waitcnt vmcnt(7)
	v_pk_mul_f32 v[144:145], v[144:145], v[86:87]
	v_pk_mul_f32 v[146:147], v[146:147], v[88:89]
	v_pk_mul_f32 v[140:141], v[140:141], v[82:83]
	v_pk_mul_f32 v[142:143], v[142:143], v[84:85]
	v_lshlrev_b32_e32 v158, 16, v178
	v_and_b32_e32 v159, 0xffff0000, v178
	v_lshlrev_b32_e32 v160, 16, v179
	v_and_b32_e32 v161, 0xffff0000, v179
	v_pk_add_f32 v[144:145], v[144:145], v[158:159]
	v_pk_add_f32 v[146:147], v[146:147], v[160:161]
	v_lshlrev_b32_e32 v158, 16, v180
	v_and_b32_e32 v159, 0xffff0000, v180
	v_lshlrev_b32_e32 v160, 16, v181
	v_and_b32_e32 v161, 0xffff0000, v181
	v_pk_add_f32 v[140:141], v[140:141], v[158:159]
	v_pk_add_f32 v[142:143], v[142:143], v[160:161]
	v_cvt_pk_bf16_f32 v178, v144, v145
	v_cvt_pk_bf16_f32 v179, v146, v147
	v_cvt_pk_bf16_f32 v180, v140, v141
	v_cvt_pk_bf16_f32 v181, v142, v143
	global_store_dwordx4 v162, v[178:181], s[8:9]
	s_nop 0
	global_load_dwordx4 v[178:181], v162, s[4:5]
	s_waitcnt vmcnt(8)
	v_pk_mul_f32 v[136:137], v[136:137], v[70:71]
	v_pk_mul_f32 v[138:139], v[138:139], v[72:73]
	v_pk_mul_f32 v[132:133], v[132:133], v[66:67]
	v_pk_mul_f32 v[134:135], v[134:135], v[68:69]
	v_lshlrev_b32_e32 v158, 16, v182
	v_and_b32_e32 v159, 0xffff0000, v182
	v_lshlrev_b32_e32 v160, 16, v183
	v_and_b32_e32 v161, 0xffff0000, v183
	v_pk_add_f32 v[136:137], v[136:137], v[158:159]
	v_pk_add_f32 v[138:139], v[138:139], v[160:161]
	v_lshlrev_b32_e32 v158, 16, v184
	v_and_b32_e32 v159, 0xffff0000, v184
	v_lshlrev_b32_e32 v160, 16, v185
	v_and_b32_e32 v161, 0xffff0000, v185
	v_pk_add_f32 v[132:133], v[132:133], v[158:159]
	v_pk_add_f32 v[134:135], v[134:135], v[160:161]
	v_cvt_pk_bf16_f32 v182, v136, v137
	v_cvt_pk_bf16_f32 v183, v138, v139
	v_cvt_pk_bf16_f32 v184, v132, v133
	v_cvt_pk_bf16_f32 v185, v134, v135
	global_store_dwordx4 v162, v[182:185], s[8:9] offset:256
	s_add_u32 s8, s8, 0x10000
	s_addc_u32 s9, s9, 0
	global_load_dwordx4 v[182:185], v162, s[4:5] offset:256
	s_add_u32 s4, s4, 0x10000
	s_addc_u32 s5, s5, 0
	s_waitcnt vmcnt(9)
	v_pk_mul_f32 v[128:129], v[128:129], v[86:87]
	v_pk_mul_f32 v[130:131], v[130:131], v[88:89]
	v_pk_mul_f32 v[124:125], v[124:125], v[82:83]
	v_pk_mul_f32 v[126:127], v[126:127], v[84:85]
	v_lshlrev_b32_e32 v158, 16, v186
	v_and_b32_e32 v159, 0xffff0000, v186
	v_lshlrev_b32_e32 v160, 16, v187
	v_and_b32_e32 v161, 0xffff0000, v187
	v_pk_add_f32 v[128:129], v[128:129], v[158:159]
	v_pk_add_f32 v[130:131], v[130:131], v[160:161]
	v_lshlrev_b32_e32 v158, 16, v188
	v_and_b32_e32 v159, 0xffff0000, v188
	v_lshlrev_b32_e32 v160, 16, v189
	v_and_b32_e32 v161, 0xffff0000, v189
	v_pk_add_f32 v[124:125], v[124:125], v[158:159]
	v_pk_add_f32 v[126:127], v[126:127], v[160:161]
	v_cvt_pk_bf16_f32 v186, v128, v129
	v_cvt_pk_bf16_f32 v187, v130, v131
	v_cvt_pk_bf16_f32 v188, v124, v125
	v_cvt_pk_bf16_f32 v189, v126, v127
	global_store_dwordx4 v162, v[186:189], s[8:9]
	s_nop 0
	global_load_dwordx4 v[186:189], v162, s[4:5]
	s_waitcnt vmcnt(10)
	v_pk_mul_f32 v[120:121], v[120:121], v[70:71]
	v_pk_mul_f32 v[122:123], v[122:123], v[72:73]
	v_pk_mul_f32 v[116:117], v[116:117], v[66:67]
	v_pk_mul_f32 v[118:119], v[118:119], v[68:69]
	v_lshlrev_b32_e32 v158, 16, v190
	v_and_b32_e32 v159, 0xffff0000, v190
	v_lshlrev_b32_e32 v160, 16, v191
	v_and_b32_e32 v161, 0xffff0000, v191
	v_pk_add_f32 v[120:121], v[120:121], v[158:159]
	v_pk_add_f32 v[122:123], v[122:123], v[160:161]
	v_lshlrev_b32_e32 v158, 16, v192
	v_and_b32_e32 v159, 0xffff0000, v192
	v_lshlrev_b32_e32 v160, 16, v193
	v_and_b32_e32 v161, 0xffff0000, v193
	v_pk_add_f32 v[116:117], v[116:117], v[158:159]
	v_pk_add_f32 v[118:119], v[118:119], v[160:161]
	v_cvt_pk_bf16_f32 v190, v120, v121
	v_cvt_pk_bf16_f32 v191, v122, v123
	v_cvt_pk_bf16_f32 v192, v116, v117
	v_cvt_pk_bf16_f32 v193, v118, v119
	global_store_dwordx4 v162, v[190:193], s[8:9] offset:256
	s_add_u32 s8, s8, 0x10000
	s_addc_u32 s9, s9, 0
	global_load_dwordx4 v[190:193], v162, s[4:5] offset:256
	s_add_u32 s4, s4, 0x10000
	s_addc_u32 s5, s5, 0
	s_waitcnt vmcnt(11)
	v_pk_mul_f32 v[112:113], v[112:113], v[86:87]
	v_pk_mul_f32 v[114:115], v[114:115], v[88:89]
	v_pk_mul_f32 v[108:109], v[108:109], v[82:83]
	v_pk_mul_f32 v[110:111], v[110:111], v[84:85]
	v_lshlrev_b32_e32 v158, 16, v194
	v_and_b32_e32 v159, 0xffff0000, v194
	v_lshlrev_b32_e32 v160, 16, v195
	v_and_b32_e32 v161, 0xffff0000, v195
	v_pk_add_f32 v[112:113], v[112:113], v[158:159]
	v_pk_add_f32 v[114:115], v[114:115], v[160:161]
	v_lshlrev_b32_e32 v158, 16, v196
	v_and_b32_e32 v159, 0xffff0000, v196
	v_lshlrev_b32_e32 v160, 16, v197
	v_and_b32_e32 v161, 0xffff0000, v197
	v_pk_add_f32 v[108:109], v[108:109], v[158:159]
	v_pk_add_f32 v[110:111], v[110:111], v[160:161]
	v_cvt_pk_bf16_f32 v194, v112, v113
	v_cvt_pk_bf16_f32 v195, v114, v115
	v_cvt_pk_bf16_f32 v196, v108, v109
	v_cvt_pk_bf16_f32 v197, v110, v111
	global_store_dwordx4 v162, v[194:197], s[8:9]
	s_nop 0
	global_load_dwordx4 v[194:197], v162, s[4:5]
	s_waitcnt vmcnt(12)
	v_pk_mul_f32 v[104:105], v[104:105], v[70:71]
	v_pk_mul_f32 v[106:107], v[106:107], v[72:73]
	v_pk_mul_f32 v[100:101], v[100:101], v[66:67]
	v_pk_mul_f32 v[102:103], v[102:103], v[68:69]
	v_lshlrev_b32_e32 v158, 16, v208
	v_and_b32_e32 v159, 0xffff0000, v208
	v_lshlrev_b32_e32 v160, 16, v209
	v_and_b32_e32 v161, 0xffff0000, v209
	v_pk_add_f32 v[104:105], v[104:105], v[158:159]
	v_pk_add_f32 v[106:107], v[106:107], v[160:161]
	v_lshlrev_b32_e32 v158, 16, v210
	v_and_b32_e32 v159, 0xffff0000, v210
	v_lshlrev_b32_e32 v160, 16, v211
	v_and_b32_e32 v161, 0xffff0000, v211
	v_pk_add_f32 v[100:101], v[100:101], v[158:159]
	v_pk_add_f32 v[102:103], v[102:103], v[160:161]
	v_cvt_pk_bf16_f32 v208, v104, v105
	v_cvt_pk_bf16_f32 v209, v106, v107
	v_cvt_pk_bf16_f32 v210, v100, v101
	v_cvt_pk_bf16_f32 v211, v102, v103
	global_store_dwordx4 v162, v[208:211], s[8:9] offset:256
	s_add_u32 s8, s8, 0x10000
	s_addc_u32 s9, s9, 0
	global_load_dwordx4 v[208:211], v162, s[4:5] offset:256
	s_add_u32 s4, s4, 0x10000
	s_addc_u32 s5, s5, 0
	s_waitcnt vmcnt(13)
	v_pk_mul_f32 v[94:95], v[94:95], v[86:87]
	v_pk_mul_f32 v[96:97], v[96:97], v[88:89]
	v_pk_mul_f32 v[90:91], v[90:91], v[82:83]
	v_pk_mul_f32 v[92:93], v[92:93], v[84:85]
	v_lshlrev_b32_e32 v158, 16, v212
	v_and_b32_e32 v159, 0xffff0000, v212
	v_lshlrev_b32_e32 v160, 16, v213
	v_and_b32_e32 v161, 0xffff0000, v213
	v_pk_add_f32 v[94:95], v[94:95], v[158:159]
	v_pk_add_f32 v[96:97], v[96:97], v[160:161]
	v_lshlrev_b32_e32 v158, 16, v214
	v_and_b32_e32 v159, 0xffff0000, v214
	v_lshlrev_b32_e32 v160, 16, v215
	v_and_b32_e32 v161, 0xffff0000, v215
	v_pk_add_f32 v[90:91], v[90:91], v[158:159]
	v_pk_add_f32 v[92:93], v[92:93], v[160:161]
	v_cvt_pk_bf16_f32 v212, v94, v95
	v_cvt_pk_bf16_f32 v213, v96, v97
	v_cvt_pk_bf16_f32 v214, v90, v91
	v_cvt_pk_bf16_f32 v215, v92, v93
	global_store_dwordx4 v162, v[212:215], s[8:9]
	s_nop 0
	global_load_dwordx4 v[212:215], v162, s[4:5]
	s_waitcnt vmcnt(14)
	v_pk_mul_f32 v[78:79], v[78:79], v[70:71]
	v_pk_mul_f32 v[80:81], v[80:81], v[72:73]
	v_pk_mul_f32 v[74:75], v[74:75], v[66:67]
	v_pk_mul_f32 v[76:77], v[76:77], v[68:69]
	v_lshlrev_b32_e32 v158, 16, v216
	v_and_b32_e32 v159, 0xffff0000, v216
	v_lshlrev_b32_e32 v160, 16, v217
	v_and_b32_e32 v161, 0xffff0000, v217
	v_pk_add_f32 v[78:79], v[78:79], v[158:159]
	v_pk_add_f32 v[80:81], v[80:81], v[160:161]
	v_lshlrev_b32_e32 v158, 16, v218
	v_and_b32_e32 v159, 0xffff0000, v218
	v_lshlrev_b32_e32 v160, 16, v219
	v_and_b32_e32 v161, 0xffff0000, v219
	v_pk_add_f32 v[74:75], v[74:75], v[158:159]
	v_pk_add_f32 v[76:77], v[76:77], v[160:161]
	v_cvt_pk_bf16_f32 v216, v78, v79
	v_cvt_pk_bf16_f32 v217, v80, v81
	v_cvt_pk_bf16_f32 v218, v74, v75
	v_cvt_pk_bf16_f32 v219, v76, v77
	global_store_dwordx4 v162, v[216:219], s[8:9] offset:256
	s_add_u32 s8, s8, 0x10000
	s_addc_u32 s9, s9, 0
	global_load_dwordx4 v[216:219], v162, s[4:5] offset:256
	s_add_u32 s4, s42, 0x80000
	s_addc_u32 s5, s43, 0
	s_waitcnt vmcnt(14)
	v_pk_mul_f32 v[62:63], v[62:63], v[86:87]
	v_pk_mul_f32 v[64:65], v[64:65], v[88:89]
	v_pk_mul_f32 v[58:59], v[58:59], v[82:83]
	v_pk_mul_f32 v[60:61], v[60:61], v[84:85]
	v_lshlrev_b32_e32 v158, 16, v178
	v_and_b32_e32 v159, 0xffff0000, v178
	v_lshlrev_b32_e32 v160, 16, v179
	v_and_b32_e32 v161, 0xffff0000, v179
	v_pk_add_f32 v[62:63], v[62:63], v[158:159]
	v_pk_add_f32 v[64:65], v[64:65], v[160:161]
	v_lshlrev_b32_e32 v158, 16, v180
	v_and_b32_e32 v159, 0xffff0000, v180
	v_lshlrev_b32_e32 v160, 16, v181
	v_and_b32_e32 v161, 0xffff0000, v181
	v_pk_add_f32 v[58:59], v[58:59], v[158:159]
	v_pk_add_f32 v[60:61], v[60:61], v[160:161]
	v_cvt_pk_bf16_f32 v178, v62, v63
	v_cvt_pk_bf16_f32 v179, v64, v65
	v_cvt_pk_bf16_f32 v180, v58, v59
	v_cvt_pk_bf16_f32 v181, v60, v61
	global_store_dwordx4 v162, v[178:181], s[4:5]
	s_waitcnt vmcnt(13)
	v_pk_mul_f32 v[54:55], v[54:55], v[70:71]
	v_pk_mul_f32 v[56:57], v[56:57], v[72:73]
	v_pk_mul_f32 v[50:51], v[50:51], v[66:67]
	v_pk_mul_f32 v[52:53], v[52:53], v[68:69]
	v_lshlrev_b32_e32 v158, 16, v182
	v_and_b32_e32 v159, 0xffff0000, v182
	v_lshlrev_b32_e32 v160, 16, v183
	v_and_b32_e32 v161, 0xffff0000, v183
	v_pk_add_f32 v[54:55], v[54:55], v[158:159]
	v_pk_add_f32 v[56:57], v[56:57], v[160:161]
	v_lshlrev_b32_e32 v158, 16, v184
	v_and_b32_e32 v159, 0xffff0000, v184
	v_lshlrev_b32_e32 v160, 16, v185
	v_and_b32_e32 v161, 0xffff0000, v185
	v_pk_add_f32 v[50:51], v[50:51], v[158:159]
	v_pk_add_f32 v[52:53], v[52:53], v[160:161]
	v_cvt_pk_bf16_f32 v182, v54, v55
	v_cvt_pk_bf16_f32 v183, v56, v57
	v_cvt_pk_bf16_f32 v184, v50, v51
	v_cvt_pk_bf16_f32 v185, v52, v53
	global_store_dwordx4 v162, v[182:185], s[4:5] offset:256
	s_add_u32 s4, s4, 0x10000
	s_addc_u32 s5, s5, 0
	s_waitcnt vmcnt(12)
	v_pk_mul_f32 v[46:47], v[46:47], v[86:87]
	v_pk_mul_f32 v[48:49], v[48:49], v[88:89]
	v_pk_mul_f32 v[42:43], v[42:43], v[82:83]
	v_pk_mul_f32 v[44:45], v[44:45], v[84:85]
	v_lshlrev_b32_e32 v158, 16, v186
	v_and_b32_e32 v159, 0xffff0000, v186
	v_lshlrev_b32_e32 v160, 16, v187
	v_and_b32_e32 v161, 0xffff0000, v187
	v_pk_add_f32 v[46:47], v[46:47], v[158:159]
	v_pk_add_f32 v[48:49], v[48:49], v[160:161]
	v_lshlrev_b32_e32 v158, 16, v188
	v_and_b32_e32 v159, 0xffff0000, v188
	v_lshlrev_b32_e32 v160, 16, v189
	v_and_b32_e32 v161, 0xffff0000, v189
	v_pk_add_f32 v[42:43], v[42:43], v[158:159]
	v_pk_add_f32 v[44:45], v[44:45], v[160:161]
	v_cvt_pk_bf16_f32 v186, v46, v47
	v_cvt_pk_bf16_f32 v187, v48, v49
	v_cvt_pk_bf16_f32 v188, v42, v43
	v_cvt_pk_bf16_f32 v189, v44, v45
	global_store_dwordx4 v162, v[186:189], s[4:5]
	s_waitcnt vmcnt(11)
	v_pk_mul_f32 v[38:39], v[38:39], v[70:71]
	v_pk_mul_f32 v[40:41], v[40:41], v[72:73]
	v_pk_mul_f32 v[34:35], v[34:35], v[66:67]
	v_pk_mul_f32 v[36:37], v[36:37], v[68:69]
	v_lshlrev_b32_e32 v158, 16, v190
	v_and_b32_e32 v159, 0xffff0000, v190
	v_lshlrev_b32_e32 v160, 16, v191
	v_and_b32_e32 v161, 0xffff0000, v191
	v_pk_add_f32 v[38:39], v[38:39], v[158:159]
	v_pk_add_f32 v[40:41], v[40:41], v[160:161]
	v_lshlrev_b32_e32 v158, 16, v192
	v_and_b32_e32 v159, 0xffff0000, v192
	v_lshlrev_b32_e32 v160, 16, v193
	v_and_b32_e32 v161, 0xffff0000, v193
	v_pk_add_f32 v[34:35], v[34:35], v[158:159]
	v_pk_add_f32 v[36:37], v[36:37], v[160:161]
	v_cvt_pk_bf16_f32 v190, v38, v39
	v_cvt_pk_bf16_f32 v191, v40, v41
	v_cvt_pk_bf16_f32 v192, v34, v35
	v_cvt_pk_bf16_f32 v193, v36, v37
	global_store_dwordx4 v162, v[190:193], s[4:5] offset:256
	s_add_u32 s4, s4, 0x10000
	s_addc_u32 s5, s5, 0
	s_waitcnt vmcnt(10)
	v_pk_mul_f32 v[30:31], v[30:31], v[86:87]
	v_pk_mul_f32 v[32:33], v[32:33], v[88:89]
	v_pk_mul_f32 v[26:27], v[26:27], v[82:83]
	v_pk_mul_f32 v[28:29], v[28:29], v[84:85]
	v_lshlrev_b32_e32 v158, 16, v194
	v_and_b32_e32 v159, 0xffff0000, v194
	v_lshlrev_b32_e32 v160, 16, v195
	v_and_b32_e32 v161, 0xffff0000, v195
	v_pk_add_f32 v[30:31], v[30:31], v[158:159]
	v_pk_add_f32 v[32:33], v[32:33], v[160:161]
	v_lshlrev_b32_e32 v158, 16, v196
	v_and_b32_e32 v159, 0xffff0000, v196
	v_lshlrev_b32_e32 v160, 16, v197
	v_and_b32_e32 v161, 0xffff0000, v197
	v_pk_add_f32 v[26:27], v[26:27], v[158:159]
	v_pk_add_f32 v[28:29], v[28:29], v[160:161]
	v_cvt_pk_bf16_f32 v194, v30, v31
	v_cvt_pk_bf16_f32 v195, v32, v33
	v_cvt_pk_bf16_f32 v196, v26, v27
	v_cvt_pk_bf16_f32 v197, v28, v29
	global_store_dwordx4 v162, v[194:197], s[4:5]
	s_waitcnt vmcnt(9)
	v_pk_mul_f32 v[22:23], v[22:23], v[70:71]
	v_pk_mul_f32 v[24:25], v[24:25], v[72:73]
	v_pk_mul_f32 v[18:19], v[18:19], v[66:67]
	v_pk_mul_f32 v[20:21], v[20:21], v[68:69]
	v_lshlrev_b32_e32 v158, 16, v208
	v_and_b32_e32 v159, 0xffff0000, v208
	v_lshlrev_b32_e32 v160, 16, v209
	v_and_b32_e32 v161, 0xffff0000, v209
	v_pk_add_f32 v[22:23], v[22:23], v[158:159]
	v_pk_add_f32 v[24:25], v[24:25], v[160:161]
	v_lshlrev_b32_e32 v158, 16, v210
	v_and_b32_e32 v159, 0xffff0000, v210
	v_lshlrev_b32_e32 v160, 16, v211
	v_and_b32_e32 v161, 0xffff0000, v211
	v_pk_add_f32 v[18:19], v[18:19], v[158:159]
	v_pk_add_f32 v[20:21], v[20:21], v[160:161]
	v_cvt_pk_bf16_f32 v208, v22, v23
	v_cvt_pk_bf16_f32 v209, v24, v25
	v_cvt_pk_bf16_f32 v210, v18, v19
	v_cvt_pk_bf16_f32 v211, v20, v21
	global_store_dwordx4 v162, v[208:211], s[4:5] offset:256
	s_add_u32 s4, s4, 0x10000
	s_addc_u32 s5, s5, 0
	s_waitcnt vmcnt(8)
	v_pk_mul_f32 v[14:15], v[14:15], v[86:87]
	v_pk_mul_f32 v[16:17], v[16:17], v[88:89]
	v_pk_mul_f32 v[10:11], v[10:11], v[82:83]
	v_pk_mul_f32 v[12:13], v[12:13], v[84:85]
	v_lshlrev_b32_e32 v158, 16, v212
	v_and_b32_e32 v159, 0xffff0000, v212
	v_lshlrev_b32_e32 v160, 16, v213
	v_and_b32_e32 v161, 0xffff0000, v213
	v_pk_add_f32 v[14:15], v[14:15], v[158:159]
	v_pk_add_f32 v[16:17], v[16:17], v[160:161]
	v_lshlrev_b32_e32 v158, 16, v214
	v_and_b32_e32 v159, 0xffff0000, v214
	v_lshlrev_b32_e32 v160, 16, v215
	v_and_b32_e32 v161, 0xffff0000, v215
	v_pk_add_f32 v[10:11], v[10:11], v[158:159]
	v_pk_add_f32 v[12:13], v[12:13], v[160:161]
	v_cvt_pk_bf16_f32 v212, v14, v15
	v_cvt_pk_bf16_f32 v213, v16, v17
	v_cvt_pk_bf16_f32 v214, v10, v11
	v_cvt_pk_bf16_f32 v215, v12, v13
	global_store_dwordx4 v162, v[212:215], s[4:5]
	s_waitcnt vmcnt(7)
	v_pk_mul_f32 v[6:7], v[6:7], v[70:71]
	v_pk_mul_f32 v[8:9], v[8:9], v[72:73]
	v_pk_mul_f32 v[2:3], v[2:3], v[66:67]
	v_pk_mul_f32 v[4:5], v[4:5], v[68:69]
	v_lshlrev_b32_e32 v158, 16, v216
	v_and_b32_e32 v159, 0xffff0000, v216
	v_lshlrev_b32_e32 v160, 16, v217
	v_and_b32_e32 v161, 0xffff0000, v217
	v_pk_add_f32 v[6:7], v[6:7], v[158:159]
	v_pk_add_f32 v[8:9], v[8:9], v[160:161]
	v_lshlrev_b32_e32 v158, 16, v218
	v_and_b32_e32 v159, 0xffff0000, v218
	v_lshlrev_b32_e32 v160, 16, v219
	v_and_b32_e32 v161, 0xffff0000, v219
	v_pk_add_f32 v[2:3], v[2:3], v[158:159]
	v_pk_add_f32 v[4:5], v[4:5], v[160:161]
	v_cvt_pk_bf16_f32 v216, v6, v7
	v_cvt_pk_bf16_f32 v217, v8, v9
	v_cvt_pk_bf16_f32 v218, v2, v3
	v_cvt_pk_bf16_f32 v219, v4, v5
	global_store_dwordx4 v162, v[216:219], s[4:5] offset:256
	s_branch .LBB0_1229

.LBB0_1169:
	s_nop 1
	v_cvt_f32_u32_e32 v171, s6
	v_cvt_f32_u32_e32 v170, s7
	s_brev_b32 s8, 31
	v_lshlrev_b64 v[164:165], 13, v[160:161]
	v_rcp_iflag_f32_e32 v172, v171
	s_mov_b32 s9, -1
	v_lshl_add_u64 v[164:165], v[164:165], 0, s[8:9]
	s_andn2_b64 vcc, exec, s[4:5]
	s_cbranch_vccnz .LBB0_1171
	v_mul_f32_e32 v173, v170, v172
	v_trunc_f32_e32 v173, v173
	v_cvt_u32_f32_e32 v174, v173
	v_fma_f32 v173, -v173, v171, v170
	v_cmp_ge_f32_e64 s[4:5], |v173|, v171
	s_cmp_lg_u64 s[4:5], 0
	v_readfirstlane_b32 s4, v174
	s_addc_u32 s4, s4, 0
	s_and_b32 s4, s4, 0xff
	s_lshl_b32 s4, s4, 23
	s_add_u32 s4, s72, s4
	s_addc_u32 s5, s73, 0
	v_lshl_add_u64 v[174:175], s[4:5], 0, v[164:165]
	v_lshl_add_u64 v[174:175], v[158:159], 2, v[174:175]
	s_cmp_eq_u32 s100, 2
	s_cbranch_scc1 .Lgd_sp0
	global_store_dwordx4 v[174:175], v[144:147], off
	global_store_dwordx4 v[174:175], v[140:143], off offset:16
.Lgd_sp0:
.LBB0_1171:
	v_pk_mul_f32 v[138:139], v[138:139], v[72:73]
	v_pk_mul_f32 v[136:137], v[136:137], v[70:71]
	v_pk_mul_f32 v[134:135], v[134:135], v[68:69]
	v_pk_mul_f32 v[132:133], v[132:133], v[66:67]
	s_mov_b64 s[4:5], -1
	s_and_b64 vcc, exec, s[56:57]
	s_cbranch_vccz .LBB0_1173
	global_load_dwordx4 v[140:143], v[162:163], off offset:256
	s_mov_b64 s[4:5], 0
	s_waitcnt vmcnt(0)
	v_lshlrev_b32_e32 v144, 16, v140
	v_and_b32_e32 v145, 0xffff0000, v140
	v_lshlrev_b32_e32 v140, 16, v141
	v_and_b32_e32 v141, 0xffff0000, v141
	v_lshlrev_b32_e32 v146, 16, v142
	v_and_b32_e32 v147, 0xffff0000, v142
	v_lshlrev_b32_e32 v142, 16, v143
	v_and_b32_e32 v143, 0xffff0000, v143
	v_pk_add_f32 v[174:175], v[138:139], v[140:141]
	v_pk_add_f32 v[140:141], v[136:137], v[144:145]
	v_pk_add_f32 v[144:145], v[134:135], v[142:143]
	v_pk_add_f32 v[142:143], v[132:133], v[146:147]
	v_cvt_pk_bf16_f32 v140, v140, v141
	v_cvt_pk_bf16_f32 v141, v174, v175
	s_nop 0
	v_cvt_pk_bf16_f32 v142, v142, v143
	v_cvt_pk_bf16_f32 v143, v144, v145
	global_store_dwordx4 v[162:163], v[140:143], off offset:256
.LBB0_1173:
	s_andn2_b64 vcc, exec, s[4:5]
	s_cbranch_vccnz .LBB0_1175
	v_mul_f32_e32 v140, v170, v172
	v_trunc_f32_e32 v140, v140
	v_cvt_u32_f32_e32 v141, v140
	v_fma_f32 v140, -v140, v171, v170
	v_cmp_ge_f32_e64 s[4:5], |v140|, v171
	s_cmp_lg_u64 s[4:5], 0
	v_readfirstlane_b32 s4, v141
	s_addc_u32 s4, s4, 0
	s_and_b32 s4, s4, 0xff
	s_lshl_b32 s4, s4, 23
	s_add_u32 s4, s72, s4
	s_addc_u32 s5, s73, 0
	v_lshl_add_u64 v[140:141], s[4:5], 0, v[164:165]
	v_lshl_add_u64 v[140:141], v[158:159], 2, v[140:141]
	s_cmp_eq_u32 s100, 1
	s_cbranch_scc1 .Lgd_sp1
	global_store_dwordx4 v[140:141], v[136:139], off offset:512
	global_store_dwordx4 v[140:141], v[132:135], off offset:528
.Lgd_sp1:
.LBB0_1175:
	s_nop 1
	v_or_b32_e32 v132, 16, v160
	v_ashrrev_i32_e32 v133, 31, v132
	v_lshlrev_b64 v[132:133], 11, v[132:133]
	v_lshl_add_u64 v[132:133], v[132:133], 0, v[158:159]
	v_pk_mul_f32 v[130:131], v[130:131], v[88:89]
	v_pk_mul_f32 v[128:129], v[128:129], v[86:87]
	v_pk_mul_f32 v[126:127], v[126:127], v[84:85]
	v_pk_mul_f32 v[124:125], v[124:125], v[82:83]
	s_mov_b64 s[4:5], -1
	s_and_b64 vcc, exec, s[56:57]
	v_lshl_add_u64 v[132:133], v[132:133], 1, s[42:43]
	s_cbranch_vccz .LBB0_1177
	global_load_dwordx4 v[134:137], v[132:133], off
	s_mov_b64 s[4:5], 0
	s_waitcnt vmcnt(0)
	v_lshlrev_b32_e32 v138, 16, v134
	v_and_b32_e32 v139, 0xffff0000, v134
	v_lshlrev_b32_e32 v134, 16, v135
	v_and_b32_e32 v135, 0xffff0000, v135
	v_lshlrev_b32_e32 v140, 16, v136
	v_and_b32_e32 v141, 0xffff0000, v136
	v_lshlrev_b32_e32 v136, 16, v137
	v_and_b32_e32 v137, 0xffff0000, v137
	v_pk_add_f32 v[142:143], v[130:131], v[134:135]
	v_pk_add_f32 v[134:135], v[128:129], v[138:139]
	v_pk_add_f32 v[138:139], v[126:127], v[136:137]
	v_pk_add_f32 v[136:137], v[124:125], v[140:141]
	v_cvt_pk_bf16_f32 v134, v134, v135
	v_cvt_pk_bf16_f32 v135, v142, v143
	s_nop 0
	v_cvt_pk_bf16_f32 v136, v136, v137
	v_cvt_pk_bf16_f32 v137, v138, v139
	global_store_dwordx4 v[132:133], v[134:137], off
.LBB0_1177:
	s_andn2_b64 vcc, exec, s[4:5]
	s_mov_b32 s4, 0xf8020000
	v_lshlrev_b64 v[134:135], 13, v[160:161]
	s_mov_b32 s5, -1
	v_lshl_add_u64 v[134:135], v[134:135], 0, s[4:5]
	s_cbranch_vccnz .LBB0_1179
	v_mul_f32_e32 v136, v170, v172
	v_trunc_f32_e32 v136, v136
	v_cvt_u32_f32_e32 v137, v136
	v_fma_f32 v136, -v136, v171, v170
	v_cmp_ge_f32_e64 s[4:5], |v136|, v171
	s_cmp_lg_u64 s[4:5], 0
	v_readfirstlane_b32 s4, v137
	s_addc_u32 s4, s4, 0
	s_and_b32 s4, s4, 0xff
	s_lshl_b32 s4, s4, 23
	s_add_u32 s4, s72, s4
	s_addc_u32 s5, s73, 0
	v_lshl_add_u64 v[136:137], s[4:5], 0, v[134:135]
	v_lshl_add_u64 v[136:137], v[158:159], 2, v[136:137]
	s_cmp_eq_u32 s100, 2
	s_cbranch_scc1 .Lgd_sp2
	global_store_dwordx4 v[136:137], v[128:131], off
	global_store_dwordx4 v[136:137], v[124:127], off offset:16
.Lgd_sp2:
.LBB0_1179:
	v_pk_mul_f32 v[122:123], v[122:123], v[72:73]
	v_pk_mul_f32 v[120:121], v[120:121], v[70:71]
	v_pk_mul_f32 v[118:119], v[118:119], v[68:69]
	v_pk_mul_f32 v[116:117], v[116:117], v[66:67]
	s_mov_b64 s[4:5], -1
	s_and_b64 vcc, exec, s[56:57]
	s_cbranch_vccz .LBB0_1181
	global_load_dwordx4 v[124:127], v[132:133], off offset:256
	s_mov_b64 s[4:5], 0
	s_waitcnt vmcnt(0)
	v_lshlrev_b32_e32 v128, 16, v124
	v_and_b32_e32 v129, 0xffff0000, v124
	v_lshlrev_b32_e32 v124, 16, v125
	v_and_b32_e32 v125, 0xffff0000, v125
	v_lshlrev_b32_e32 v130, 16, v126
	v_and_b32_e32 v131, 0xffff0000, v126
	v_lshlrev_b32_e32 v126, 16, v127
	v_and_b32_e32 v127, 0xffff0000, v127
	v_pk_add_f32 v[136:137], v[122:123], v[124:125]
	v_pk_add_f32 v[124:125], v[120:121], v[128:129]
	v_pk_add_f32 v[128:129], v[118:119], v[126:127]
	v_pk_add_f32 v[126:127], v[116:117], v[130:131]
	v_cvt_pk_bf16_f32 v124, v124, v125
	v_cvt_pk_bf16_f32 v125, v136, v137
	s_nop 0
	v_cvt_pk_bf16_f32 v126, v126, v127
	v_cvt_pk_bf16_f32 v127, v128, v129
	global_store_dwordx4 v[132:133], v[124:127], off offset:256
.LBB0_1181:
	s_andn2_b64 vcc, exec, s[4:5]
	s_cbranch_vccnz .LBB0_1183
	v_mul_f32_e32 v124, v170, v172
	v_trunc_f32_e32 v124, v124
	v_cvt_u32_f32_e32 v125, v124
	v_fma_f32 v124, -v124, v171, v170
	v_cmp_ge_f32_e64 s[4:5], |v124|, v171
	s_cmp_lg_u64 s[4:5], 0
	v_readfirstlane_b32 s4, v125
	s_addc_u32 s4, s4, 0
	s_and_b32 s4, s4, 0xff
	s_lshl_b32 s4, s4, 23
	s_add_u32 s4, s72, s4
	s_addc_u32 s5, s73, 0
	v_lshl_add_u64 v[124:125], s[4:5], 0, v[134:135]
	v_lshl_add_u64 v[124:125], v[158:159], 2, v[124:125]
	s_cmp_eq_u32 s100, 1
	s_cbranch_scc1 .Lgd_sp3
	global_store_dwordx4 v[124:125], v[120:123], off offset:512
	global_store_dwordx4 v[124:125], v[116:119], off offset:528
.Lgd_sp3:
.LBB0_1183:
	s_nop 1
	v_or_b32_e32 v116, 32, v160
	v_ashrrev_i32_e32 v117, 31, v116
	v_lshlrev_b64 v[116:117], 11, v[116:117]
	v_lshl_add_u64 v[116:117], v[116:117], 0, v[158:159]
	v_pk_mul_f32 v[114:115], v[114:115], v[88:89]
	v_pk_mul_f32 v[112:113], v[112:113], v[86:87]
	v_pk_mul_f32 v[110:111], v[110:111], v[84:85]
	v_pk_mul_f32 v[108:109], v[108:109], v[82:83]
	s_mov_b64 s[4:5], -1
	s_and_b64 vcc, exec, s[56:57]
	v_lshl_add_u64 v[116:117], v[116:117], 1, s[42:43]
	s_cbranch_vccz .LBB0_1185
	global_load_dwordx4 v[118:121], v[116:117], off
	s_mov_b64 s[4:5], 0
	s_waitcnt vmcnt(0)
	v_lshlrev_b32_e32 v122, 16, v118
	v_and_b32_e32 v123, 0xffff0000, v118
	v_lshlrev_b32_e32 v118, 16, v119
	v_and_b32_e32 v119, 0xffff0000, v119
	v_lshlrev_b32_e32 v124, 16, v120
	v_and_b32_e32 v125, 0xffff0000, v120
	v_lshlrev_b32_e32 v120, 16, v121
	v_and_b32_e32 v121, 0xffff0000, v121
	v_pk_add_f32 v[126:127], v[114:115], v[118:119]
	v_pk_add_f32 v[118:119], v[112:113], v[122:123]
	v_pk_add_f32 v[122:123], v[110:111], v[120:121]
	v_pk_add_f32 v[120:121], v[108:109], v[124:125]
	v_cvt_pk_bf16_f32 v118, v118, v119
	v_cvt_pk_bf16_f32 v119, v126, v127
	s_nop 0
	v_cvt_pk_bf16_f32 v120, v120, v121
	v_cvt_pk_bf16_f32 v121, v122, v123
	global_store_dwordx4 v[116:117], v[118:121], off
.LBB0_1185:
	s_andn2_b64 vcc, exec, s[4:5]
	s_mov_b32 s4, 0xf8040000
	v_lshlrev_b64 v[118:119], 13, v[160:161]
	s_mov_b32 s5, -1
	v_lshl_add_u64 v[118:119], v[118:119], 0, s[4:5]
	s_cbranch_vccnz .LBB0_1187
	v_mul_f32_e32 v120, v170, v172
	v_trunc_f32_e32 v120, v120
	v_cvt_u32_f32_e32 v121, v120
	v_fma_f32 v120, -v120, v171, v170
	v_cmp_ge_f32_e64 s[4:5], |v120|, v171
	s_cmp_lg_u64 s[4:5], 0
	v_readfirstlane_b32 s4, v121
	s_addc_u32 s4, s4, 0
	s_and_b32 s4, s4, 0xff
	s_lshl_b32 s4, s4, 23
	s_add_u32 s4, s72, s4
	s_addc_u32 s5, s73, 0
	v_lshl_add_u64 v[120:121], s[4:5], 0, v[118:119]
	v_lshl_add_u64 v[120:121], v[158:159], 2, v[120:121]
	s_cmp_eq_u32 s100, 2
	s_cbranch_scc1 .Lgd_sp4
	global_store_dwordx4 v[120:121], v[112:115], off
	global_store_dwordx4 v[120:121], v[108:111], off offset:16
.Lgd_sp4:
.LBB0_1187:
	v_pk_mul_f32 v[106:107], v[106:107], v[72:73]
	v_pk_mul_f32 v[104:105], v[104:105], v[70:71]
	v_pk_mul_f32 v[102:103], v[102:103], v[68:69]
	v_pk_mul_f32 v[100:101], v[100:101], v[66:67]
	s_mov_b64 s[4:5], -1
	s_and_b64 vcc, exec, s[56:57]
	s_cbranch_vccz .LBB0_1189
	global_load_dwordx4 v[108:111], v[116:117], off offset:256
	s_mov_b64 s[4:5], 0
	s_waitcnt vmcnt(0)
	v_lshlrev_b32_e32 v112, 16, v108
	v_and_b32_e32 v113, 0xffff0000, v108
	v_lshlrev_b32_e32 v108, 16, v109
	v_and_b32_e32 v109, 0xffff0000, v109
	v_lshlrev_b32_e32 v114, 16, v110
	v_and_b32_e32 v115, 0xffff0000, v110
	v_lshlrev_b32_e32 v110, 16, v111
	v_and_b32_e32 v111, 0xffff0000, v111
	v_pk_add_f32 v[120:121], v[106:107], v[108:109]
	v_pk_add_f32 v[108:109], v[104:105], v[112:113]
	v_pk_add_f32 v[112:113], v[102:103], v[110:111]
	v_pk_add_f32 v[110:111], v[100:101], v[114:115]
	v_cvt_pk_bf16_f32 v108, v108, v109
	v_cvt_pk_bf16_f32 v109, v120, v121
	s_nop 0
	v_cvt_pk_bf16_f32 v110, v110, v111
	v_cvt_pk_bf16_f32 v111, v112, v113
	global_store_dwordx4 v[116:117], v[108:111], off offset:256
.LBB0_1189:
	s_andn2_b64 vcc, exec, s[4:5]
	s_cbranch_vccnz .LBB0_1191
	v_mul_f32_e32 v108, v170, v172
	v_trunc_f32_e32 v108, v108
	v_cvt_u32_f32_e32 v109, v108
	v_fma_f32 v108, -v108, v171, v170
	v_cmp_ge_f32_e64 s[4:5], |v108|, v171
	s_cmp_lg_u64 s[4:5], 0
	v_readfirstlane_b32 s4, v109
	s_addc_u32 s4, s4, 0
	s_and_b32 s4, s4, 0xff
	s_lshl_b32 s4, s4, 23
	s_add_u32 s4, s72, s4
	s_addc_u32 s5, s73, 0
	v_lshl_add_u64 v[108:109], s[4:5], 0, v[118:119]
	v_lshl_add_u64 v[108:109], v[158:159], 2, v[108:109]
	s_cmp_eq_u32 s100, 1
	s_cbranch_scc1 .Lgd_sp5
	global_store_dwordx4 v[108:109], v[104:107], off offset:512
	global_store_dwordx4 v[108:109], v[100:103], off offset:528
.Lgd_sp5:
.LBB0_1191:
	s_nop 1
	v_or_b32_e32 v100, 48, v160
	v_ashrrev_i32_e32 v101, 31, v100
	v_lshlrev_b64 v[100:101], 11, v[100:101]
	v_lshl_add_u64 v[100:101], v[100:101], 0, v[158:159]
	v_pk_mul_f32 v[96:97], v[96:97], v[88:89]
	v_pk_mul_f32 v[94:95], v[94:95], v[86:87]
	v_pk_mul_f32 v[92:93], v[92:93], v[84:85]
	v_pk_mul_f32 v[90:91], v[90:91], v[82:83]
	s_mov_b64 s[4:5], -1
	s_and_b64 vcc, exec, s[56:57]
	v_lshl_add_u64 v[100:101], v[100:101], 1, s[42:43]
	s_cbranch_vccz .LBB0_1193
	global_load_dwordx4 v[102:105], v[100:101], off
	s_mov_b64 s[4:5], 0
	s_waitcnt vmcnt(0)
	v_lshlrev_b32_e32 v106, 16, v102
	v_and_b32_e32 v107, 0xffff0000, v102
	v_lshlrev_b32_e32 v102, 16, v103
	v_and_b32_e32 v103, 0xffff0000, v103
	v_lshlrev_b32_e32 v108, 16, v104
	v_and_b32_e32 v109, 0xffff0000, v104
	v_lshlrev_b32_e32 v104, 16, v105
	v_and_b32_e32 v105, 0xffff0000, v105
	v_pk_add_f32 v[110:111], v[96:97], v[102:103]
	v_pk_add_f32 v[102:103], v[94:95], v[106:107]
	v_pk_add_f32 v[106:107], v[92:93], v[104:105]
	v_pk_add_f32 v[104:105], v[90:91], v[108:109]
	v_cvt_pk_bf16_f32 v102, v102, v103
	v_cvt_pk_bf16_f32 v103, v110, v111
	s_nop 0
	v_cvt_pk_bf16_f32 v104, v104, v105
	v_cvt_pk_bf16_f32 v105, v106, v107
	global_store_dwordx4 v[100:101], v[102:105], off
.LBB0_1193:
	s_andn2_b64 vcc, exec, s[4:5]
	s_mov_b32 s4, 0xf8060000
	v_lshlrev_b64 v[102:103], 13, v[160:161]
	s_mov_b32 s5, -1
	v_lshl_add_u64 v[102:103], v[102:103], 0, s[4:5]
	s_cbranch_vccnz .LBB0_1195
	v_mul_f32_e32 v104, v170, v172
	v_trunc_f32_e32 v104, v104
	v_cvt_u32_f32_e32 v105, v104
	v_fma_f32 v104, -v104, v171, v170
	v_cmp_ge_f32_e64 s[4:5], |v104|, v171
	s_cmp_lg_u64 s[4:5], 0
	v_readfirstlane_b32 s4, v105
	s_addc_u32 s4, s4, 0
	s_and_b32 s4, s4, 0xff
	s_lshl_b32 s4, s4, 23
	s_add_u32 s4, s72, s4
	s_addc_u32 s5, s73, 0
	v_lshl_add_u64 v[104:105], s[4:5], 0, v[102:103]
	v_lshl_add_u64 v[104:105], v[158:159], 2, v[104:105]
	s_cmp_eq_u32 s100, 2
	s_cbranch_scc1 .Lgd_sp6
	global_store_dwordx4 v[104:105], v[94:97], off
	global_store_dwordx4 v[104:105], v[90:93], off offset:16
.Lgd_sp6:
.LBB0_1195:
	v_pk_mul_f32 v[80:81], v[80:81], v[72:73]
	v_pk_mul_f32 v[78:79], v[78:79], v[70:71]
	v_pk_mul_f32 v[76:77], v[76:77], v[68:69]
	v_pk_mul_f32 v[74:75], v[74:75], v[66:67]
	s_mov_b64 s[4:5], -1
	s_and_b64 vcc, exec, s[56:57]
	s_cbranch_vccz .LBB0_1197
	global_load_dwordx4 v[90:93], v[100:101], off offset:256
	s_mov_b64 s[4:5], 0
	s_waitcnt vmcnt(0)
	v_lshlrev_b32_e32 v94, 16, v90
	v_and_b32_e32 v95, 0xffff0000, v90
	v_lshlrev_b32_e32 v90, 16, v91
	v_and_b32_e32 v91, 0xffff0000, v91
	v_lshlrev_b32_e32 v96, 16, v92
	v_and_b32_e32 v97, 0xffff0000, v92
	v_lshlrev_b32_e32 v92, 16, v93
	v_and_b32_e32 v93, 0xffff0000, v93
	v_pk_add_f32 v[104:105], v[80:81], v[90:91]
	v_pk_add_f32 v[90:91], v[78:79], v[94:95]
	v_pk_add_f32 v[94:95], v[76:77], v[92:93]
	v_pk_add_f32 v[92:93], v[74:75], v[96:97]
	v_cvt_pk_bf16_f32 v90, v90, v91
	v_cvt_pk_bf16_f32 v91, v104, v105
	s_nop 0
	v_cvt_pk_bf16_f32 v92, v92, v93
	v_cvt_pk_bf16_f32 v93, v94, v95
	global_store_dwordx4 v[100:101], v[90:93], off offset:256
.LBB0_1197:
	s_andn2_b64 vcc, exec, s[4:5]
	s_cbranch_vccnz .LBB0_1199
	v_mul_f32_e32 v90, v170, v172
	v_trunc_f32_e32 v90, v90
	v_cvt_u32_f32_e32 v91, v90
	v_fma_f32 v90, -v90, v171, v170
	v_cmp_ge_f32_e64 s[4:5], |v90|, v171
	s_cmp_lg_u64 s[4:5], 0
	v_readfirstlane_b32 s4, v91
	s_addc_u32 s4, s4, 0
	s_and_b32 s4, s4, 0xff
	s_lshl_b32 s4, s4, 23
	s_add_u32 s4, s72, s4
	s_addc_u32 s5, s73, 0
	v_lshl_add_u64 v[90:91], s[4:5], 0, v[102:103]
	v_lshl_add_u64 v[90:91], v[158:159], 2, v[90:91]
	s_cmp_eq_u32 s100, 1
	s_cbranch_scc1 .Lgd_sp7
	global_store_dwordx4 v[90:91], v[78:81], off offset:512
	global_store_dwordx4 v[90:91], v[74:77], off offset:528
.Lgd_sp7:
.LBB0_1199:
	s_nop 1
	v_lshlrev_b64 v[74:75], 11, v[160:161]
	v_lshl_add_u64 v[74:75], v[74:75], 0, v[158:159]
	s_mov_b64 s[4:5], 0x40000
	v_lshl_add_u64 v[74:75], v[74:75], 0, s[4:5]
	v_pk_mul_f32 v[64:65], v[64:65], v[88:89]
	v_pk_mul_f32 v[62:63], v[62:63], v[86:87]
	v_pk_mul_f32 v[60:61], v[60:61], v[84:85]
	v_pk_mul_f32 v[58:59], v[58:59], v[82:83]
	s_mov_b64 s[4:5], -1
	s_and_b64 vcc, exec, s[56:57]
	v_lshl_add_u64 v[74:75], v[74:75], 1, s[42:43]
	s_cbranch_vccz .LBB0_1201
	global_load_dwordx4 v[76:79], v[74:75], off
	s_mov_b64 s[4:5], 0
	s_waitcnt vmcnt(0)
	v_lshlrev_b32_e32 v80, 16, v76
	v_and_b32_e32 v81, 0xffff0000, v76
	v_lshlrev_b32_e32 v76, 16, v77
	v_and_b32_e32 v77, 0xffff0000, v77
	v_lshlrev_b32_e32 v90, 16, v78
	v_and_b32_e32 v91, 0xffff0000, v78
	v_lshlrev_b32_e32 v78, 16, v79
	v_and_b32_e32 v79, 0xffff0000, v79
	v_pk_add_f32 v[92:93], v[64:65], v[76:77]
	v_pk_add_f32 v[76:77], v[62:63], v[80:81]
	v_pk_add_f32 v[80:81], v[60:61], v[78:79]
	v_pk_add_f32 v[78:79], v[58:59], v[90:91]
	v_cvt_pk_bf16_f32 v76, v76, v77
	v_cvt_pk_bf16_f32 v77, v92, v93
	s_nop 0
	v_cvt_pk_bf16_f32 v78, v78, v79
	v_cvt_pk_bf16_f32 v79, v80, v81
	global_store_dwordx4 v[74:75], v[76:79], off
.LBB0_1201:
	s_andn2_b64 vcc, exec, s[4:5]
	s_mov_b32 s4, 0xf8100000
	v_lshlrev_b64 v[76:77], 13, v[160:161]
	s_mov_b32 s5, -1
	v_lshl_add_u64 v[76:77], v[76:77], 0, s[4:5]
	s_cbranch_vccnz .LBB0_1203
	v_mul_f32_e32 v78, v170, v172
	v_trunc_f32_e32 v78, v78
	v_cvt_u32_f32_e32 v79, v78
	v_fma_f32 v78, -v78, v171, v170
	v_cmp_ge_f32_e64 s[4:5], |v78|, v171
	s_cmp_lg_u64 s[4:5], 0
	v_readfirstlane_b32 s4, v79
	s_addc_u32 s4, s4, 0
	s_and_b32 s4, s4, 0xff
	s_lshl_b32 s4, s4, 23
	s_add_u32 s4, s72, s4
	s_addc_u32 s5, s73, 0
	v_lshl_add_u64 v[78:79], s[4:5], 0, v[76:77]
	v_lshl_add_u64 v[78:79], v[158:159], 2, v[78:79]
	s_cmp_eq_u32 s100, 2
	s_cbranch_scc1 .Lgd_sp8
	global_store_dwordx4 v[78:79], v[62:65], off
	global_store_dwordx4 v[78:79], v[58:61], off offset:16
.Lgd_sp8:
.LBB0_1203:
	v_pk_mul_f32 v[56:57], v[56:57], v[72:73]
	v_pk_mul_f32 v[54:55], v[54:55], v[70:71]
	v_pk_mul_f32 v[52:53], v[52:53], v[68:69]
	v_pk_mul_f32 v[50:51], v[50:51], v[66:67]
	s_mov_b64 s[4:5], -1
	s_and_b64 vcc, exec, s[56:57]
	s_cbranch_vccz .LBB0_1205
	global_load_dwordx4 v[58:61], v[74:75], off offset:256
	s_mov_b64 s[4:5], 0
	s_waitcnt vmcnt(0)
	v_lshlrev_b32_e32 v62, 16, v58
	v_and_b32_e32 v63, 0xffff0000, v58
	v_lshlrev_b32_e32 v58, 16, v59
	v_and_b32_e32 v59, 0xffff0000, v59
	v_lshlrev_b32_e32 v64, 16, v60
	v_and_b32_e32 v65, 0xffff0000, v60
	v_lshlrev_b32_e32 v60, 16, v61
	v_and_b32_e32 v61, 0xffff0000, v61
	v_pk_add_f32 v[78:79], v[56:57], v[58:59]
	v_pk_add_f32 v[58:59], v[54:55], v[62:63]
	v_pk_add_f32 v[62:63], v[52:53], v[60:61]
	v_pk_add_f32 v[60:61], v[50:51], v[64:65]
	v_cvt_pk_bf16_f32 v58, v58, v59
	v_cvt_pk_bf16_f32 v59, v78, v79
	s_nop 0
	v_cvt_pk_bf16_f32 v60, v60, v61
	v_cvt_pk_bf16_f32 v61, v62, v63
	global_store_dwordx4 v[74:75], v[58:61], off offset:256
.LBB0_1205:
	s_andn2_b64 vcc, exec, s[4:5]
	s_cbranch_vccnz .LBB0_1207
	v_mul_f32_e32 v58, v170, v172
	v_trunc_f32_e32 v58, v58
	v_cvt_u32_f32_e32 v59, v58
	v_fma_f32 v58, -v58, v171, v170
	v_cmp_ge_f32_e64 s[4:5], |v58|, v171
	s_cmp_lg_u64 s[4:5], 0
	v_readfirstlane_b32 s4, v59
	s_addc_u32 s4, s4, 0
	s_and_b32 s4, s4, 0xff
	s_lshl_b32 s4, s4, 23
	s_add_u32 s4, s72, s4
	s_addc_u32 s5, s73, 0
	v_lshl_add_u64 v[58:59], s[4:5], 0, v[76:77]
	v_lshl_add_u64 v[58:59], v[158:159], 2, v[58:59]
	s_cmp_eq_u32 s100, 1
	s_cbranch_scc1 .Lgd_sp9
	global_store_dwordx4 v[58:59], v[54:57], off offset:512
	global_store_dwordx4 v[58:59], v[50:53], off offset:528
.Lgd_sp9:
.LBB0_1207:
	s_nop 1
	v_lshlrev_b64 v[50:51], 11, v[160:161]
	v_lshl_add_u64 v[50:51], v[50:51], 0, v[158:159]
	s_mov_b64 s[4:5], 0x48000
	v_lshl_add_u64 v[50:51], v[50:51], 0, s[4:5]
	v_pk_mul_f32 v[48:49], v[48:49], v[88:89]
	v_pk_mul_f32 v[46:47], v[46:47], v[86:87]
	v_pk_mul_f32 v[44:45], v[44:45], v[84:85]
	v_pk_mul_f32 v[42:43], v[42:43], v[82:83]
	s_mov_b64 s[4:5], -1
	s_and_b64 vcc, exec, s[56:57]
	v_lshl_add_u64 v[50:51], v[50:51], 1, s[42:43]
	s_cbranch_vccz .LBB0_1209
	global_load_dwordx4 v[52:55], v[50:51], off
	s_mov_b64 s[4:5], 0
	s_waitcnt vmcnt(0)
	v_lshlrev_b32_e32 v56, 16, v52
	v_and_b32_e32 v57, 0xffff0000, v52
	v_lshlrev_b32_e32 v52, 16, v53
	v_and_b32_e32 v53, 0xffff0000, v53
	v_lshlrev_b32_e32 v58, 16, v54
	v_and_b32_e32 v59, 0xffff0000, v54
	v_lshlrev_b32_e32 v54, 16, v55
	v_and_b32_e32 v55, 0xffff0000, v55
	v_pk_add_f32 v[60:61], v[48:49], v[52:53]
	v_pk_add_f32 v[52:53], v[46:47], v[56:57]
	v_pk_add_f32 v[56:57], v[44:45], v[54:55]
	v_pk_add_f32 v[54:55], v[42:43], v[58:59]
	v_cvt_pk_bf16_f32 v52, v52, v53
	v_cvt_pk_bf16_f32 v53, v60, v61
	s_nop 0
	v_cvt_pk_bf16_f32 v54, v54, v55
	v_cvt_pk_bf16_f32 v55, v56, v57
	global_store_dwordx4 v[50:51], v[52:55], off
.LBB0_1209:
	s_andn2_b64 vcc, exec, s[4:5]
	s_mov_b32 s4, 0xf8120000
	v_lshlrev_b64 v[52:53], 13, v[160:161]
	s_mov_b32 s5, -1
	v_lshl_add_u64 v[52:53], v[52:53], 0, s[4:5]
	s_cbranch_vccnz .LBB0_1211
	v_mul_f32_e32 v54, v170, v172
	v_trunc_f32_e32 v54, v54
	v_cvt_u32_f32_e32 v55, v54
	v_fma_f32 v54, -v54, v171, v170
	v_cmp_ge_f32_e64 s[4:5], |v54|, v171
	s_cmp_lg_u64 s[4:5], 0
	v_readfirstlane_b32 s4, v55
	s_addc_u32 s4, s4, 0
	s_and_b32 s4, s4, 0xff
	s_lshl_b32 s4, s4, 23
	s_add_u32 s4, s72, s4
	s_addc_u32 s5, s73, 0
	v_lshl_add_u64 v[54:55], s[4:5], 0, v[52:53]
	v_lshl_add_u64 v[54:55], v[158:159], 2, v[54:55]
	s_cmp_eq_u32 s100, 2
	s_cbranch_scc1 .Lgd_sp10
	global_store_dwordx4 v[54:55], v[46:49], off
	global_store_dwordx4 v[54:55], v[42:45], off offset:16
.Lgd_sp10:
.LBB0_1211:
	v_pk_mul_f32 v[40:41], v[40:41], v[72:73]
	v_pk_mul_f32 v[38:39], v[38:39], v[70:71]
	v_pk_mul_f32 v[36:37], v[36:37], v[68:69]
	v_pk_mul_f32 v[34:35], v[34:35], v[66:67]
	s_mov_b64 s[4:5], -1
	s_and_b64 vcc, exec, s[56:57]
	s_cbranch_vccz .LBB0_1213
	global_load_dwordx4 v[42:45], v[50:51], off offset:256
	s_mov_b64 s[4:5], 0
	s_waitcnt vmcnt(0)
	v_lshlrev_b32_e32 v46, 16, v42
	v_and_b32_e32 v47, 0xffff0000, v42
	v_lshlrev_b32_e32 v42, 16, v43
	v_and_b32_e32 v43, 0xffff0000, v43
	v_lshlrev_b32_e32 v48, 16, v44
	v_and_b32_e32 v49, 0xffff0000, v44
	v_lshlrev_b32_e32 v44, 16, v45
	v_and_b32_e32 v45, 0xffff0000, v45
	v_pk_add_f32 v[54:55], v[40:41], v[42:43]
	v_pk_add_f32 v[42:43], v[38:39], v[46:47]
	v_pk_add_f32 v[46:47], v[36:37], v[44:45]
	v_pk_add_f32 v[44:45], v[34:35], v[48:49]
	v_cvt_pk_bf16_f32 v42, v42, v43
	v_cvt_pk_bf16_f32 v43, v54, v55
	s_nop 0
	v_cvt_pk_bf16_f32 v44, v44, v45
	v_cvt_pk_bf16_f32 v45, v46, v47
	global_store_dwordx4 v[50:51], v[42:45], off offset:256
.LBB0_1213:
	s_andn2_b64 vcc, exec, s[4:5]
	s_cbranch_vccnz .LBB0_1215
	v_mul_f32_e32 v42, v170, v172
	v_trunc_f32_e32 v42, v42
	v_cvt_u32_f32_e32 v43, v42
	v_fma_f32 v42, -v42, v171, v170
	v_cmp_ge_f32_e64 s[4:5], |v42|, v171
	s_cmp_lg_u64 s[4:5], 0
	v_readfirstlane_b32 s4, v43
	s_addc_u32 s4, s4, 0
	s_and_b32 s4, s4, 0xff
	s_lshl_b32 s4, s4, 23
	s_add_u32 s4, s72, s4
	s_addc_u32 s5, s73, 0
	v_lshl_add_u64 v[42:43], s[4:5], 0, v[52:53]
	v_lshl_add_u64 v[42:43], v[158:159], 2, v[42:43]
	s_cmp_eq_u32 s100, 1
	s_cbranch_scc1 .Lgd_sp11
	global_store_dwordx4 v[42:43], v[38:41], off offset:512
	global_store_dwordx4 v[42:43], v[34:37], off offset:528
.Lgd_sp11:
.LBB0_1215:
	s_nop 1
	v_lshlrev_b64 v[34:35], 11, v[160:161]
	v_lshl_add_u64 v[34:35], v[34:35], 0, v[158:159]
	s_mov_b64 s[4:5], 0x50000
	v_lshl_add_u64 v[34:35], v[34:35], 0, s[4:5]
	v_pk_mul_f32 v[32:33], v[32:33], v[88:89]
	v_pk_mul_f32 v[30:31], v[30:31], v[86:87]
	v_pk_mul_f32 v[28:29], v[28:29], v[84:85]
	v_pk_mul_f32 v[26:27], v[26:27], v[82:83]
	s_mov_b64 s[4:5], -1
	s_and_b64 vcc, exec, s[56:57]
	v_lshl_add_u64 v[34:35], v[34:35], 1, s[42:43]
	s_cbranch_vccz .LBB0_1217
	global_load_dwordx4 v[36:39], v[34:35], off
	s_mov_b64 s[4:5], 0
	s_waitcnt vmcnt(0)
	v_lshlrev_b32_e32 v40, 16, v36
	v_and_b32_e32 v41, 0xffff0000, v36
	v_lshlrev_b32_e32 v36, 16, v37
	v_and_b32_e32 v37, 0xffff0000, v37
	v_lshlrev_b32_e32 v42, 16, v38
	v_and_b32_e32 v43, 0xffff0000, v38
	v_lshlrev_b32_e32 v38, 16, v39
	v_and_b32_e32 v39, 0xffff0000, v39
	v_pk_add_f32 v[44:45], v[32:33], v[36:37]
	v_pk_add_f32 v[36:37], v[30:31], v[40:41]
	v_pk_add_f32 v[40:41], v[28:29], v[38:39]
	v_pk_add_f32 v[38:39], v[26:27], v[42:43]
	v_cvt_pk_bf16_f32 v36, v36, v37
	v_cvt_pk_bf16_f32 v37, v44, v45
	s_nop 0
	v_cvt_pk_bf16_f32 v38, v38, v39
	v_cvt_pk_bf16_f32 v39, v40, v41
	global_store_dwordx4 v[34:35], v[36:39], off
.LBB0_1217:
	s_andn2_b64 vcc, exec, s[4:5]
	s_mov_b32 s4, 0xf8140000
	v_lshlrev_b64 v[36:37], 13, v[160:161]
	s_mov_b32 s5, -1
	v_lshl_add_u64 v[36:37], v[36:37], 0, s[4:5]
	s_cbranch_vccnz .LBB0_1219
	v_mul_f32_e32 v38, v170, v172
	v_trunc_f32_e32 v38, v38
	v_cvt_u32_f32_e32 v39, v38
	v_fma_f32 v38, -v38, v171, v170
	v_cmp_ge_f32_e64 s[4:5], |v38|, v171
	s_cmp_lg_u64 s[4:5], 0
	v_readfirstlane_b32 s4, v39
	s_addc_u32 s4, s4, 0
	s_and_b32 s4, s4, 0xff
	s_lshl_b32 s4, s4, 23
	s_add_u32 s4, s72, s4
	s_addc_u32 s5, s73, 0
	v_lshl_add_u64 v[38:39], s[4:5], 0, v[36:37]
	v_lshl_add_u64 v[38:39], v[158:159], 2, v[38:39]
	s_cmp_eq_u32 s100, 2
	s_cbranch_scc1 .Lgd_sp12
	global_store_dwordx4 v[38:39], v[30:33], off
	global_store_dwordx4 v[38:39], v[26:29], off offset:16
.Lgd_sp12:
.LBB0_1219:
	v_pk_mul_f32 v[24:25], v[24:25], v[72:73]
	v_pk_mul_f32 v[22:23], v[22:23], v[70:71]
	v_pk_mul_f32 v[20:21], v[20:21], v[68:69]
	v_pk_mul_f32 v[18:19], v[18:19], v[66:67]
	s_mov_b64 s[4:5], -1
	s_and_b64 vcc, exec, s[56:57]
	s_cbranch_vccz .LBB0_1221
	global_load_dwordx4 v[26:29], v[34:35], off offset:256
	s_mov_b64 s[4:5], 0
	s_waitcnt vmcnt(0)
	v_lshlrev_b32_e32 v30, 16, v26
	v_and_b32_e32 v31, 0xffff0000, v26
	v_lshlrev_b32_e32 v26, 16, v27
	v_and_b32_e32 v27, 0xffff0000, v27
	v_lshlrev_b32_e32 v32, 16, v28
	v_and_b32_e32 v33, 0xffff0000, v28
	v_lshlrev_b32_e32 v28, 16, v29
	v_and_b32_e32 v29, 0xffff0000, v29
	v_pk_add_f32 v[38:39], v[24:25], v[26:27]
	v_pk_add_f32 v[26:27], v[22:23], v[30:31]
	v_pk_add_f32 v[30:31], v[20:21], v[28:29]
	v_pk_add_f32 v[28:29], v[18:19], v[32:33]
	v_cvt_pk_bf16_f32 v26, v26, v27
	v_cvt_pk_bf16_f32 v27, v38, v39
	s_nop 0
	v_cvt_pk_bf16_f32 v28, v28, v29
	v_cvt_pk_bf16_f32 v29, v30, v31
	global_store_dwordx4 v[34:35], v[26:29], off offset:256
.LBB0_1221:
	s_andn2_b64 vcc, exec, s[4:5]
	s_cbranch_vccnz .LBB0_1223
	v_mul_f32_e32 v26, v170, v172
	v_trunc_f32_e32 v26, v26
	v_cvt_u32_f32_e32 v27, v26
	v_fma_f32 v26, -v26, v171, v170
	v_cmp_ge_f32_e64 s[4:5], |v26|, v171
	s_cmp_lg_u64 s[4:5], 0
	v_readfirstlane_b32 s4, v27
	s_addc_u32 s4, s4, 0
	s_and_b32 s4, s4, 0xff
	s_lshl_b32 s4, s4, 23
	s_add_u32 s4, s72, s4
	s_addc_u32 s5, s73, 0
	v_lshl_add_u64 v[26:27], s[4:5], 0, v[36:37]
	v_lshl_add_u64 v[26:27], v[158:159], 2, v[26:27]
	s_cmp_eq_u32 s100, 1
	s_cbranch_scc1 .Lgd_sp13
	global_store_dwordx4 v[26:27], v[22:25], off offset:512
	global_store_dwordx4 v[26:27], v[18:21], off offset:528
.Lgd_sp13:
.LBB0_1223:
	s_nop 1
	v_lshlrev_b64 v[18:19], 11, v[160:161]
	v_lshl_add_u64 v[18:19], v[18:19], 0, v[158:159]
	s_mov_b64 s[4:5], 0x58000
	v_lshl_add_u64 v[18:19], v[18:19], 0, s[4:5]
	v_pk_mul_f32 v[16:17], v[16:17], v[88:89]
	v_pk_mul_f32 v[14:15], v[14:15], v[86:87]
	v_pk_mul_f32 v[12:13], v[12:13], v[84:85]
	v_pk_mul_f32 v[10:11], v[10:11], v[82:83]
	s_mov_b64 s[4:5], -1
	s_and_b64 vcc, exec, s[56:57]
	v_lshl_add_u64 v[18:19], v[18:19], 1, s[42:43]
	s_cbranch_vccz .LBB0_1225
	global_load_dwordx4 v[20:23], v[18:19], off
	s_mov_b64 s[4:5], 0
	s_waitcnt vmcnt(0)
	v_lshlrev_b32_e32 v24, 16, v20
	v_and_b32_e32 v25, 0xffff0000, v20
	v_lshlrev_b32_e32 v20, 16, v21
	v_and_b32_e32 v21, 0xffff0000, v21
	v_lshlrev_b32_e32 v26, 16, v22
	v_and_b32_e32 v27, 0xffff0000, v22
	v_lshlrev_b32_e32 v22, 16, v23
	v_and_b32_e32 v23, 0xffff0000, v23
	v_pk_add_f32 v[28:29], v[16:17], v[20:21]
	v_pk_add_f32 v[20:21], v[14:15], v[24:25]
	v_pk_add_f32 v[24:25], v[12:13], v[22:23]
	v_pk_add_f32 v[22:23], v[10:11], v[26:27]
	v_cvt_pk_bf16_f32 v20, v20, v21
	v_cvt_pk_bf16_f32 v21, v28, v29
	s_nop 0
	v_cvt_pk_bf16_f32 v22, v22, v23
	v_cvt_pk_bf16_f32 v23, v24, v25
	global_store_dwordx4 v[18:19], v[20:23], off
.LBB0_1225:
	s_andn2_b64 vcc, exec, s[4:5]
	s_mov_b32 s4, 0xf8160000
	v_lshlrev_b64 v[20:21], 13, v[160:161]
	s_mov_b32 s5, -1
	v_lshl_add_u64 v[20:21], v[20:21], 0, s[4:5]
	s_cbranch_vccnz .LBB0_1227
	v_mul_f32_e32 v22, v170, v172
	v_trunc_f32_e32 v22, v22
	v_cvt_u32_f32_e32 v23, v22
	v_fma_f32 v22, -v22, v171, v170
	v_cmp_ge_f32_e64 s[4:5], |v22|, v171
	s_cmp_lg_u64 s[4:5], 0
	v_readfirstlane_b32 s4, v23
	s_addc_u32 s4, s4, 0
	s_and_b32 s4, s4, 0xff
	s_lshl_b32 s4, s4, 23
	s_add_u32 s4, s72, s4
	s_addc_u32 s5, s73, 0
	v_lshl_add_u64 v[22:23], s[4:5], 0, v[20:21]
	v_lshl_add_u64 v[22:23], v[158:159], 2, v[22:23]
	s_cmp_eq_u32 s100, 2
	s_cbranch_scc1 .Lgd_sp14
	global_store_dwordx4 v[22:23], v[14:17], off
	global_store_dwordx4 v[22:23], v[10:13], off offset:16
.Lgd_sp14:
.LBB0_1227:
	v_pk_mul_f32 v[8:9], v[8:9], v[72:73]
	v_pk_mul_f32 v[6:7], v[6:7], v[70:71]
	v_pk_mul_f32 v[4:5], v[4:5], v[68:69]
	v_pk_mul_f32 v[2:3], v[2:3], v[66:67]
	s_mov_b64 s[4:5], -1
	s_and_b64 vcc, exec, s[56:57]
	s_cbranch_vccz .LBB0_1230
	global_load_dwordx4 v[10:13], v[18:19], off offset:256
	s_waitcnt vmcnt(0)
	v_lshlrev_b32_e32 v14, 16, v10
	v_and_b32_e32 v15, 0xffff0000, v10
	v_lshlrev_b32_e32 v10, 16, v11
	v_and_b32_e32 v11, 0xffff0000, v11
	v_lshlrev_b32_e32 v16, 16, v12
	v_and_b32_e32 v17, 0xffff0000, v12
	v_lshlrev_b32_e32 v12, 16, v13
	v_and_b32_e32 v13, 0xffff0000, v13
	v_pk_add_f32 v[22:23], v[8:9], v[10:11]
	v_pk_add_f32 v[10:11], v[6:7], v[14:15]
	v_pk_add_f32 v[14:15], v[4:5], v[12:13]
	v_pk_add_f32 v[12:13], v[2:3], v[16:17]
	v_cvt_pk_bf16_f32 v10, v10, v11
	v_cvt_pk_bf16_f32 v11, v22, v23
	s_nop 0
	v_cvt_pk_bf16_f32 v12, v12, v13
	v_cvt_pk_bf16_f32 v13, v14, v15
	global_store_dwordx4 v[18:19], v[10:13], off offset:256
	s_cbranch_execz .LBB0_1231

.LBB0_1231:
	s_nop 0
	v_mul_f32_e32 v10, v170, v172
	v_trunc_f32_e32 v10, v10
	v_cvt_u32_f32_e32 v11, v10
	v_fma_f32 v10, -v10, v171, v170
	v_cmp_ge_f32_e64 s[4:5], |v10|, v171
	s_cmp_lg_u64 s[4:5], 0
	v_readfirstlane_b32 s4, v11
	s_addc_u32 s4, s4, 0
	s_and_b32 s4, s4, 0xff
	s_lshl_b32 s4, s4, 23
	s_add_u32 s4, s72, s4
	s_addc_u32 s5, s73, 0
	v_lshl_add_u64 v[10:11], s[4:5], 0, v[20:21]
	v_lshl_add_u64 v[10:11], v[158:159], 2, v[10:11]
	s_cmp_eq_u32 s100, 1
	s_cbranch_scc1 .Lgd_sp15
	global_store_dwordx4 v[10:11], v[6:9], off offset:512
	global_store_dwordx4 v[10:11], v[2:5], off offset:528
.Lgd_sp15:
	s_and_b64 vcc, exec, s[40:41]
	s_mov_b64 s[4:5], -1
	s_cbranch_vccnz .LBB0_1148
.LBB0_1232:
	s_andn2_b64 vcc, exec, s[38:39]
	s_cbranch_vccnz .LBB0_1147
	s_barrier
	s_branch .LBB0_1147
.Lgd_h0_loop:
	s_add_i32 s11, s10, 2
	s_add_u32 s36, s4, 0x100
	s_addc_u32 s37, s5, 0
	s_add_i32 s12, 0, 0x10000
	s_cmp_eq_u32 s84, s10
	s_cselect_b32 s59, s49, s37
	s_cselect_b32 s58, s48, s36
	s_cselect_b32 s21, s55, s86
	s_cselect_b32 s20, s54, s85
	s_add_i32 s10, 0, 0x14000
	v_add_u32_e32 v86, s12, v167
	v_add_u32_e32 v174, s10, v167
	ds_read_b128 v[66:69], v86
	ds_read_b128 v[70:73], v86 offset:1024
	ds_read_b128 v[82:85], v86 offset:2048
	ds_read_b128 v[86:89], v86 offset:3072
	v_lshl_add_u64 v[198:199], s[4:5], 0, v[154:155]
	s_add_i32 m0, s66, 0xc000
	ds_read_b128 v[178:181], v169
	ds_read_b128 v[182:185], v169 offset:1024
	ds_read_b128 v[186:189], v169 offset:2048
	ds_read_b128 v[190:193], v169 offset:3072
	ds_read_b128 v[194:197], v169 offset:4096
	ds_read_b128 v[208:211], v169 offset:5120
	ds_read_b128 v[212:215], v169 offset:6144
	ds_read_b128 v[216:219], v169 offset:7168
	global_load_lds_dwordx4 v[198:199], off
	v_lshl_add_u64 v[198:199], s[4:5], 0, v[156:157]
	s_add_i32 m0, s66, 0xe000
	s_nop 0
	global_load_lds_dwordx4 v[198:199], off
	s_waitcnt vmcnt(8)
	s_waitcnt lgkmcnt(0)
	s_barrier
	s_setprio 1
	s_waitcnt lgkmcnt(0)
	v_mfma_f32_16x16x32_bf16 v[144:147], v[66:69], v[178:181], v[144:147]
	v_mfma_f32_16x16x32_bf16 v[140:143], v[82:85], v[178:181], v[140:143]
	v_mfma_f32_16x16x32_bf16 v[128:131], v[66:69], v[186:189], v[128:131]
	v_mfma_f32_16x16x32_bf16 v[124:127], v[82:85], v[186:189], v[124:127]
	v_mfma_f32_16x16x32_bf16 v[112:115], v[66:69], v[194:197], v[112:115]
	v_mfma_f32_16x16x32_bf16 v[108:111], v[82:85], v[194:197], v[108:111]
	v_mfma_f32_16x16x32_bf16 v[94:97], v[66:69], v[212:215], v[94:97]
	v_mfma_f32_16x16x32_bf16 v[90:93], v[82:85], v[212:215], v[90:93]
	v_mfma_f32_16x16x32_bf16 v[144:147], v[70:73], v[182:185], v[144:147]
	v_mfma_f32_16x16x32_bf16 v[140:143], v[86:89], v[182:185], v[140:143]
	v_mfma_f32_16x16x32_bf16 v[128:131], v[70:73], v[190:193], v[128:131]
	v_mfma_f32_16x16x32_bf16 v[124:127], v[86:89], v[190:193], v[124:127]
	v_mfma_f32_16x16x32_bf16 v[112:115], v[70:73], v[208:211], v[112:115]
	v_mfma_f32_16x16x32_bf16 v[108:111], v[86:89], v[208:211], v[108:111]
	v_mfma_f32_16x16x32_bf16 v[94:97], v[70:73], v[216:219], v[94:97]
	v_mfma_f32_16x16x32_bf16 v[90:93], v[86:89], v[216:219], v[90:93]
	s_setprio 0
	s_setprio 1
	s_setprio 0
	s_barrier
	s_add_i32 s4, s12, s65
	v_lshl_add_u64 v[198:199], s[20:21], 0, v[152:153]
	s_mov_b32 m0, s4
	ds_read_b128 v[178:181], v169 offset:16384
	ds_read_b128 v[182:185], v169 offset:17408
	ds_read_b128 v[186:189], v169 offset:18432
	ds_read_b128 v[190:193], v169 offset:19456
	ds_read_b128 v[194:197], v169 offset:20480
	ds_read_b128 v[208:211], v169 offset:21504
	ds_read_b128 v[212:215], v169 offset:22528
	ds_read_b128 v[216:219], v169 offset:23552
	global_load_lds_dwordx4 v[198:199], off
	s_add_i32 m0, s4, 0x2000
	s_add_u32 s4, s20, 0x4000
	v_lshl_add_u64 v[198:199], s[20:21], 0, v[148:149]
	s_addc_u32 s5, s21, 0
	s_add_i32 s10, s10, s65
	global_load_lds_dwordx4 v[198:199], off
	v_lshl_add_u64 v[198:199], s[4:5], 0, v[152:153]
	s_mov_b32 m0, s10
	v_lshl_add_u64 v[220:221], s[58:59], 0, v[150:151]
	global_load_lds_dwordx4 v[198:199], off
	v_lshl_add_u64 v[198:199], s[4:5], 0, v[148:149]
	s_add_i32 m0, s10, 0x2000
	s_nop 0
	global_load_lds_dwordx4 v[198:199], off
	v_lshl_add_u64 v[198:199], s[58:59], 0, v[98:99]
	s_mov_b32 m0, s66
	s_nop 0
	global_load_lds_dwordx4 v[198:199], off
	s_mov_b32 m0, s67
	s_nop 0
	global_load_lds_dwordx4 v[220:221], off
	s_waitcnt vmcnt(8)
	s_waitcnt lgkmcnt(0)
	s_barrier
	s_setprio 1
	s_waitcnt lgkmcnt(0)
	v_mfma_f32_16x16x32_bf16 v[62:65], v[66:69], v[178:181], v[62:65]
	v_mfma_f32_16x16x32_bf16 v[58:61], v[82:85], v[178:181], v[58:61]
	v_mfma_f32_16x16x32_bf16 v[46:49], v[66:69], v[186:189], v[46:49]
	v_mfma_f32_16x16x32_bf16 v[42:45], v[82:85], v[186:189], v[42:45]
	v_mfma_f32_16x16x32_bf16 v[30:33], v[66:69], v[194:197], v[30:33]
	v_mfma_f32_16x16x32_bf16 v[26:29], v[82:85], v[194:197], v[26:29]
	v_mfma_f32_16x16x32_bf16 v[14:17], v[66:69], v[212:215], v[14:17]
	v_mfma_f32_16x16x32_bf16 v[10:13], v[82:85], v[212:215], v[10:13]
	v_mfma_f32_16x16x32_bf16 v[62:65], v[70:73], v[182:185], v[62:65]
	v_mfma_f32_16x16x32_bf16 v[58:61], v[86:89], v[182:185], v[58:61]
	v_mfma_f32_16x16x32_bf16 v[46:49], v[70:73], v[190:193], v[46:49]
	v_mfma_f32_16x16x32_bf16 v[42:45], v[86:89], v[190:193], v[42:45]
	v_mfma_f32_16x16x32_bf16 v[30:33], v[70:73], v[208:211], v[30:33]
	v_mfma_f32_16x16x32_bf16 v[26:29], v[86:89], v[208:211], v[26:29]
	v_mfma_f32_16x16x32_bf16 v[14:17], v[70:73], v[216:219], v[14:17]
	v_mfma_f32_16x16x32_bf16 v[10:13], v[86:89], v[216:219], v[10:13]
	s_setprio 0
	s_setprio 1
	s_setprio 0
	s_barrier
	s_add_i32 s10, 0, 0x18000
	s_add_i32 s12, 0, 0x1c000
	v_add_u32_e32 v86, s10, v167
	v_add_u32_e32 v174, s12, v167
	ds_read_b128 v[66:69], v86
	ds_read_b128 v[70:73], v86 offset:1024
	ds_read_b128 v[82:85], v86 offset:2048
	ds_read_b128 v[86:89], v86 offset:3072
	s_add_u32 s4, s58, 0x160000
	s_addc_u32 s5, s59, 0
	s_mov_b32 m0, s68
	v_lshl_add_u64 v[222:223], s[4:5], 0, v[98:99]
	ds_read_b128 v[178:181], v169 offset:32768
	ds_read_b128 v[182:185], v169 offset:33792
	ds_read_b128 v[186:189], v169 offset:34816
	ds_read_b128 v[190:193], v169 offset:35840
	ds_read_b128 v[194:197], v169 offset:36864
	ds_read_b128 v[208:211], v169 offset:37888
	ds_read_b128 v[212:215], v169 offset:38912
	ds_read_b128 v[216:219], v169 offset:39936
	global_load_lds_dwordx4 v[222:223], off
	v_lshl_add_u64 v[222:223], s[4:5], 0, v[150:151]
	s_mov_b32 m0, s69
	s_nop 0
	global_load_lds_dwordx4 v[222:223], off
	s_waitcnt vmcnt(8)
	s_waitcnt lgkmcnt(0)
	s_barrier
	s_setprio 1
	s_waitcnt lgkmcnt(0)
	v_mfma_f32_16x16x32_bf16 v[144:147], v[66:69], v[178:181], v[144:147]
	v_mfma_f32_16x16x32_bf16 v[140:143], v[82:85], v[178:181], v[140:143]
	v_mfma_f32_16x16x32_bf16 v[128:131], v[66:69], v[186:189], v[128:131]
	v_mfma_f32_16x16x32_bf16 v[124:127], v[82:85], v[186:189], v[124:127]
	v_mfma_f32_16x16x32_bf16 v[112:115], v[66:69], v[194:197], v[112:115]
	v_mfma_f32_16x16x32_bf16 v[108:111], v[82:85], v[194:197], v[108:111]
	v_mfma_f32_16x16x32_bf16 v[94:97], v[66:69], v[212:215], v[94:97]
	v_mfma_f32_16x16x32_bf16 v[90:93], v[82:85], v[212:215], v[90:93]
	v_mfma_f32_16x16x32_bf16 v[144:147], v[70:73], v[182:185], v[144:147]
	v_mfma_f32_16x16x32_bf16 v[140:143], v[86:89], v[182:185], v[140:143]
	v_mfma_f32_16x16x32_bf16 v[128:131], v[70:73], v[190:193], v[128:131]
	v_mfma_f32_16x16x32_bf16 v[124:127], v[86:89], v[190:193], v[124:127]
	v_mfma_f32_16x16x32_bf16 v[112:115], v[70:73], v[208:211], v[112:115]
	v_mfma_f32_16x16x32_bf16 v[108:111], v[86:89], v[208:211], v[108:111]
	v_mfma_f32_16x16x32_bf16 v[94:97], v[70:73], v[216:219], v[94:97]
	v_mfma_f32_16x16x32_bf16 v[90:93], v[86:89], v[216:219], v[90:93]
	s_setprio 0
	s_setprio 1
	s_setprio 0
	s_barrier
	s_add_u32 s4, s20, 0x8000
	s_addc_u32 s5, s21, 0
	s_add_i32 s10, s10, s65
	v_lshl_add_u64 v[222:223], s[4:5], 0, v[152:153]
	s_mov_b32 m0, s10
	ds_read_b128 v[178:181], v169 offset:49152
	ds_read_b128 v[182:185], v169 offset:50176
	ds_read_b128 v[186:189], v169 offset:51200
	ds_read_b128 v[190:193], v169 offset:52224
	ds_read_b128 v[194:197], v169 offset:53248
	ds_read_b128 v[208:211], v169 offset:54272
	ds_read_b128 v[212:215], v169 offset:55296
	ds_read_b128 v[216:219], v169 offset:56320
	global_load_lds_dwordx4 v[222:223], off
	s_add_i32 m0, s10, 0x2000
	v_lshl_add_u64 v[222:223], s[4:5], 0, v[148:149]
	s_add_u32 s4, s20, 0xc000
	s_addc_u32 s5, s21, 0
	s_add_i32 s10, s12, s65
	global_load_lds_dwordx4 v[222:223], off
	v_lshl_add_u64 v[222:223], s[4:5], 0, v[152:153]
	s_mov_b32 m0, s10
	v_lshl_add_u64 v[198:199], v[198:199], 0, s[24:25]
	global_load_lds_dwordx4 v[222:223], off
	v_lshl_add_u64 v[222:223], s[4:5], 0, v[148:149]
	s_add_i32 m0, s10, 0x2000
	s_nop 0
	global_load_lds_dwordx4 v[222:223], off
	s_mov_b32 m0, s74
	s_nop 0
	global_load_lds_dwordx4 v[198:199], off
	v_lshl_add_u64 v[198:199], v[220:221], 0, s[24:25]
	s_mov_b32 m0, s75
	s_nop 0
	global_load_lds_dwordx4 v[198:199], off
	s_waitcnt vmcnt(8)
	s_waitcnt lgkmcnt(0)
	s_barrier
	s_setprio 1
	s_waitcnt lgkmcnt(0)
	v_mfma_f32_16x16x32_bf16 v[62:65], v[66:69], v[178:181], v[62:65]
	v_mfma_f32_16x16x32_bf16 v[58:61], v[82:85], v[178:181], v[58:61]
	v_mfma_f32_16x16x32_bf16 v[46:49], v[66:69], v[186:189], v[46:49]
	v_mfma_f32_16x16x32_bf16 v[42:45], v[82:85], v[186:189], v[42:45]
	v_mfma_f32_16x16x32_bf16 v[30:33], v[66:69], v[194:197], v[30:33]
	v_mfma_f32_16x16x32_bf16 v[26:29], v[82:85], v[194:197], v[26:29]
	v_mfma_f32_16x16x32_bf16 v[14:17], v[66:69], v[212:215], v[14:17]
	v_mfma_f32_16x16x32_bf16 v[10:13], v[82:85], v[212:215], v[10:13]
	v_mfma_f32_16x16x32_bf16 v[62:65], v[70:73], v[182:185], v[62:65]
	v_mfma_f32_16x16x32_bf16 v[58:61], v[86:89], v[182:185], v[58:61]
	v_mfma_f32_16x16x32_bf16 v[46:49], v[70:73], v[190:193], v[46:49]
	v_mfma_f32_16x16x32_bf16 v[42:45], v[86:89], v[190:193], v[42:45]
	v_mfma_f32_16x16x32_bf16 v[30:33], v[70:73], v[208:211], v[30:33]
	v_mfma_f32_16x16x32_bf16 v[26:29], v[86:89], v[208:211], v[26:29]
	v_mfma_f32_16x16x32_bf16 v[14:17], v[70:73], v[216:219], v[14:17]
	v_mfma_f32_16x16x32_bf16 v[10:13], v[86:89], v[216:219], v[10:13]
	s_setprio 0
	s_setprio 1
	s_setprio 0
	s_barrier
	s_add_u32 s85, s85, 0x10000
	s_addc_u32 s86, s86, 0
	s_cmp_ge_u32 s11, s6
	s_mov_b64 s[4:5], s[36:37]
	s_mov_b32 s10, s11
	s_cbranch_scc0 .Lgd_h0_loop
	s_branch .Lgd_after_loop
.Lgd_h1_loop:
	s_add_i32 s11, s10, 2
	s_add_u32 s36, s4, 0x100
	s_addc_u32 s37, s5, 0
	s_add_i32 s12, 0, 0x10000
	s_cmp_eq_u32 s84, s10
	s_cselect_b32 s59, s49, s37
	s_cselect_b32 s58, s48, s36
	s_cselect_b32 s21, s55, s86
	s_cselect_b32 s20, s54, s85
	s_add_i32 s10, 0, 0x14000
	v_add_u32_e32 v86, s12, v167
	v_add_u32_e32 v174, s10, v167
	ds_read_b128 v[158:161], v174
	ds_read_b128 v[162:165], v174 offset:1024
	ds_read_b128 v[170:173], v174 offset:2048
	ds_read_b128 v[174:177], v174 offset:3072
	v_lshl_add_u64 v[198:199], s[4:5], 0, v[154:155]
	s_add_i32 m0, s66, 0xc000
	ds_read_b128 v[178:181], v169
	ds_read_b128 v[182:185], v169 offset:1024
	ds_read_b128 v[186:189], v169 offset:2048
	ds_read_b128 v[190:193], v169 offset:3072
	ds_read_b128 v[194:197], v169 offset:4096
	ds_read_b128 v[208:211], v169 offset:5120
	ds_read_b128 v[212:215], v169 offset:6144
	ds_read_b128 v[216:219], v169 offset:7168
	global_load_lds_dwordx4 v[198:199], off
	v_lshl_add_u64 v[198:199], s[4:5], 0, v[156:157]
	s_add_i32 m0, s66, 0xe000
	s_nop 0
	global_load_lds_dwordx4 v[198:199], off
	s_waitcnt vmcnt(8)
	s_waitcnt lgkmcnt(0)
	s_barrier
	s_setprio 1
	s_waitcnt lgkmcnt(0)
	s_setprio 0
	s_setprio 1
	v_mfma_f32_16x16x32_bf16 v[136:139], v[158:161], v[178:181], v[136:139]
	v_mfma_f32_16x16x32_bf16 v[132:135], v[170:173], v[178:181], v[132:135]
	v_mfma_f32_16x16x32_bf16 v[120:123], v[158:161], v[186:189], v[120:123]
	v_mfma_f32_16x16x32_bf16 v[116:119], v[170:173], v[186:189], v[116:119]
	v_mfma_f32_16x16x32_bf16 v[104:107], v[158:161], v[194:197], v[104:107]
	v_mfma_f32_16x16x32_bf16 v[100:103], v[170:173], v[194:197], v[100:103]
	v_mfma_f32_16x16x32_bf16 v[78:81], v[158:161], v[212:215], v[78:81]
	v_mfma_f32_16x16x32_bf16 v[74:77], v[170:173], v[212:215], v[74:77]
	v_mfma_f32_16x16x32_bf16 v[136:139], v[162:165], v[182:185], v[136:139]
	v_mfma_f32_16x16x32_bf16 v[132:135], v[174:177], v[182:185], v[132:135]
	v_mfma_f32_16x16x32_bf16 v[120:123], v[162:165], v[190:193], v[120:123]
	v_mfma_f32_16x16x32_bf16 v[116:119], v[174:177], v[190:193], v[116:119]
	v_mfma_f32_16x16x32_bf16 v[104:107], v[162:165], v[208:211], v[104:107]
	v_mfma_f32_16x16x32_bf16 v[100:103], v[174:177], v[208:211], v[100:103]
	v_mfma_f32_16x16x32_bf16 v[78:81], v[162:165], v[216:219], v[78:81]
	v_mfma_f32_16x16x32_bf16 v[74:77], v[174:177], v[216:219], v[74:77]
	s_setprio 0
	s_barrier
	s_add_i32 s4, s12, s65
	v_lshl_add_u64 v[198:199], s[20:21], 0, v[152:153]
	s_mov_b32 m0, s4
	ds_read_b128 v[178:181], v169 offset:16384
	ds_read_b128 v[182:185], v169 offset:17408
	ds_read_b128 v[186:189], v169 offset:18432
	ds_read_b128 v[190:193], v169 offset:19456
	ds_read_b128 v[194:197], v169 offset:20480
	ds_read_b128 v[208:211], v169 offset:21504
	ds_read_b128 v[212:215], v169 offset:22528
	ds_read_b128 v[216:219], v169 offset:23552
	global_load_lds_dwordx4 v[198:199], off
	s_add_i32 m0, s4, 0x2000
	s_add_u32 s4, s20, 0x4000
	v_lshl_add_u64 v[198:199], s[20:21], 0, v[148:149]
	s_addc_u32 s5, s21, 0
	s_add_i32 s10, s10, s65
	global_load_lds_dwordx4 v[198:199], off
	v_lshl_add_u64 v[198:199], s[4:5], 0, v[152:153]
	s_mov_b32 m0, s10
	v_lshl_add_u64 v[220:221], s[58:59], 0, v[150:151]
	global_load_lds_dwordx4 v[198:199], off
	v_lshl_add_u64 v[198:199], s[4:5], 0, v[148:149]
	s_add_i32 m0, s10, 0x2000
	s_nop 0
	global_load_lds_dwordx4 v[198:199], off
	v_lshl_add_u64 v[198:199], s[58:59], 0, v[98:99]
	s_mov_b32 m0, s66
	s_nop 0
	global_load_lds_dwordx4 v[198:199], off
	s_mov_b32 m0, s67
	s_nop 0
	global_load_lds_dwordx4 v[220:221], off
	s_waitcnt vmcnt(8)
	s_waitcnt lgkmcnt(0)
	s_barrier
	s_setprio 1
	s_waitcnt lgkmcnt(0)
	s_setprio 0
	s_setprio 1
	v_mfma_f32_16x16x32_bf16 v[54:57], v[158:161], v[178:181], v[54:57]
	v_mfma_f32_16x16x32_bf16 v[50:53], v[170:173], v[178:181], v[50:53]
	v_mfma_f32_16x16x32_bf16 v[38:41], v[158:161], v[186:189], v[38:41]
	v_mfma_f32_16x16x32_bf16 v[34:37], v[170:173], v[186:189], v[34:37]
	v_mfma_f32_16x16x32_bf16 v[22:25], v[158:161], v[194:197], v[22:25]
	v_mfma_f32_16x16x32_bf16 v[18:21], v[170:173], v[194:197], v[18:21]
	v_mfma_f32_16x16x32_bf16 v[6:9], v[158:161], v[212:215], v[6:9]
	v_mfma_f32_16x16x32_bf16 v[2:5], v[170:173], v[212:215], v[2:5]
	v_mfma_f32_16x16x32_bf16 v[54:57], v[162:165], v[182:185], v[54:57]
	v_mfma_f32_16x16x32_bf16 v[50:53], v[174:177], v[182:185], v[50:53]
	v_mfma_f32_16x16x32_bf16 v[38:41], v[162:165], v[190:193], v[38:41]
	v_mfma_f32_16x16x32_bf16 v[34:37], v[174:177], v[190:193], v[34:37]
	v_mfma_f32_16x16x32_bf16 v[22:25], v[162:165], v[208:211], v[22:25]
	v_mfma_f32_16x16x32_bf16 v[18:21], v[174:177], v[208:211], v[18:21]
	v_mfma_f32_16x16x32_bf16 v[6:9], v[162:165], v[216:219], v[6:9]
	v_mfma_f32_16x16x32_bf16 v[2:5], v[174:177], v[216:219], v[2:5]
	s_setprio 0
	s_barrier
	s_add_i32 s10, 0, 0x18000
	s_add_i32 s12, 0, 0x1c000
	v_add_u32_e32 v86, s10, v167
	v_add_u32_e32 v174, s12, v167
	ds_read_b128 v[158:161], v174
	ds_read_b128 v[162:165], v174 offset:1024
	ds_read_b128 v[170:173], v174 offset:2048
	ds_read_b128 v[174:177], v174 offset:3072
	s_add_u32 s4, s58, 0x160000
	s_addc_u32 s5, s59, 0
	s_mov_b32 m0, s68
	v_lshl_add_u64 v[222:223], s[4:5], 0, v[98:99]
	ds_read_b128 v[178:181], v169 offset:32768
	ds_read_b128 v[182:185], v169 offset:33792
	ds_read_b128 v[186:189], v169 offset:34816
	ds_read_b128 v[190:193], v169 offset:35840
	ds_read_b128 v[194:197], v169 offset:36864
	ds_read_b128 v[208:211], v169 offset:37888
	ds_read_b128 v[212:215], v169 offset:38912
	ds_read_b128 v[216:219], v169 offset:39936
	global_load_lds_dwordx4 v[222:223], off
	v_lshl_add_u64 v[222:223], s[4:5], 0, v[150:151]
	s_mov_b32 m0, s69
	s_nop 0
	global_load_lds_dwordx4 v[222:223], off
	s_waitcnt vmcnt(8)
	s_waitcnt lgkmcnt(0)
	s_barrier
	s_setprio 1
	s_waitcnt lgkmcnt(0)
	s_setprio 0
	s_setprio 1
	v_mfma_f32_16x16x32_bf16 v[136:139], v[158:161], v[178:181], v[136:139]
	v_mfma_f32_16x16x32_bf16 v[132:135], v[170:173], v[178:181], v[132:135]
	v_mfma_f32_16x16x32_bf16 v[120:123], v[158:161], v[186:189], v[120:123]
	v_mfma_f32_16x16x32_bf16 v[116:119], v[170:173], v[186:189], v[116:119]
	v_mfma_f32_16x16x32_bf16 v[104:107], v[158:161], v[194:197], v[104:107]
	v_mfma_f32_16x16x32_bf16 v[100:103], v[170:173], v[194:197], v[100:103]
	v_mfma_f32_16x16x32_bf16 v[78:81], v[158:161], v[212:215], v[78:81]
	v_mfma_f32_16x16x32_bf16 v[74:77], v[170:173], v[212:215], v[74:77]
	v_mfma_f32_16x16x32_bf16 v[136:139], v[162:165], v[182:185], v[136:139]
	v_mfma_f32_16x16x32_bf16 v[132:135], v[174:177], v[182:185], v[132:135]
	v_mfma_f32_16x16x32_bf16 v[120:123], v[162:165], v[190:193], v[120:123]
	v_mfma_f32_16x16x32_bf16 v[116:119], v[174:177], v[190:193], v[116:119]
	v_mfma_f32_16x16x32_bf16 v[104:107], v[162:165], v[208:211], v[104:107]
	v_mfma_f32_16x16x32_bf16 v[100:103], v[174:177], v[208:211], v[100:103]
	v_mfma_f32_16x16x32_bf16 v[78:81], v[162:165], v[216:219], v[78:81]
	v_mfma_f32_16x16x32_bf16 v[74:77], v[174:177], v[216:219], v[74:77]
	s_setprio 0
	s_barrier
	s_add_u32 s4, s20, 0x8000
	s_addc_u32 s5, s21, 0
	s_add_i32 s10, s10, s65
	v_lshl_add_u64 v[222:223], s[4:5], 0, v[152:153]
	s_mov_b32 m0, s10
	ds_read_b128 v[178:181], v169 offset:49152
	ds_read_b128 v[182:185], v169 offset:50176
	ds_read_b128 v[186:189], v169 offset:51200
	ds_read_b128 v[190:193], v169 offset:52224
	ds_read_b128 v[194:197], v169 offset:53248
	ds_read_b128 v[208:211], v169 offset:54272
	ds_read_b128 v[212:215], v169 offset:55296
	ds_read_b128 v[216:219], v169 offset:56320
	global_load_lds_dwordx4 v[222:223], off
	s_add_i32 m0, s10, 0x2000
	v_lshl_add_u64 v[222:223], s[4:5], 0, v[148:149]
	s_add_u32 s4, s20, 0xc000
	s_addc_u32 s5, s21, 0
	s_add_i32 s10, s12, s65
	global_load_lds_dwordx4 v[222:223], off
	v_lshl_add_u64 v[222:223], s[4:5], 0, v[152:153]
	s_mov_b32 m0, s10
	v_lshl_add_u64 v[198:199], v[198:199], 0, s[24:25]
	global_load_lds_dwordx4 v[222:223], off
	v_lshl_add_u64 v[222:223], s[4:5], 0, v[148:149]
	s_add_i32 m0, s10, 0x2000
	s_nop 0
	global_load_lds_dwordx4 v[222:223], off
	s_mov_b32 m0, s74
	s_nop 0
	global_load_lds_dwordx4 v[198:199], off
	v_lshl_add_u64 v[198:199], v[220:221], 0, s[24:25]
	s_mov_b32 m0, s75
	s_nop 0
	global_load_lds_dwordx4 v[198:199], off
	s_waitcnt vmcnt(8)
	s_waitcnt lgkmcnt(0)
	s_barrier
	s_setprio 1
	s_waitcnt lgkmcnt(0)
	s_setprio 0
	s_setprio 1
	v_mfma_f32_16x16x32_bf16 v[54:57], v[158:161], v[178:181], v[54:57]
	v_mfma_f32_16x16x32_bf16 v[50:53], v[170:173], v[178:181], v[50:53]
	v_mfma_f32_16x16x32_bf16 v[38:41], v[158:161], v[186:189], v[38:41]
	v_mfma_f32_16x16x32_bf16 v[34:37], v[170:173], v[186:189], v[34:37]
	v_mfma_f32_16x16x32_bf16 v[22:25], v[158:161], v[194:197], v[22:25]
	v_mfma_f32_16x16x32_bf16 v[18:21], v[170:173], v[194:197], v[18:21]
	v_mfma_f32_16x16x32_bf16 v[6:9], v[158:161], v[212:215], v[6:9]
	v_mfma_f32_16x16x32_bf16 v[2:5], v[170:173], v[212:215], v[2:5]
	v_mfma_f32_16x16x32_bf16 v[54:57], v[162:165], v[182:185], v[54:57]
	v_mfma_f32_16x16x32_bf16 v[50:53], v[174:177], v[182:185], v[50:53]
	v_mfma_f32_16x16x32_bf16 v[38:41], v[162:165], v[190:193], v[38:41]
	v_mfma_f32_16x16x32_bf16 v[34:37], v[174:177], v[190:193], v[34:37]
	v_mfma_f32_16x16x32_bf16 v[22:25], v[162:165], v[208:211], v[22:25]
	v_mfma_f32_16x16x32_bf16 v[18:21], v[174:177], v[208:211], v[18:21]
	v_mfma_f32_16x16x32_bf16 v[6:9], v[162:165], v[216:219], v[6:9]
	v_mfma_f32_16x16x32_bf16 v[2:5], v[174:177], v[216:219], v[2:5]
	s_setprio 0
	s_barrier
	s_add_u32 s85, s85, 0x10000
	s_addc_u32 s86, s86, 0
	s_cmp_ge_u32 s11, s6
	s_mov_b64 s[4:5], s[36:37]
	s_mov_b32 s10, s11
	s_cbranch_scc0 .Lgd_h1_loop
	s_branch .Lgd_after_loop
